# attention: no-running-max fast path (score bound from gains, fallback kept) + half-step stagger of waves 4-7, 4 V LDS buffers
# speedup vs baseline: 1.0335x; 1.0335x over previous
; #define LAS __attribute__((address_space(3)))
; __global__ void __launch_bounds__(512, 2) fwd_kernel(Args a) {
;     extern __shared__ __attribute__((aligned(16))) unsigned char lds_raw[];
;     LAS unsigned char* lds = (LAS unsigned char*)lds_raw;
;     const int wid = __builtin_amdgcn_readfirstlane(threadIdx.x >> 6);
;     const int G = gridDim.x, bx0 = blockIdx.x;
;     int bx = bx0;
;     unsigned char* ws = a.ws;
;     bf16_t* P = (bf16_t*)(ws + WS_P); bf16_t* XB = (bf16_t*)(ws + WS_XB);
;     float* SS = (float*)(ws + WS_SS); float* SSV = (float*)(ws + WS_SSV);
;     const float* rope = (const float*)(ws + WS_ROPE);
;     if (threadIdx.x < 4) ((LAS unsigned*)(lds + BARW_OFF))[threadIdx.x] = 0u;
;     __syncthreads();
;     XcdBarrier xbar = xcd_barrier_post((unsigned*)(ws + WS_BAR), (volatile LAS unsigned*)(lds + BARW_OFF));
_Z10fwd_kernel4Args:
	s_load_dwordx2 s[90:91], s[0:1], 0x80
	s_mov_b32 s101, 0
	s_add_u32 s4, s0, 0x90
	s_addc_u32 s5, s1, 0
	v_and_b32_e32 v199, 0x3ff, v0
	v_writelane_b32 v253, s4, 0
	v_readfirstlane_b32 s16, v199
	v_cmp_gt_u32_e32 vcc, 4, v199
	v_writelane_b32 v253, s5, 1
	s_and_saveexec_b64 s[4:5], vcc
	v_lshl_add_u32 v1, v199, 2, 0
	v_add_u32_e32 v1, 0x27000, v1
	v_mov_b32_e32 v2, 0
	ds_write_b32 v1, v2
	s_or_b64 exec, exec, s[4:5]
	s_load_dwordx2 s[4:5], s[0:1], 0x88
	s_load_dword s3, s[0:1], 0x90
	s_waitcnt lgkmcnt(0)
	s_barrier
	v_writelane_b32 v253, s4, 2
	s_getreg_b32 s6, hwreg(HW_REG_XCC_ID, 0, 4)
	v_cmp_eq_u32_e64 s[8:9], 0, v199
	v_writelane_b32 v253, s5, 3
	s_add_u32 s4, s90, 0x1dc2000
	s_addc_u32 s5, s91, 0
	s_and_b32 s13, s6, 15
	s_mov_b64 s[6:7], exec
	v_writelane_b32 v253, s8, 4
	s_nop 1
	v_writelane_b32 v253, s9, 5
	s_and_b64 s[8:9], s[6:7], s[8:9]
	s_mov_b64 exec, s[8:9]
	s_cbranch_execz .LBB0_6
	s_mov_b64 s[10:11], exec
	v_mbcnt_lo_u32_b32 v1, s10, 0
	v_mbcnt_hi_u32_b32 v1, s11, v1
	v_cmp_eq_u32_e32 vcc, 0, v1
	s_and_saveexec_b64 s[8:9], vcc
	s_cbranch_execz .LBB0_5
	s_lshl_b32 s12, s13, 8
	s_bcnt1_i32_b64 s10, s[10:11]
	v_mov_b32_e32 v2, s12
	v_mov_b32_e32 v3, s10
	global_atomic_add v2, v2, v3, s[4:5] offset:1024 sc0

; __device__ __forceinline__ unsigned cvt_pk_bf16(float lo, float hi) { unsigned r; asm volatile("v_cvt_pk_bf16_f32 %0, %1, %2" : "=v"(r) : "v"(lo), "v"(hi)); return r; }
; __device__ __forceinline__ float bflo(unsigned w) { return __uint_as_float(w << 16); }
; __device__ __forceinline__ float bfhi(unsigned w) { return __uint_as_float(w & 0xffff0000u); }
; __device__ __forceinline__ float silu_f(float v) { return v * __builtin_amdgcn_rcpf(1.f + __builtin_amdgcn_exp2f(-1.4426950408889634f * v)); }
; __device__ __forceinline__ void attn_unit(LAS unsigned char* lds, bf16_t* P, const float* qgain, const float* rope, int s, int h, int qb, int lane, int wid, bool dry) {
;     const int r32 = lane & 31, hi = lane >> 5, kvh = h >> 2;
;     const size_t rowbase = (size_t)s * SEQ;
;     const bf16_t* ksrc = P + (rowbase + lane) * EVEN_IN + 1536 + kvh * 64 + wid * 8;
;     const bf16_t* vsrc = P + (rowbase + 16 * (wid & 3) + (lane >> 2)) * EVEN_IN + 1664 + kvh * 64 + (wid >> 2) * 32 + (lane & 3) * 8;
;     const int kdst = wid * 1024 + lane * 16;
;     const int vdst = 16384 + (wid >> 2) * 4096 + (16 * (wid & 3) + (lane >> 2)) * 64 + (lane & 3) * 16;
;     const size_t qrow = rowbase + (size_t)qb * 256 + wid * 32 + r32;
;     const bf16_t* qg = P + qrow * EVEN_IN + 1024 + h * 64 + hi * 8;
;     ...
;     lsum += __shfl_xor(lsum, 32);
;     const float inv = 1.0f / lsum;
;     bf16_t* op = P + qrow * EVEN_IN + 1792 + h * 64 + 4 * hi;
;     u32x2 zq[8];
; #pragma unroll
;     for (int i = 0; i < 4; ++i) { zq[i] = *(const u32x2*)(op + 8 * i); zq[4 + i] = *(const u32x2*)(op + 32 + 8 * i); }
;     if (!dry)
; #pragma unroll
;     for (int i = 0; i < 4; ++i) {
;         { const u32x2 z = zq[i]; u32x2 w;
;           w.x = cvt_pk_bf16(o0[4 * i] * inv * silu_f(bflo(z.x)), o0[4 * i + 1] * inv * silu_f(bfhi(z.x))); w.y = cvt_pk_bf16(o0[4 * i + 2] * inv * silu_f(bflo(z.y)), o0[4 * i + 3] * inv * silu_f(bfhi(z.y))); *(u32x2*)(op + 8 * i) = w; }
;         { const u32x2 z = zq[4 + i]; u32x2 w;
;           w.x = cvt_pk_bf16(o1[4 * i] * inv * silu_f(bflo(z.x)), o1[4 * i + 1] * inv * silu_f(bfhi(z.x))); w.y = cvt_pk_bf16(o1[4 * i + 2] * inv * silu_f(bflo(z.y)), o1[4 * i + 3] * inv * silu_f(bfhi(z.y))); *(u32x2*)(op + 32 + 8 * i) = w; }
.LBB0_60:
	s_mov_b32 s30, s37
	s_andn2_b64 vcc, exec, s[38:39]
	s_cbranch_vccnz .LBB0_141
	s_lshl_b64 s[8:9], s[80:81], 2
	s_add_u32 s8, s60, s8
	s_addc_u32 s9, s61, s9
	v_and_b32_e32 v112, 32, v198
	v_lshl_add_u64 v[152:153], s[8:9], 0, v[112:113]
	v_readlane_b32 s8, v253, 16
	v_and_b32_e32 v176, 31, v233
	s_waitcnt vmcnt(14)
	v_lshrrev_b32_e32 v1, 5, v198
	s_waitcnt vmcnt(13)
	v_lshl_or_b32 v8, v198, 4, s8
	v_readlane_b32 s8, v253, 18
	v_lshrrev_b32_e32 v151, 2, v198
	v_and_b32_e32 v2, 3, v233
	v_or_b32_e32 v4, s8, v176
	v_readlane_b32 s8, v253, 8
	v_readlane_b32 s9, v253, 9
	v_readlane_b32 s11, v253, 14
	v_lshlrev_b32_e32 v0, 3, v2
	v_lshl_add_u64 v[154:155], s[8:9], 0, v[112:113]
	v_readlane_b32 s8, v253, 19
	v_readlane_b32 s9, v253, 20
	v_lshlrev_b32_e32 v5, 4, v2
	v_lshlrev_b32_e32 v2, 3, v1
	v_lshl_add_u64 v[156:157], s[8:9], 0, v[112:113]
	v_lshlrev_b32_e32 v112, 6, v4
	v_lshlrev_b32_e32 v4, 4, v176
	s_waitcnt lgkmcnt(0)
	v_lshl_or_b32 v9, v1, 10, v4
	v_lshlrev_b32_e32 v4, 1, v198
	v_and_b32_e32 v6, 32, v4
	v_lshlrev_b32_e32 v4, 2, v1
	v_and_or_b32 v1, v151, 3, v4
	v_or_b32_e32 v150, s11, v151
	v_lshlrev_b32_e32 v1, 6, v1
	v_lshlrev_b32_e32 v3, 6, v150
	v_readlane_b32 s8, v253, 15
	v_or3_b32 v1, v1, v6, v0
	v_add_u32_e32 v6, s11, v151
	v_add3_u32 v3, v3, s8, v5
	v_mul_hi_u32_u24_e32 v7, 0x1200, v6
	v_mul_u32_u24_e32 v6, 0x1200, v6
	v_readlane_b32 s8, v255, 5
	v_or_b32_e32 v6, v6, v5
	v_readlane_b32 s9, v255, 6
	v_lshl_add_u64 v[158:159], v[154:155], 0, v[112:113]
	v_lshl_add_u64 v[160:161], v[156:157], 0, v[112:113]
	v_lshl_add_u64 v[162:163], s[8:9], 0, v[6:7]
	v_readlane_b32 s8, v255, 7
	v_readlane_b32 s9, v255, 8
	s_mov_b32 s11, 0
	v_lshlrev_b32_e32 v112, 1, v0
	v_mov_b64_e32 v[6:7], s[8:9]
	s_movk_i32 s8, 0x1200
	v_mad_u64_u32 v[164:165], s[8:9], v198, s8, v[6:7]
	v_lshlrev_b32_e32 v166, 1, v2
	v_lshlrev_b32_e32 v168, 1, v4
	v_add_u32_e32 v177, 0, v8
	v_add_u32_e32 v178, 0, v3
	v_add_u32_e32 v179, 0, v9
	v_add_u32_e32 v180, 0, v1
	s_lshl_b64 s[8:9], s[80:81], 2
	s_add_u32 s22, s60, s8
	s_addc_u32 s23, s61, s9
	s_add_u32 s8, s62, s8
	s_addc_u32 s9, s63, s9
	v_lshlrev_b32_e32 v0, 2, v198
	global_load_dword v1, v0, s[22:23]
	global_load_dword v2, v0, s[8:9]
	s_waitcnt vmcnt(0)
	v_and_b32_e32 v1, 0x7fffffff, v1
	v_and_b32_e32 v2, 0x7fffffff, v2
	v_xor_b32_e32 v3, 1, v198
	v_lshlrev_b32_e32 v3, 2, v3
	ds_bpermute_b32 v4, v3, v1
	ds_bpermute_b32 v5, v3, v2
	s_waitcnt lgkmcnt(0)
	v_max_f32_e32 v1, v1, v4
	v_max_f32_e32 v2, v2, v5
	v_xor_b32_e32 v3, 2, v198
	v_lshlrev_b32_e32 v3, 2, v3
	ds_bpermute_b32 v4, v3, v1
	ds_bpermute_b32 v5, v3, v2
	s_waitcnt lgkmcnt(0)
	v_max_f32_e32 v1, v1, v4
	v_max_f32_e32 v2, v2, v5
	v_xor_b32_e32 v3, 4, v198
	v_lshlrev_b32_e32 v3, 2, v3
	ds_bpermute_b32 v4, v3, v1
	ds_bpermute_b32 v5, v3, v2
	s_waitcnt lgkmcnt(0)
	v_max_f32_e32 v1, v1, v4
	v_max_f32_e32 v2, v2, v5
	v_xor_b32_e32 v3, 8, v198
	v_lshlrev_b32_e32 v3, 2, v3
	ds_bpermute_b32 v4, v3, v1
	ds_bpermute_b32 v5, v3, v2
	s_waitcnt lgkmcnt(0)
	v_max_f32_e32 v1, v1, v4
	v_max_f32_e32 v2, v2, v5
	v_xor_b32_e32 v3, 16, v198
	v_lshlrev_b32_e32 v3, 2, v3
	ds_bpermute_b32 v4, v3, v1
	ds_bpermute_b32 v5, v3, v2
	s_waitcnt lgkmcnt(0)
	v_max_f32_e32 v1, v1, v4
	v_max_f32_e32 v2, v2, v5
	v_xor_b32_e32 v3, 32, v198
	v_lshlrev_b32_e32 v3, 2, v3
	ds_bpermute_b32 v4, v3, v1
	ds_bpermute_b32 v5, v3, v2
	s_waitcnt lgkmcnt(0)
	v_max_f32_e32 v1, v1, v4
	v_max_f32_e32 v2, v2, v5
	v_mul_f32_e32 v1, v1, v2
	v_mul_f32_e32 v1, 0x413c5bb7, v1
	v_mov_b32_e32 v2, 0x42000000
	v_cmp_ge_f32_e32 vcc, v2, v1
	s_nop 3
	s_cmp_lg_u64 vcc, 0
	s_cselect_b32 s101, 1, 0
	s_branch .LBB0_64
.LBB0_62:
	v_xor_b32_e32 v32, 32, v221
	v_cmp_lt_i32_e32 vcc, v32, v223
	s_add_i32 s11, s11, 1
	s_mov_b64 s[38:39], 0
	v_cndmask_b32_e32 v32, v221, v32, vcc
	v_lshlrev_b32_e32 v32, 2, v32
	ds_bpermute_b32 v32, v32, v169
	s_waitcnt lgkmcnt(0)
	v_add_f32_e32 v34, v169, v32
	v_mov_b32_e32 v169, v113
	v_lshl_add_u64 v[32:33], v[170:171], 0, v[168:169]
	global_load_dwordx2 v[50:51], v[32:33], off offset:3584
	global_load_dwordx2 v[48:49], v[32:33], off offset:3648
	global_load_dwordx2 v[46:47], v[32:33], off offset:3600
	global_load_dwordx2 v[44:45], v[32:33], off offset:3664
	global_load_dwordx2 v[42:43], v[32:33], off offset:3616
	global_load_dwordx2 v[40:41], v[32:33], off offset:3680
	global_load_dwordx2 v[38:39], v[32:33], off offset:3632
	global_load_dwordx2 v[36:37], v[32:33], off offset:3696
	v_div_scale_f32 v35, s[8:9], v34, v34, 1.0
	v_rcp_f32_e32 v52, v35
	s_nop 0
	v_fma_f32 v53, -v35, v52, 1.0
	v_fmac_f32_e32 v52, v53, v52
	v_div_scale_f32 v53, vcc, 1.0, v34, 1.0
	v_mul_f32_e32 v54, v53, v52
	v_fma_f32 v55, -v35, v54, v53
	v_fmac_f32_e32 v54, v55, v52
	v_fma_f32 v35, -v35, v54, v53
	v_div_fmas_f32 v35, v35, v52, v54
	v_div_fixup_f32 v34, v35, v34, 1.0
	s_waitcnt vmcnt(7)
	v_lshlrev_b32_e32 v35, 16, v50
	v_mul_f32_e32 v52, 0xbfb8aa3b, v35
	v_exp_f32_e32 v52, v52
	s_nop 0
	v_add_f32_e32 v52, 1.0, v52
	v_rcp_f32_e32 v53, v52
	v_mov_b32_e32 v52, v16
	v_pk_mul_f32 v[52:53], v[52:53], v[34:35]
	v_and_b32_e32 v35, 0xffff0000, v50
	v_mul_f32_e32 v16, 0xbfb8aa3b, v35
	v_exp_f32_e32 v16, v16
	v_mul_f32_e32 v54, v52, v53
	v_mov_b32_e32 v52, v17
	v_mov_b32_e32 v50, v19
	v_add_f32_e32 v16, 1.0, v16
	v_rcp_f32_e32 v53, v16
	s_nop 0
	v_pk_mul_f32 v[16:17], v[52:53], v[34:35]
	v_lshlrev_b32_e32 v35, 16, v51
	v_mul_f32_e32 v16, v16, v17
	v_mul_f32_e32 v17, 0xbfb8aa3b, v35
	v_exp_f32_e32 v17, v17
	v_mov_b32_e32 v52, v18
	v_cvt_pk_bf16_f32 v16, v54, v16
	v_add_f32_e32 v17, 1.0, v17
	v_rcp_f32_e32 v53, v17
	s_nop 0
	v_pk_mul_f32 v[52:53], v[52:53], v[34:35]
	v_and_b32_e32 v35, 0xffff0000, v51
	v_mul_f32_e32 v18, 0xbfb8aa3b, v35
	v_exp_f32_e32 v18, v18
	v_mul_f32_e32 v17, v52, v53
	v_add_f32_e32 v18, 1.0, v18
	v_rcp_f32_e32 v51, v18
	s_nop 0
	v_pk_mul_f32 v[18:19], v[50:51], v[34:35]
	s_waitcnt vmcnt(6)
; __device__ __forceinline__ unsigned cvt_pk_bf16(float lo, float hi) { unsigned r; asm volatile("v_cvt_pk_bf16_f32 %0, %1, %2" : "=v"(r) : "v"(lo), "v"(hi)); return r; }
; __device__ __forceinline__ float bflo(unsigned w) { return __uint_as_float(w << 16); }
; __device__ __forceinline__ float bfhi(unsigned w) { return __uint_as_float(w & 0xffff0000u); }
; __device__ __forceinline__ float silu_f(float v) { return v * __builtin_amdgcn_rcpf(1.f + __builtin_amdgcn_exp2f(-1.4426950408889634f * v)); }
; __device__ __forceinline__ void attn_unit(LAS unsigned char* lds, bf16_t* P, const float* qgain, const float* rope, int s, int h, int qb, int lane, int wid, bool dry) {
;     ...
;     if (!dry)
; #pragma unroll
;     for (int i = 0; i < 4; ++i) {
;         { const u32x2 z = zq[i]; u32x2 w;
;           w.x = cvt_pk_bf16(o0[4 * i] * inv * silu_f(bflo(z.x)), o0[4 * i + 1] * inv * silu_f(bfhi(z.x))); w.y = cvt_pk_bf16(o0[4 * i + 2] * inv * silu_f(bflo(z.y)), o0[4 * i + 3] * inv * silu_f(bfhi(z.y))); *(u32x2*)(op + 8 * i) = w; }
;         { const u32x2 z = zq[4 + i]; u32x2 w;
;           w.x = cvt_pk_bf16(o1[4 * i] * inv * silu_f(bflo(z.x)), o1[4 * i + 1] * inv * silu_f(bfhi(z.x))); w.y = cvt_pk_bf16(o1[4 * i + 2] * inv * silu_f(bflo(z.y)), o1[4 * i + 3] * inv * silu_f(bfhi(z.y))); *(u32x2*)(op + 32 + 8 * i) = w; }
;     }
	v_lshlrev_b32_e32 v35, 16, v48
	v_mul_f32_e32 v18, v18, v19
	v_cvt_pk_bf16_f32 v17, v17, v18
	global_store_dwordx2 v[32:33], v[16:17], off offset:3584
	v_mul_f32_e32 v16, 0xbfb8aa3b, v35
	v_exp_f32_e32 v16, v16
	s_nop 0
	v_add_f32_e32 v16, 1.0, v16
	v_rcp_f32_e32 v17, v16
	v_mov_b32_e32 v16, v0
	v_pk_mul_f32 v[16:17], v[16:17], v[34:35]
	v_and_b32_e32 v35, 0xffff0000, v48
	v_mul_f32_e32 v0, 0xbfb8aa3b, v35
	v_exp_f32_e32 v0, v0
	v_mul_f32_e32 v18, v16, v17
	v_mov_b32_e32 v16, v1
	v_add_f32_e32 v0, 1.0, v0
	v_rcp_f32_e32 v17, v0
	s_nop 0
	v_pk_mul_f32 v[0:1], v[16:17], v[34:35]
	v_lshlrev_b32_e32 v35, 16, v49
	v_mul_f32_e32 v0, v0, v1
	v_mul_f32_e32 v1, 0xbfb8aa3b, v35
	v_exp_f32_e32 v1, v1
	v_mov_b32_e32 v16, v2
	v_cvt_pk_bf16_f32 v0, v18, v0
	v_add_f32_e32 v1, 1.0, v1
	v_rcp_f32_e32 v17, v1
	s_nop 0
	v_pk_mul_f32 v[16:17], v[16:17], v[34:35]
	v_and_b32_e32 v35, 0xffff0000, v49
	v_mul_f32_e32 v2, 0xbfb8aa3b, v35
	v_exp_f32_e32 v2, v2
	v_mul_f32_e32 v1, v16, v17
	v_mov_b32_e32 v16, v3
	v_add_f32_e32 v2, 1.0, v2
	v_rcp_f32_e32 v17, v2
	s_nop 0
	v_pk_mul_f32 v[2:3], v[16:17], v[34:35]
	s_waitcnt vmcnt(6)
	v_lshlrev_b32_e32 v35, 16, v46
	v_mul_f32_e32 v2, v2, v3
	v_cvt_pk_bf16_f32 v1, v1, v2
	global_store_dwordx2 v[32:33], v[0:1], off offset:3648
	v_mul_f32_e32 v0, 0xbfb8aa3b, v35
	v_exp_f32_e32 v0, v0
	s_nop 0
	v_add_f32_e32 v0, 1.0, v0
	v_rcp_f32_e32 v1, v0
	v_mov_b32_e32 v0, v20
	v_pk_mul_f32 v[0:1], v[0:1], v[34:35]
	v_and_b32_e32 v35, 0xffff0000, v46
	v_mul_f32_e32 v2, v0, v1
	v_mul_f32_e32 v0, 0xbfb8aa3b, v35
	v_exp_f32_e32 v0, v0
	s_nop 0
	v_add_f32_e32 v0, 1.0, v0
	v_rcp_f32_e32 v1, v0
	v_mov_b32_e32 v0, v21
	v_pk_mul_f32 v[0:1], v[0:1], v[34:35]
	v_lshlrev_b32_e32 v35, 16, v47
	v_mul_f32_e32 v0, v0, v1
	v_mul_f32_e32 v1, 0xbfb8aa3b, v35
	v_exp_f32_e32 v1, v1
	v_cvt_pk_bf16_f32 v0, v2, v0
	v_mov_b32_e32 v2, v22
	v_add_f32_e32 v1, 1.0, v1
	v_rcp_f32_e32 v3, v1
	s_nop 0
	v_pk_mul_f32 v[2:3], v[2:3], v[34:35]
	v_and_b32_e32 v35, 0xffff0000, v47
	v_mul_f32_e32 v1, v2, v3
	v_mul_f32_e32 v2, 0xbfb8aa3b, v35
	v_exp_f32_e32 v2, v2
	s_nop 0
	v_add_f32_e32 v2, 1.0, v2
	v_rcp_f32_e32 v3, v2
	v_mov_b32_e32 v2, v23
	v_pk_mul_f32 v[2:3], v[2:3], v[34:35]
	s_waitcnt vmcnt(6)
	v_lshlrev_b32_e32 v35, 16, v44
	v_mul_f32_e32 v2, v2, v3
	v_cvt_pk_bf16_f32 v1, v1, v2
	global_store_dwordx2 v[32:33], v[0:1], off offset:3600
	v_mul_f32_e32 v0, 0xbfb8aa3b, v35
	v_exp_f32_e32 v0, v0
	s_nop 0
	v_add_f32_e32 v0, 1.0, v0
	v_rcp_f32_e32 v1, v0
	v_mov_b32_e32 v0, v4
	v_pk_mul_f32 v[0:1], v[0:1], v[34:35]
	v_and_b32_e32 v35, 0xffff0000, v44
	v_mul_f32_e32 v2, v0, v1
	v_mul_f32_e32 v0, 0xbfb8aa3b, v35
	v_exp_f32_e32 v0, v0
	s_nop 0
	v_add_f32_e32 v0, 1.0, v0
	v_rcp_f32_e32 v1, v0
	v_mov_b32_e32 v0, v5
	v_pk_mul_f32 v[0:1], v[0:1], v[34:35]
	v_lshlrev_b32_e32 v35, 16, v45
	v_mul_f32_e32 v0, v0, v1
	v_mul_f32_e32 v1, 0xbfb8aa3b, v35
	v_exp_f32_e32 v1, v1
	v_cvt_pk_bf16_f32 v0, v2, v0
	v_mov_b32_e32 v2, v6
	v_add_f32_e32 v1, 1.0, v1
	v_rcp_f32_e32 v3, v1
	s_nop 0
	v_pk_mul_f32 v[2:3], v[2:3], v[34:35]
	v_and_b32_e32 v35, 0xffff0000, v45
	v_mul_f32_e32 v1, v2, v3
	v_mul_f32_e32 v2, 0xbfb8aa3b, v35
	v_exp_f32_e32 v2, v2
	s_nop 0
	v_add_f32_e32 v2, 1.0, v2
	v_rcp_f32_e32 v3, v2
	v_mov_b32_e32 v2, v7
	v_pk_mul_f32 v[2:3], v[2:3], v[34:35]
	s_waitcnt vmcnt(6)
	v_lshlrev_b32_e32 v35, 16, v42
	v_mul_f32_e32 v2, v2, v3
	v_cvt_pk_bf16_f32 v1, v1, v2
	global_store_dwordx2 v[32:33], v[0:1], off offset:3664
	v_mul_f32_e32 v0, 0xbfb8aa3b, v35
	v_exp_f32_e32 v0, v0
	s_nop 0
	v_add_f32_e32 v0, 1.0, v0
	v_rcp_f32_e32 v1, v0
	v_mov_b32_e32 v0, v24
	v_pk_mul_f32 v[0:1], v[0:1], v[34:35]
	v_and_b32_e32 v35, 0xffff0000, v42
	v_mul_f32_e32 v2, v0, v1
	v_mul_f32_e32 v0, 0xbfb8aa3b, v35
	v_exp_f32_e32 v0, v0
	s_nop 0
	v_add_f32_e32 v0, 1.0, v0
	v_rcp_f32_e32 v1, v0
	v_mov_b32_e32 v0, v25
	v_pk_mul_f32 v[0:1], v[0:1], v[34:35]
	v_lshlrev_b32_e32 v35, 16, v43
	v_mul_f32_e32 v0, v0, v1
	v_mul_f32_e32 v1, 0xbfb8aa3b, v35
	v_exp_f32_e32 v1, v1
	v_cvt_pk_bf16_f32 v0, v2, v0
	v_mov_b32_e32 v2, v26
	v_add_f32_e32 v1, 1.0, v1
	v_rcp_f32_e32 v3, v1
	s_nop 0
	v_pk_mul_f32 v[2:3], v[2:3], v[34:35]
	v_and_b32_e32 v35, 0xffff0000, v43
	v_mul_f32_e32 v1, v2, v3
	v_mul_f32_e32 v2, 0xbfb8aa3b, v35
	v_exp_f32_e32 v2, v2
	s_nop 0
	v_add_f32_e32 v2, 1.0, v2
	v_rcp_f32_e32 v3, v2
	v_mov_b32_e32 v2, v27
	v_pk_mul_f32 v[2:3], v[2:3], v[34:35]
	s_waitcnt vmcnt(6)
; __device__ __forceinline__ unsigned cvt_pk_bf16(float lo, float hi) { unsigned r; asm volatile("v_cvt_pk_bf16_f32 %0, %1, %2" : "=v"(r) : "v"(lo), "v"(hi)); return r; }
; __device__ __forceinline__ float bflo(unsigned w) { return __uint_as_float(w << 16); }
; __device__ __forceinline__ float bfhi(unsigned w) { return __uint_as_float(w & 0xffff0000u); }
; __device__ __forceinline__ float silu_f(float v) { return v * __builtin_amdgcn_rcpf(1.f + __builtin_amdgcn_exp2f(-1.4426950408889634f * v)); }
; __device__ __forceinline__ void attn_unit(LAS unsigned char* lds, bf16_t* P, const float* qgain, const float* rope, int s, int h, int qb, int lane, int wid, bool dry) {
;     ...
;     if (!dry)
; #pragma unroll
;     for (int i = 0; i < 4; ++i) {
;         { const u32x2 z = zq[i]; u32x2 w;
;           w.x = cvt_pk_bf16(o0[4 * i] * inv * silu_f(bflo(z.x)), o0[4 * i + 1] * inv * silu_f(bfhi(z.x))); w.y = cvt_pk_bf16(o0[4 * i + 2] * inv * silu_f(bflo(z.y)), o0[4 * i + 3] * inv * silu_f(bfhi(z.y))); *(u32x2*)(op + 8 * i) = w; }
;         { const u32x2 z = zq[4 + i]; u32x2 w;
;           w.x = cvt_pk_bf16(o1[4 * i] * inv * silu_f(bflo(z.x)), o1[4 * i + 1] * inv * silu_f(bfhi(z.x))); w.y = cvt_pk_bf16(o1[4 * i + 2] * inv * silu_f(bflo(z.y)), o1[4 * i + 3] * inv * silu_f(bfhi(z.y))); *(u32x2*)(op + 32 + 8 * i) = w; }
;     }
	v_lshlrev_b32_e32 v35, 16, v40
	v_mul_f32_e32 v2, v2, v3
	v_cvt_pk_bf16_f32 v1, v1, v2
	global_store_dwordx2 v[32:33], v[0:1], off offset:3616
	v_mul_f32_e32 v0, 0xbfb8aa3b, v35
	v_exp_f32_e32 v0, v0
	s_nop 0
	v_add_f32_e32 v0, 1.0, v0
	v_rcp_f32_e32 v1, v0
	v_mov_b32_e32 v0, v8
	v_pk_mul_f32 v[0:1], v[0:1], v[34:35]
	v_and_b32_e32 v35, 0xffff0000, v40
	v_mul_f32_e32 v2, v0, v1
	v_mul_f32_e32 v0, 0xbfb8aa3b, v35
	v_exp_f32_e32 v0, v0
	s_nop 0
	v_add_f32_e32 v0, 1.0, v0
	v_rcp_f32_e32 v1, v0
	v_mov_b32_e32 v0, v9
	v_pk_mul_f32 v[0:1], v[0:1], v[34:35]
	v_lshlrev_b32_e32 v35, 16, v41
	v_mul_f32_e32 v0, v0, v1
	v_mul_f32_e32 v1, 0xbfb8aa3b, v35
	v_exp_f32_e32 v1, v1
	v_cvt_pk_bf16_f32 v0, v2, v0
	v_mov_b32_e32 v2, v10
	v_add_f32_e32 v1, 1.0, v1
	v_rcp_f32_e32 v3, v1
	s_nop 0
	v_pk_mul_f32 v[2:3], v[2:3], v[34:35]
	v_and_b32_e32 v35, 0xffff0000, v41
	v_mul_f32_e32 v1, v2, v3
	v_mul_f32_e32 v2, 0xbfb8aa3b, v35
	v_exp_f32_e32 v2, v2
	s_nop 0
	v_add_f32_e32 v2, 1.0, v2
	v_rcp_f32_e32 v3, v2
	v_mov_b32_e32 v2, v11
	v_pk_mul_f32 v[2:3], v[2:3], v[34:35]
	s_waitcnt vmcnt(6)
	v_lshlrev_b32_e32 v35, 16, v38
	v_mul_f32_e32 v2, v2, v3
	v_cvt_pk_bf16_f32 v1, v1, v2
	global_store_dwordx2 v[32:33], v[0:1], off offset:3680
	v_mul_f32_e32 v0, 0xbfb8aa3b, v35
	v_exp_f32_e32 v0, v0
	s_nop 0
	v_add_f32_e32 v0, 1.0, v0
	v_rcp_f32_e32 v1, v0
	v_mov_b32_e32 v0, v28
	v_pk_mul_f32 v[0:1], v[0:1], v[34:35]
	v_and_b32_e32 v35, 0xffff0000, v38
	v_mul_f32_e32 v2, v0, v1
	v_mul_f32_e32 v0, 0xbfb8aa3b, v35
	v_exp_f32_e32 v0, v0
	s_nop 0
	v_add_f32_e32 v0, 1.0, v0
	v_rcp_f32_e32 v1, v0
	v_mov_b32_e32 v0, v29
	v_pk_mul_f32 v[0:1], v[0:1], v[34:35]
	v_lshlrev_b32_e32 v35, 16, v39
	v_mul_f32_e32 v0, v0, v1
	v_mul_f32_e32 v1, 0xbfb8aa3b, v35
	v_exp_f32_e32 v1, v1
	v_cvt_pk_bf16_f32 v0, v2, v0
	v_mov_b32_e32 v2, v30
	v_add_f32_e32 v1, 1.0, v1
	v_rcp_f32_e32 v3, v1
	s_nop 0
	v_pk_mul_f32 v[2:3], v[2:3], v[34:35]
	v_and_b32_e32 v35, 0xffff0000, v39
	v_mul_f32_e32 v1, v2, v3
	v_mul_f32_e32 v2, 0xbfb8aa3b, v35
	v_exp_f32_e32 v2, v2
	s_nop 0
	v_add_f32_e32 v2, 1.0, v2
	v_rcp_f32_e32 v3, v2
	v_mov_b32_e32 v2, v31
	v_pk_mul_f32 v[2:3], v[2:3], v[34:35]
	s_waitcnt vmcnt(6)
	v_lshlrev_b32_e32 v35, 16, v36
	v_mul_f32_e32 v2, v2, v3
	v_cvt_pk_bf16_f32 v1, v1, v2
	global_store_dwordx2 v[32:33], v[0:1], off offset:3632
	v_mul_f32_e32 v0, 0xbfb8aa3b, v35
	v_exp_f32_e32 v0, v0
	s_nop 0
	v_add_f32_e32 v0, 1.0, v0
	v_rcp_f32_e32 v1, v0
	v_mov_b32_e32 v0, v12
	v_pk_mul_f32 v[0:1], v[0:1], v[34:35]
	v_and_b32_e32 v35, 0xffff0000, v36
	v_mul_f32_e32 v2, v0, v1
	v_mul_f32_e32 v0, 0xbfb8aa3b, v35
	v_exp_f32_e32 v0, v0
	s_nop 0
	v_add_f32_e32 v0, 1.0, v0
	v_rcp_f32_e32 v1, v0
	v_mov_b32_e32 v0, v13
	v_pk_mul_f32 v[0:1], v[0:1], v[34:35]
	v_lshlrev_b32_e32 v35, 16, v37
	v_mul_f32_e32 v0, v0, v1
	v_mul_f32_e32 v1, 0xbfb8aa3b, v35
	v_exp_f32_e32 v1, v1
	v_cvt_pk_bf16_f32 v0, v2, v0
	v_mov_b32_e32 v2, v14
	v_add_f32_e32 v1, 1.0, v1
	v_rcp_f32_e32 v3, v1
	s_nop 0
	v_pk_mul_f32 v[2:3], v[2:3], v[34:35]
	v_and_b32_e32 v35, 0xffff0000, v37
	v_mul_f32_e32 v1, v2, v3
	v_mul_f32_e32 v2, 0xbfb8aa3b, v35
	v_exp_f32_e32 v2, v2
	s_nop 0
	v_add_f32_e32 v2, 1.0, v2
	v_rcp_f32_e32 v3, v2
	v_mov_b32_e32 v2, v15
	v_pk_mul_f32 v[2:3], v[2:3], v[34:35]
	s_nop 0
	v_mul_f32_e32 v2, v2, v3
	v_cvt_pk_bf16_f32 v1, v1, v2
	global_store_dwordx2 v[32:33], v[0:1], off offset:3696
	s_cmp_eq_u32 s101, 0
	s_cbranch_scc1 .LBB0_63
	s_barrier

; __device__ __forceinline__ float bflo(unsigned w) { return __uint_as_float(w << 16); }
; __device__ __forceinline__ float bfhi(unsigned w) { return __uint_as_float(w & 0xffff0000u); }
; __device__ __forceinline__ void attn_unit(LAS unsigned char* lds, bf16_t* P, const float* qgain, const float* rope, int s, int h, int qb, int lane, int wid, bool dry) {
;     ...
;     const size_t rowbase = (size_t)s * SEQ;
;     const bf16_t* ksrc = P + (rowbase + lane) * EVEN_IN + 1536 + kvh * 64 + wid * 8;
;     const bf16_t* vsrc = P + (rowbase + 16 * (wid & 3) + (lane >> 2)) * EVEN_IN + 1664 + kvh * 64 + (wid >> 2) * 32 + (lane & 3) * 8;
;     const int kdst = wid * 1024 + lane * 16;
;     const int vdst = 16384 + (wid >> 2) * 4096 + (16 * (wid & 3) + (lane >> 2)) * 64 + (lane & 3) * 16;
;     const size_t qrow = rowbase + (size_t)qb * 256 + wid * 32 + r32;
;     const bf16_t* qg = P + qrow * EVEN_IN + 1024 + h * 64 + hi * 8;
;     u32x4 krA = *(const u32x4*)ksrc, vrA = *(const u32x4*)vsrc;
;     u32x4 krB = *(const u32x4*)(ksrc + (size_t)64 * EVEN_IN), vrB;
;     bf16x8 qf[4];
;     {
;         float y[4][8]; float ssq = 0.f;
; #pragma unroll
;         for (int d0 = 0; d0 < 4; ++d0) { const u32x4 w = *(const u32x4*)(qg + d0 * 16);
;             y[d0][0] = bflo(w.x); y[d0][1] = bfhi(w.x); y[d0][2] = bflo(w.y); y[d0][3] = bfhi(w.y); y[d0][4] = bflo(w.z); y[d0][5] = bfhi(w.z); y[d0][6] = bflo(w.w); y[d0][7] = bfhi(w.w);
; #pragma unroll
;             for (int e = 0; e < 8; ++e) ssq += y[d0][e] * y[d0][e]; }
.LBB0_69:
	s_ashr_i32 s38, s16, 7
	s_ashr_i32 s39, s38, 31
	s_and_b32 s13, s16, 64
	s_lshl_b64 s[8:9], s[38:39], 12
	s_lshl_b32 s46, s13, 1
	s_lshl_b32 s13, s16, 8
	v_or_b32_e32 v2, s8, v198
	v_mov_b64_e32 v[0:1], s[0:1]
	s_movk_i32 s19, 0x1200
	v_or_b32_e32 v4, s8, v150
	s_and_b32 s13, s13, 0xf00
	v_readlane_b32 s17, v253, 17
	v_mad_u64_u32 v[2:3], s[22:23], v2, s19, v[0:1]
	v_mad_u64_u32 v[4:5], s[22:23], v4, s19, v[0:1]
	s_add_u32 s8, s8, s17
	v_mad_i32_i24 v3, s9, v226, v3
	v_mad_i32_i24 v5, s9, v226, v5
	v_or_b32_e32 v6, s13, v176
	v_mov_b32_e32 v7, v113
	s_addc_u32 s9, s9, 0
	v_lshl_add_u64 v[6:7], s[8:9], 0, v[6:7]
	v_mad_u64_u32 v[0:1], s[8:9], v6, s19, v[0:1]
	s_lshl_b32 s8, s16, 3
	v_lshl_add_u64 v[2:3], v[2:3], 0, s[46:47]
	v_lshl_add_u64 v[4:5], v[4:5], 0, s[46:47]
	v_mad_i32_i24 v1, v7, s19, v1
	s_and_b32 s46, s8, 0x380
	v_lshl_add_u64 v[170:171], v[0:1], 0, s[46:47]
	v_mov_b32_e32 v167, v113
	v_lshl_add_u64 v[0:1], v[170:171], 0, v[166:167]
	s_add_i32 s13, s13, s17
	global_load_dwordx4 v[72:75], v[152:153], off offset:80
	global_load_dwordx4 v[40:43], v[152:153], off offset:16
	global_load_dwordx4 v[68:71], v[0:1], off offset:2144
	global_load_dwordx4 v[76:79], v[0:1], off offset:2112
	global_load_dwordx4 v[80:83], v[0:1], off offset:2048
	global_load_dwordx4 v[84:87], v[0:1], off offset:2080
	s_and_b32 s46, s13, 0x7fffffc0
	v_lshl_add_u64 v[0:1], v[154:155], 0, s[46:47]
	v_lshl_add_u64 v[6:7], v[156:157], 0, s[46:47]
	global_load_dwordx4 v[24:27], v[0:1], off offset:16
	global_load_dwordx4 v[28:31], v[6:7], off offset:16
	global_load_dwordx4 v[48:51], v[152:153], off offset:64
	global_load_dwordx4 v[44:47], v[152:153], off
	global_load_dwordx4 v[36:39], v[0:1], off
	global_load_dwordx4 v[32:35], v[6:7], off
	v_readlane_b32 s8, v255, 32
	v_readlane_b32 s9, v255, 33
	v_readlane_b32 s36, v255, 34
	s_mov_b32 s22, s8
	v_readlane_b32 s13, v255, 49
	s_mov_b32 s9, s47
	v_readlane_b32 s37, v255, 35
	v_writelane_b32 v255, s22, 32
	v_lshl_add_u64 v[52:53], v[2:3], 0, s[8:9]
	s_mov_b32 s8, s36
	v_writelane_b32 v255, s23, 33
	v_writelane_b32 v255, s8, 34
	s_mov_b32 s37, s47
	v_lshl_add_u64 v[0:1], v[4:5], 0, s[36:37]
	v_writelane_b32 v255, s9, 35
	s_mov_b32 s8, 0x48000
	v_add_co_u32_e32 v56, vcc, s8, v52
	global_load_dwordx4 v[12:15], v[152:153], off offset:128
	global_load_dwordx4 v[8:11], v[152:153], off offset:144
	global_load_dwordx4 v[16:19], v[152:153], off offset:192
	global_load_dwordx4 v[20:23], v[152:153], off offset:208
	v_addc_co_u32_e32 v57, vcc, 0, v53, vcc
	v_lshl_add_u64 v[54:55], v[0:1], 0, v[112:113]
	global_load_dwordx4 v[0:3], v[52:53], off offset:3072
	global_load_dwordx4 v[4:7], v[54:55], off offset:3328
	global_load_dwordx4 v[114:117], v[56:57], off offset:3072
	s_mov_b32 s9, 0x90000
	s_mov_b32 s80, 0
	s_mov_b32 s81, s80
	s_mov_b32 s82, s80
	s_mov_b32 s83, s80
	s_mov_b32 s84, s80
	s_mov_b32 s85, s80
	s_mov_b32 s86, s80
	s_mov_b32 s87, s80
	s_mov_b32 s88, s80
	s_mov_b32 s89, s80
	s_mov_b32 s90, s80
	s_mov_b32 s91, s80
	s_mov_b32 s92, s80
	s_mov_b32 s93, s80
	s_mov_b32 s94, s80
	s_mov_b32 s95, s80
	v_mov_b32_e32 v169, 0
	s_waitcnt vmcnt(16)
	v_lshlrev_b32_e32 v58, 16, v71
	v_mov_b32_e32 v88, v74
	s_waitcnt vmcnt(15)
	v_lshlrev_b32_e32 v63, 16, v78
	v_and_b32_e32 v61, 0xffff0000, v78
	s_waitcnt vmcnt(13)
	v_lshlrev_b32_e32 v74, 16, v87
	v_and_b32_e32 v78, 0xffff0000, v87
	s_waitcnt vmcnt(9)
	v_mov_b32_e32 v87, v46
	v_mov_b32_e32 v46, v51
	v_lshlrev_b32_e32 v51, 16, v80
	v_mov_b32_e32 v95, v40
	v_mov_b32_e32 v40, v73
	v_lshlrev_b32_e32 v73, 16, v81
	v_and_b32_e32 v101, 0xffff0000, v81
	v_mov_b32_e32 v102, v48
	v_and_b32_e32 v81, 0xffff0000, v80
	v_mul_f32_e32 v48, v51, v51
	v_fmac_f32_e32 v48, v81, v81
	v_fmac_f32_e32 v48, v73, v73
	v_lshlrev_b32_e32 v91, 16, v82
	v_fmac_f32_e32 v48, v101, v101
	v_mov_b32_e32 v89, v42
	v_mov_b32_e32 v42, v75
	v_lshlrev_b32_e32 v59, 16, v79
	v_and_b32_e32 v57, 0xffff0000, v79
	v_lshlrev_b32_e32 v75, 16, v83
	v_and_b32_e32 v79, 0xffff0000, v83
	v_and_b32_e32 v83, 0xffff0000, v82
	v_fmac_f32_e32 v48, v91, v91
	v_fmac_f32_e32 v48, v83, v83
	v_fmac_f32_e32 v48, v75, v75
	v_lshlrev_b32_e32 v90, 16, v86
	v_and_b32_e32 v82, 0xffff0000, v86
	v_mov_b32_e32 v86, v50
	v_lshlrev_b32_e32 v50, 16, v84
	v_fmac_f32_e32 v48, v79, v79
	v_mov_b32_e32 v94, v72
	v_lshlrev_b32_e32 v72, 16, v85
	v_and_b32_e32 v100, 0xffff0000, v85
	v_and_b32_e32 v80, 0xffff0000, v84
	v_pk_fma_f32 v[84:85], v[50:51], v[50:51], v[48:49] op_sel_hi:[1,1,0]
	v_and_b32_e32 v56, 0xffff0000, v71
	v_pk_fma_f32 v[84:85], v[80:81], v[80:81], v[84:85]
	v_lshlrev_b32_e32 v71, 16, v76
	v_pk_fma_f32 v[84:85], v[72:73], v[72:73], v[84:85]
	v_lshlrev_b32_e32 v66, 16, v69
	v_pk_fma_f32 v[84:85], v[100:101], v[100:101], v[84:85]
	v_and_b32_e32 v64, 0xffff0000, v69
	v_pk_fma_f32 v[84:85], v[90:91], v[90:91], v[84:85]
	v_and_b32_e32 v69, 0xffff0000, v76
	v_pk_fma_f32 v[84:85], v[82:83], v[82:83], v[84:85]
	v_mul_f32_e32 v48, v71, v71
	v_pk_fma_f32 v[84:85], v[74:75], v[74:75], v[84:85]
	v_lshlrev_b32_e32 v67, 16, v77
	v_pk_fma_f32 v[84:85], v[78:79], v[78:79], v[84:85]
	v_and_b32_e32 v65, 0xffff0000, v77
	v_pk_add_f32 v[84:85], v[48:49], v[84:85] op_sel_hi:[0,1]
	v_mul_f32_e32 v48, v69, v69
	v_pk_add_f32 v[84:85], v[48:49], v[84:85] op_sel_hi:[0,1]
	v_mul_f32_e32 v48, v67, v67
	v_pk_add_f32 v[84:85], v[48:49], v[84:85] op_sel_hi:[0,1]
	v_mul_f32_e32 v48, v65, v65
	v_pk_add_f32 v[84:85], v[48:49], v[84:85] op_sel_hi:[0,1]
	v_mul_f32_e32 v48, v63, v63
	v_pk_add_f32 v[84:85], v[48:49], v[84:85] op_sel_hi:[0,1]
	v_mul_f32_e32 v48, v61, v61
	v_pk_add_f32 v[84:85], v[48:49], v[84:85] op_sel_hi:[0,1]
	v_mul_f32_e32 v48, v59, v59
	v_pk_add_f32 v[84:85], v[48:49], v[84:85] op_sel_hi:[0,1]
	v_mul_f32_e32 v48, v57, v57
	v_lshlrev_b32_e32 v62, 16, v70
	v_and_b32_e32 v60, 0xffff0000, v70
	v_lshlrev_b32_e32 v70, 16, v68
	v_pk_add_f32 v[84:85], v[48:49], v[84:85] op_sel_hi:[0,1]
	v_and_b32_e32 v68, 0xffff0000, v68
	v_pk_fma_f32 v[84:85], v[70:71], v[70:71], v[84:85]
	v_mul_f32_e32 v48, v58, v58
	v_pk_fma_f32 v[84:85], v[68:69], v[68:69], v[84:85]
	v_mov_b32_e32 v92, v56
	v_pk_fma_f32 v[84:85], v[66:67], v[66:67], v[84:85]
	v_mov_b32_e32 v93, v58
	v_pk_fma_f32 v[84:85], v[64:65], v[64:65], v[84:85]
	v_mov_b32_e32 v103, v44
	v_pk_fma_f32 v[84:85], v[62:63], v[62:63], v[84:85]
	v_mov_b32_e32 v44, v49
	v_pk_fma_f32 v[84:85], v[60:61], v[60:61], v[84:85]
	s_waitcnt vmcnt(8)
; #define LAS __attribute__((address_space(3)))
; __device__ __forceinline__ void attn_unit(LAS unsigned char* lds, bf16_t* P, const float* qgain, const float* rope, int s, int h, int qb, int lane, int wid, bool dry) {
;     ...
;         { const auto rr = __builtin_amdgcn_permlane32_swap(__float_as_uint(ssq), __float_as_uint(ssq), false, false); ssq = __uint_as_float(rr[0]) + __uint_as_float(rr[1]); }
;         const float rh = __builtin_amdgcn_rsqf(ssq * (1.0f / 64.0f) + EPS) * C2;
;         const int tq = qb * 256 + wid * 32 + r32;
; #pragma unroll
;         for (int d0 = 0; d0 < 4; ++d0) { const f32x4 g0 = *(const f32x4*)(qgain + d0 * 16 + hi * 8), g1 = *(const f32x4*)(qgain + d0 * 16 + hi * 8 + 4);
; #pragma unroll
;             for (int e = 0; e < 8; ++e) y[d0][e] *= rh * (e < 4 ? g0[e & 3] : g1[e & 3]); }
; #pragma unroll
;         for (int hf = 0; hf < 2; ++hf) {
;             const int ir = hf ? (tq & 63) : (tq >> 6);
;             const f32x4 c0 = *(const f32x4*)(rope + ir * 16 + 8 * hi), c1 = *(const f32x4*)(rope + ir * 16 + 8 * hi + 4);
;             const f32x4 s0 = *(const f32x4*)(rope + 1024 + ir * 16 + 8 * hi), s1 = *(const f32x4*)(rope + 1024 + ir * 16 + 8 * hi + 4);
;             u32x4 wa, wb; unsigned* pa = (unsigned*)&wa; unsigned* pb = (unsigned*)&wb; (void)pa; (void)pb;
;             float oa[8], ob[8];
; #pragma unroll
;             for (int e = 0; e < 8; ++e) { const float c = (e < 4 ? c0[e & 3] : c1[e & 3]), sn = (e < 4 ? s0[e & 3] : s1[e & 3]); const float x1 = y[2 * hf][e], x2 = y[2 * hf + 1][e];
;                 oa[e] = x1 * c - x2 * sn; ob[e] = x2 * c + x1 * sn; }
;             wa.x = cvt_pk_bf16(oa[0], oa[1]); wa.y = cvt_pk_bf16(oa[2], oa[3]); wa.z = cvt_pk_bf16(oa[4], oa[5]); wa.w = cvt_pk_bf16(oa[6], oa[7]);
;             wb.x = cvt_pk_bf16(ob[0], ob[1]); wb.y = cvt_pk_bf16(ob[2], ob[3]); wb.z = cvt_pk_bf16(ob[4], ob[5]); wb.w = cvt_pk_bf16(ob[6], ob[7]);
;             qf[2 * hf] = __builtin_bit_cast(bf16x8, wa); qf[2 * hf + 1] = __builtin_bit_cast(bf16x8, wb);
;         }
;     }
;     *(LAS u32x4*)(lds + kdst) = krA; *(LAS u32x4*)(lds + vdst) = vrA; *(LAS u32x4*)(lds + 8192 + kdst) = krB;
;     asm volatile("s_waitcnt vmcnt(0) lgkmcnt(0)\n\ts_barrier" ::: "memory");
	v_mov_b32_e32 v98, v38
	v_pk_add_f32 v[84:85], v[48:49], v[84:85] op_sel_hi:[0,1]
	v_pk_fma_f32 v[84:85], v[92:93], v[92:93], v[84:85]
	s_waitcnt vmcnt(7)
	v_mov_b32_e32 v99, v34
	v_mov_b32_e32 v48, v84
	s_nop 1
	v_permlane32_swap_b32_e32 v84, v48
	v_add_f32_e32 v48, v84, v48
	v_fmamk_f32 v48, v48, 0x3c800000, v217
	v_rsq_f32_e32 v48, v48
	v_mov_b32_e32 v84, v36
	v_mov_b32_e32 v85, v32
	v_mov_b32_e32 v96, v24
	v_mul_f32_e32 v48, 0x3e38aa3b, v48
	v_pk_mul_f32 v[92:93], v[102:103], v[48:49] op_sel_hi:[1,0]
	v_pk_mul_f32 v[44:45], v[44:45], v[48:49] op_sel_hi:[1,0]
	v_pk_mul_f32 v[42:43], v[42:43], v[48:49] op_sel_hi:[1,0]
	v_pk_mul_f32 v[50:51], v[92:93], v[50:51]
	v_pk_mul_f32 v[44:45], v[44:45], v[80:81]
	v_pk_mul_f32 v[42:43], v[42:43], v[78:79]
	v_mov_b32_e32 v78, v32
	v_mov_b32_e32 v79, v36
	v_mov_b32_e32 v32, v37
	v_pk_mul_f32 v[80:81], v[86:87], v[48:49] op_sel_hi:[1,0]
	v_pk_mul_f32 v[40:41], v[40:41], v[48:49] op_sel_hi:[1,0]
	v_pk_mul_f32 v[78:79], v[50:51], v[78:79]
	v_pk_mul_f32 v[50:51], v[50:51], v[84:85]
	v_mov_b32_e32 v36, v33
	v_pk_mul_f32 v[32:33], v[44:45], v[32:33]
	v_pk_mul_f32 v[72:73], v[80:81], v[72:73]
	v_pk_mul_f32 v[46:47], v[46:47], v[48:49] op_sel_hi:[1,0]
	v_pk_mul_f32 v[80:81], v[94:95], v[48:49] op_sel_hi:[1,0]
	v_pk_mul_f32 v[40:41], v[40:41], v[82:83]
	v_pk_mul_f32 v[82:83], v[88:89], v[48:49] op_sel_hi:[1,0]
	v_sub_f32_e32 v49, v79, v78
	v_add_f32_e32 v78, v50, v51
	v_pk_mul_f32 v[50:51], v[44:45], v[36:37]
	v_add_f32_e32 v37, v32, v33
	v_mov_b32_e32 v32, v34
	v_mov_b32_e32 v33, v38
	v_pk_mul_f32 v[32:33], v[72:73], v[32:33]
	v_pk_mul_f32 v[46:47], v[46:47], v[100:101]
	v_sub_f32_e32 v44, v33, v32
	v_pk_mul_f32 v[32:33], v[72:73], v[98:99]
	v_mov_b32_e32 v38, v35
	v_add_f32_e32 v45, v32, v33
	v_pk_mul_f32 v[32:33], v[46:47], v[38:39]
	v_mov_b32_e32 v34, v39
	v_sub_f32_e32 v38, v33, v32
	v_pk_mul_f32 v[32:33], v[46:47], v[34:35]
	v_pk_mul_f32 v[80:81], v[80:81], v[90:91]
	v_add_f32_e32 v34, v32, v33
	v_mov_b32_e32 v32, v28
	v_mov_b32_e32 v33, v24
	v_mov_b32_e32 v97, v28
	v_pk_mul_f32 v[32:33], v[80:81], v[32:33]
	v_mov_b32_e32 v24, v29
	v_sub_f32_e32 v35, v33, v32
	v_pk_mul_f32 v[32:33], v[80:81], v[96:97]
	v_mov_b32_e32 v28, v25
	v_add_f32_e32 v39, v32, v33
	v_pk_mul_f32 v[32:33], v[40:41], v[24:25]
	v_pk_mul_f32 v[24:25], v[40:41], v[28:29]
	v_pk_mul_f32 v[74:75], v[82:83], v[74:75]
	v_add_f32_e32 v28, v24, v25
	v_mov_b32_e32 v24, v30
	v_mov_b32_e32 v25, v26
	v_mov_b32_e32 v76, v26
	v_mov_b32_e32 v77, v30
	v_pk_mul_f32 v[24:25], v[74:75], v[24:25]
	v_mov_b32_e32 v26, v31
	v_sub_f32_e32 v29, v25, v24
	v_pk_mul_f32 v[24:25], v[74:75], v[76:77]
	v_sub_f32_e32 v32, v33, v32
	v_add_f32_e32 v33, v24, v25
	v_pk_mul_f32 v[24:25], v[42:43], v[26:27]
	v_mov_b32_e32 v30, v27
	v_sub_f32_e32 v26, v25, v24
	v_pk_mul_f32 v[24:25], v[42:43], v[30:31]
	v_sub_f32_e32 v36, v51, v50
	v_add_f32_e32 v24, v24, v25
	v_cvt_pk_bf16_f32 v118, v49, v36
	v_cvt_pk_bf16_f32 v119, v44, v38
	v_cvt_pk_bf16_f32 v120, v35, v32
	v_cvt_pk_bf16_f32 v121, v29, v26
	v_cvt_pk_bf16_f32 v122, v78, v37
	v_cvt_pk_bf16_f32 v123, v45, v34
	v_cvt_pk_bf16_f32 v124, v39, v28
	v_cvt_pk_bf16_f32 v125, v33, v24
	global_load_dwordx4 v[24:27], v[160:161], off
	global_load_dwordx4 v[28:31], v[158:159], off
	global_load_dwordx4 v[32:35], v[160:161], off offset:16
	global_load_dwordx4 v[36:39], v[158:159], off offset:16
	s_waitcnt vmcnt(7)
	v_mov_b32_e32 v40, v22
	v_mov_b32_e32 v41, v10
	v_mov_b32_e32 v10, v23
	v_mov_b32_e32 v22, v20
	v_mov_b32_e32 v23, v8
	v_mov_b32_e32 v8, v21
	v_mov_b32_e32 v20, v18
	v_mov_b32_e32 v21, v14
	v_mov_b32_e32 v14, v19
	v_mov_b32_e32 v18, v16
	v_mov_b32_e32 v19, v12
	v_mov_b32_e32 v12, v17
	v_pk_mul_f32 v[16:17], v[48:49], v[18:19] op_sel_hi:[0,1]
	v_pk_mul_f32 v[16:17], v[16:17], v[70:71]
	v_pk_mul_f32 v[18:19], v[48:49], v[20:21] op_sel_hi:[0,1]
	v_pk_mul_f32 v[20:21], v[48:49], v[22:23] op_sel_hi:[0,1]
	v_pk_mul_f32 v[22:23], v[48:49], v[40:41] op_sel_hi:[0,1]
	v_pk_mul_f32 v[12:13], v[48:49], v[12:13] op_sel_hi:[0,1]
	v_pk_mul_f32 v[12:13], v[12:13], v[68:69]
	v_pk_mul_f32 v[18:19], v[18:19], v[66:67]
	v_pk_mul_f32 v[14:15], v[48:49], v[14:15] op_sel_hi:[0,1]
	v_pk_mul_f32 v[14:15], v[14:15], v[64:65]
	v_pk_mul_f32 v[20:21], v[20:21], v[62:63]
	v_pk_mul_f32 v[8:9], v[48:49], v[8:9] op_sel_hi:[0,1]
	v_pk_mul_f32 v[8:9], v[8:9], v[60:61]
	v_pk_mul_f32 v[22:23], v[22:23], v[58:59]
	v_pk_mul_f32 v[10:11], v[48:49], v[10:11] op_sel_hi:[0,1]
	v_pk_mul_f32 v[10:11], v[10:11], v[56:57]
	s_waitcnt vmcnt(3)
	v_mov_b32_e32 v40, v24
	s_waitcnt vmcnt(2)
	v_mov_b32_e32 v41, v28
	v_pk_mul_f32 v[40:41], v[16:17], v[40:41]
	s_nop 0
	v_sub_f32_e32 v42, v41, v40
	v_mov_b32_e32 v40, v28
	v_mov_b32_e32 v41, v24
	v_pk_mul_f32 v[16:17], v[16:17], v[40:41]
	v_mov_b32_e32 v28, v25
	v_mov_b32_e32 v24, v29
	v_add_f32_e32 v40, v16, v17
	v_pk_mul_f32 v[16:17], v[12:13], v[28:29]
	v_pk_mul_f32 v[12:13], v[12:13], v[24:25]
	v_sub_f32_e32 v16, v17, v16
	v_add_f32_e32 v17, v12, v13
	v_mov_b32_e32 v12, v26
	v_mov_b32_e32 v13, v30
	v_pk_mul_f32 v[12:13], v[18:19], v[12:13]
	v_cvt_pk_bf16_f32 v126, v42, v16
	s_nop 0
	v_sub_f32_e32 v24, v13, v12
	v_mov_b32_e32 v12, v30
	v_mov_b32_e32 v13, v26
	v_pk_mul_f32 v[12:13], v[18:19], v[12:13]
	v_mov_b32_e32 v30, v27
	v_add_f32_e32 v18, v12, v13
	v_pk_mul_f32 v[12:13], v[14:15], v[30:31]
	v_mov_b32_e32 v26, v31
	v_sub_f32_e32 v19, v13, v12
	v_pk_mul_f32 v[12:13], v[14:15], v[26:27]
	v_cvt_pk_bf16_f32 v127, v24, v19
	v_add_co_u32_e32 v24, vcc, s9, v52
	v_add_f32_e32 v14, v12, v13
	s_waitcnt vmcnt(1)
	v_mov_b32_e32 v12, v32
	s_waitcnt vmcnt(0)
	v_mov_b32_e32 v13, v36
	v_pk_mul_f32 v[12:13], v[20:21], v[12:13]
	v_addc_co_u32_e32 v25, vcc, 0, v53, vcc
	v_sub_f32_e32 v15, v13, v12
	v_mov_b32_e32 v12, v36
	v_mov_b32_e32 v13, v32
	v_pk_mul_f32 v[12:13], v[20:21], v[12:13]
	v_mov_b32_e32 v36, v33
	v_mov_b32_e32 v32, v37
	v_add_f32_e32 v20, v12, v13
	v_pk_mul_f32 v[12:13], v[8:9], v[36:37]
	v_pk_mul_f32 v[8:9], v[8:9], v[32:33]
	v_sub_f32_e32 v12, v13, v12
	v_add_f32_e32 v13, v8, v9
	v_mov_b32_e32 v8, v34
	v_mov_b32_e32 v9, v38
	v_pk_mul_f32 v[8:9], v[22:23], v[8:9]
	v_cvt_pk_bf16_f32 v128, v15, v12
	s_nop 0
	v_sub_f32_e32 v21, v9, v8
	v_mov_b32_e32 v8, v38
	v_mov_b32_e32 v9, v34
	v_pk_mul_f32 v[8:9], v[22:23], v[8:9]
	v_mov_b32_e32 v38, v35
	v_add_f32_e32 v22, v8, v9
	v_pk_mul_f32 v[8:9], v[10:11], v[38:39]
	v_mov_b32_e32 v34, v39
	v_sub_f32_e32 v23, v9, v8
	v_pk_mul_f32 v[8:9], v[10:11], v[34:35]
	v_cvt_pk_bf16_f32 v129, v21, v23
	v_cvt_pk_bf16_f32 v130, v40, v17
	v_cvt_pk_bf16_f32 v131, v18, v14
	v_cvt_pk_bf16_f32 v132, v20, v13
	s_nop 0
	v_add_f32_e32 v8, v8, v9
	v_cvt_pk_bf16_f32 v133, v22, v8
	ds_write_b128 v177, v[0:3]
	ds_write_b128 v178, v[4:7] offset:16384
	ds_write_b128 v177, v[114:117] offset:8192
	s_waitcnt vmcnt(0) lgkmcnt(0)
	s_barrier
; #define LAS __attribute__((address_space(3)))
; #define MFMA32(a, b, c) __builtin_amdgcn_mfma_f32_32x32x16_bf16(a, b, c, 0, 0, 0)
; __device__ __forceinline__ void attn_unit(LAS unsigned char* lds, bf16_t* P, const float* qgain, const float* rope, int s, int h, int qb, int lane, int wid, bool dry) {
;     ...
;     const int koff = hi * 1024 + r32 * 16;
;     const int voff = 16384 + ((lane >> 4) & 1) * 32 + (lane & 3) * 8 + (4 * hi + ((lane & 15) >> 2)) * 64;
;     float mref, lsum = 0.f;
;     f32x16 o0 = {}, o1 = {}, pA0 = {}, pA1 = {}, pB0, pB1;
;     {
; #pragma unroll
;         for (int d0 = 0; d0 < 4; ++d0) {
;             const bf16x8 k0 = *(const LAS bf16x8*)(lds + koff + d0 * 2048), k1 = *(const LAS bf16x8*)(lds + koff + d0 * 2048 + 512);
;             pA0 = MFMA32(k0, qf[d0], pA0); pA1 = MFMA32(k1, qf[d0], pA1);
;         }
;         mref = rowmax32(pA0, pA1);
; #pragma unroll
;         for (int r = 0; r < 16; ++r) { pA0[r] -= mref; pA1[r] -= mref; }
;     }
;     f32x16 negm;
; #pragma unroll
;     for (int r = 0; r < 16; ++r) negm[r] = -mref;
	ds_read_b128 v[0:3], v179
	ds_read_b128 v[16:19], v179 offset:512
	s_waitcnt lgkmcnt(1)
	v_mfma_f32_32x32x16_bf16 v[0:15], v[0:3], v[118:121], 0
	s_waitcnt lgkmcnt(0)
	v_mfma_f32_32x32x16_bf16 v[32:47], v[16:19], v[118:121], 0
	ds_read_b128 v[16:19], v179 offset:2048
	ds_read_b128 v[20:23], v179 offset:2560
	s_waitcnt lgkmcnt(1)
	v_mfma_f32_32x32x16_bf16 v[0:15], v[16:19], v[122:125], v[0:15]
	ds_read_b128 v[16:19], v179 offset:4096
	s_waitcnt lgkmcnt(1)
	v_mfma_f32_32x32x16_bf16 v[32:47], v[20:23], v[122:125], v[32:47]
	ds_read_b128 v[20:23], v179 offset:4608
	s_waitcnt lgkmcnt(1)
	v_mfma_f32_32x32x16_bf16 v[0:15], v[16:19], v[126:129], v[0:15]
	v_add_co_u32_e32 v16, vcc, s8, v54
	s_lshl_b32 s8, s16, 1
	s_nop 0
	v_addc_co_u32_e32 v17, vcc, 0, v55, vcc
	global_load_dwordx4 v[134:137], v[24:25], off offset:3072
	global_load_dwordx4 v[138:141], v[16:17], off offset:3328
	ds_read_b128 v[16:19], v179 offset:6144
	ds_read_b128 v[48:51], v179 offset:6656
	s_waitcnt lgkmcnt(2)
	v_mfma_f32_32x32x16_bf16 v[32:47], v[20:23], v[126:129], v[32:47]
	s_and_b32 s46, s8, 0x80
	v_mad_i64_i32 v[172:173], s[8:9], s38, v227, v[162:163]
	v_mad_i64_i32 v[174:175], s[8:9], s38, v227, v[164:165]
	s_waitcnt lgkmcnt(1)
	v_mfma_f32_32x32x16_bf16 v[0:15], v[16:19], v[130:133], v[0:15]
	v_mov_b64_e32 v[16:17], s[80:81]
	v_mov_b64_e32 v[18:19], s[82:83]
	v_mov_b64_e32 v[20:21], s[84:85]
	v_mov_b64_e32 v[22:23], s[86:87]
	v_mov_b64_e32 v[24:25], s[88:89]
	v_mov_b64_e32 v[26:27], s[90:91]
	v_mov_b64_e32 v[28:29], s[92:93]
	s_waitcnt lgkmcnt(0)
	v_mfma_f32_32x32x16_bf16 v[32:47], v[48:51], v[130:133], v[32:47]
	s_nop 2
	v_max_f32_e32 v48, v1, v1
	v_max_f32_e32 v49, v0, v0
	v_max_f32_e32 v48, v49, v48
	v_mov_b64_e32 v[30:31], s[94:95]
	v_readlane_b32 s90, v255, 43
	v_readlane_b32 s91, v255, 44
	s_nop 2
	v_max3_f32 v49, v2, v3, v33
	v_max3_f32 v48, v48, v32, v34
	v_max3_f32 v48, v48, v35, v4
	v_max3_f32 v49, v49, v6, v7
	v_max3_f32 v48, v48, v5, v36
	v_max3_f32 v49, v49, v38, v39
	v_max3_f32 v48, v48, v37, v8
	v_max3_f32 v49, v49, v10, v11
	v_max3_f32 v48, v48, v9, v40
	v_max3_f32 v49, v49, v42, v43
	v_max3_f32 v48, v48, v41, v12
	v_max3_f32 v49, v49, v14, v15
	v_max3_f32 v48, v48, v13, v44
	v_max3_f32 v49, v49, v46, v47
	v_max3_f32 v48, v48, v45, v49
	v_mov_b32_e32 v49, v48
	s_nop 1
	v_permlane32_swap_b32_e32 v48, v49
	v_max_f32_e32 v49, v49, v49
	v_max_f32_e32 v48, v48, v48
	v_max_f32_e32 v167, v48, v49
	v_sub_f32_e32 v48, v32, v167
	v_xor_b32_e32 v32, 0x80000000, v167
	v_sub_f32_e32 v79, v15, v167
	v_sub_f32_e32 v78, v14, v167
	v_sub_f32_e32 v77, v13, v167
	v_sub_f32_e32 v76, v12, v167
	v_sub_f32_e32 v75, v11, v167
	v_sub_f32_e32 v74, v10, v167
	v_sub_f32_e32 v73, v9, v167
	v_sub_f32_e32 v72, v8, v167
	v_sub_f32_e32 v71, v7, v167
	v_sub_f32_e32 v70, v6, v167
	v_sub_f32_e32 v69, v5, v167
	v_sub_f32_e32 v68, v4, v167
	v_sub_f32_e32 v67, v3, v167
	v_sub_f32_e32 v66, v2, v167
	v_sub_f32_e32 v65, v1, v167
	v_sub_f32_e32 v64, v0, v167
	v_mov_b64_e32 v[0:1], v[16:17]
	v_sub_f32_e32 v63, v47, v167
	v_sub_f32_e32 v62, v46, v167
	v_sub_f32_e32 v61, v45, v167
	v_sub_f32_e32 v60, v44, v167
	v_sub_f32_e32 v59, v43, v167
	v_sub_f32_e32 v58, v42, v167
	v_sub_f32_e32 v57, v41, v167
	v_sub_f32_e32 v56, v40, v167
	v_sub_f32_e32 v55, v39, v167
	v_sub_f32_e32 v54, v38, v167
	v_sub_f32_e32 v53, v37, v167
	v_sub_f32_e32 v52, v36, v167
	v_sub_f32_e32 v51, v35, v167
	v_sub_f32_e32 v50, v34, v167
	v_sub_f32_e32 v49, v33, v167
	v_mov_b64_e32 v[2:3], v[18:19]
	v_mov_b64_e32 v[4:5], v[20:21]
	v_mov_b64_e32 v[6:7], v[22:23]
	v_mov_b64_e32 v[8:9], v[24:25]
	v_mov_b64_e32 v[10:11], v[26:27]
	v_mov_b64_e32 v[12:13], v[28:29]
	v_mov_b64_e32 v[14:15], v[30:31]
	v_mov_b32_e32 v33, v32
	v_mov_b32_e32 v34, v32
	v_mov_b32_e32 v35, v32
	v_mov_b32_e32 v36, v32
	v_mov_b32_e32 v37, v32
	v_mov_b32_e32 v38, v32
	v_mov_b32_e32 v39, v32
	v_mov_b32_e32 v40, v32
	v_mov_b32_e32 v41, v32
	v_mov_b32_e32 v42, v32
	v_mov_b32_e32 v43, v32
	v_mov_b32_e32 v44, v32
	v_mov_b32_e32 v45, v32
	v_mov_b32_e32 v46, v32
	v_mov_b32_e32 v47, v32
	s_cmp_eq_u32 s101, 0
	s_cbranch_scc1 .LBB0_71
	v_lshrrev_b32_e32 v182, 6, v233
	s_nop 0
	v_readfirstlane_b32 s38, v182
	s_nop 3
	s_cmp_ge_u32 s38, 4
	s_cbranch_scc1 .Lfa_g1_entry
	s_branch .Lfa_g0_entry

.Lfa_g0_entry:
	s_mov_b32 s80, 0
.Lfa_g0_loop:
	v_lshl_add_u64 v[146:147], v[174:175], 0, s[46:47]
	v_lshl_add_u64 v[148:149], v[172:173], 0, s[46:47]
	v_add_co_u32_e32 v80, vcc, 0x88d8000, v146
	s_nop 1
	v_addc_co_u32_e32 v81, vcc, 0, v147, vcc
	global_load_dwordx4 v[114:117], v[80:81], off offset:3072
	v_add_co_u32_e32 v80, vcc, 0x8890000, v148
	s_nop 1
	v_addc_co_u32_e32 v81, vcc, 0, v149, vcc
	global_load_dwordx4 v[142:145], v[80:81], off offset:3328
	ds_read_b128 v[80:83], v179 offset:8192
	ds_read_b128 v[182:185], v179 offset:8704
	ds_read_b128 v[186:189], v179 offset:10240
	ds_read_b128 v[190:193], v179 offset:10752
	ds_read_b128 v[200:203], v179 offset:12288
	ds_read_b128 v[204:207], v179 offset:12800
	ds_read_b128 v[208:211], v179 offset:14336
	ds_read_b128 v[212:215], v179 offset:14848
	v_exp_f32_e32 v64, v64
	v_exp_f32_e32 v65, v65
	v_exp_f32_e32 v66, v66
	v_exp_f32_e32 v67, v67
	v_exp_f32_e32 v48, v48
	v_exp_f32_e32 v49, v49
	v_exp_f32_e32 v50, v50
	v_exp_f32_e32 v51, v51
	v_add_f32_e32 v84, v50, v66
	v_add_f32_e32 v85, v51, v67
	v_add_f32_e32 v86, v48, v64
	v_add_f32_e32 v87, v49, v65
	v_cvt_pk_bf16_f32 v64, v64, v65
	v_cvt_pk_bf16_f32 v65, v66, v67
	v_cvt_pk_bf16_f32 v48, v48, v49
	v_cvt_pk_bf16_f32 v49, v50, v51
	s_waitcnt lgkmcnt(7)
	v_mfma_f32_32x32x16_bf16 v[96:111], v[80:83], v[118:121], v[32:47]
	v_exp_f32_e32 v50, v68
	v_exp_f32_e32 v51, v69
	v_exp_f32_e32 v68, v70
	v_exp_f32_e32 v69, v71
	v_add_f32_e32 v70, v50, v86
	v_add_f32_e32 v71, v51, v87
	v_add_f32_e32 v181, v68, v84
	v_add_f32_e32 v228, v69, v85
	v_cvt_pk_bf16_f32 v66, v50, v51
	v_cvt_pk_bf16_f32 v67, v68, v69
	s_waitcnt lgkmcnt(6)
	v_mfma_f32_32x32x16_bf16 v[80:95], v[182:185], v[118:121], v[32:47]
	v_exp_f32_e32 v50, v52
	v_exp_f32_e32 v51, v53
	v_exp_f32_e32 v52, v54
	v_exp_f32_e32 v53, v55
	v_add_f32_e32 v54, v50, v70
	v_add_f32_e32 v55, v51, v71
	v_add_f32_e32 v68, v52, v181
	v_add_f32_e32 v69, v53, v228
	v_cvt_pk_bf16_f32 v50, v50, v51
	v_cvt_pk_bf16_f32 v51, v52, v53
	s_waitcnt lgkmcnt(5)
	v_mfma_f32_32x32x16_bf16 v[96:111], v[186:189], v[122:125], v[96:111]
	v_exp_f32_e32 v52, v72
	v_exp_f32_e32 v53, v73
	v_exp_f32_e32 v70, v74
	v_exp_f32_e32 v71, v75
	v_add_f32_e32 v54, v52, v54
	v_add_f32_e32 v55, v53, v55
	v_add_f32_e32 v72, v70, v68
	v_add_f32_e32 v73, v71, v69
	v_cvt_pk_bf16_f32 v68, v52, v53
	v_cvt_pk_bf16_f32 v69, v70, v71
	s_waitcnt lgkmcnt(4)
	v_mfma_f32_32x32x16_bf16 v[80:95], v[190:193], v[122:125], v[80:95]
	v_exp_f32_e32 v52, v56
	v_exp_f32_e32 v53, v57
	v_exp_f32_e32 v57, v58
	v_exp_f32_e32 v58, v59
	v_add_f32_e32 v54, v52, v54
	v_add_f32_e32 v55, v53, v55
	v_add_f32_e32 v59, v57, v72
	v_add_f32_e32 v70, v58, v73
	v_cvt_pk_bf16_f32 v56, v52, v53
	v_cvt_pk_bf16_f32 v57, v57, v58
	s_waitcnt lgkmcnt(3)
	v_mfma_f32_32x32x16_bf16 v[96:111], v[200:203], v[126:129], v[96:111]
	v_exp_f32_e32 v52, v76
	v_exp_f32_e32 v53, v77
	v_exp_f32_e32 v58, v78
	v_exp_f32_e32 v71, v79
	v_add_f32_e32 v54, v52, v54
	v_add_f32_e32 v55, v53, v55
	v_add_f32_e32 v59, v58, v59
	v_add_f32_e32 v72, v71, v70
	v_cvt_pk_bf16_f32 v70, v52, v53
	v_cvt_pk_bf16_f32 v71, v58, v71
	s_waitcnt lgkmcnt(2)
	v_mfma_f32_32x32x16_bf16 v[80:95], v[204:207], v[126:129], v[80:95]
	v_exp_f32_e32 v58, v60
	v_exp_f32_e32 v60, v61
	v_exp_f32_e32 v61, v62
	v_exp_f32_e32 v62, v63
	v_add_f32_e32 v52, v58, v54
	v_add_f32_e32 v53, v60, v55
	v_add_f32_e32 v54, v61, v59
	v_add_f32_e32 v55, v62, v72
	v_cvt_pk_bf16_f32 v58, v58, v60
	v_cvt_pk_bf16_f32 v59, v61, v62
	s_waitcnt lgkmcnt(1)
	v_mfma_f32_32x32x16_bf16 v[96:111], v[208:211], v[130:133], v[96:111]
	ds_read_b64_tr_b16 v[60:61], v180 offset:16384
	ds_read_b64_tr_b16 v[62:63], v180 offset:16896
	ds_read_b64_tr_b16 v[72:73], v180 offset:20480
	ds_read_b64_tr_b16 v[74:75], v180 offset:20992
	s_waitcnt lgkmcnt(4)
	v_mfma_f32_32x32x16_bf16 v[80:95], v[212:215], v[130:133], v[80:95]
	s_waitcnt lgkmcnt(2)
	v_mfma_f32_32x32x16_bf16 v[16:31], v[60:63], v[64:67], v[16:31]
	s_waitcnt lgkmcnt(0)
	v_mfma_f32_32x32x16_bf16 v[0:15], v[72:75], v[64:67], v[0:15]
	ds_read_b64_tr_b16 v[60:61], v180 offset:17408
	ds_read_b64_tr_b16 v[62:63], v180 offset:17920
	ds_read_b64_tr_b16 v[64:65], v180 offset:21504
	ds_read_b64_tr_b16 v[66:67], v180 offset:22016
	s_waitcnt lgkmcnt(2)
	v_mfma_f32_32x32x16_bf16 v[16:31], v[60:63], v[68:71], v[16:31]
	s_waitcnt lgkmcnt(0)
	v_mfma_f32_32x32x16_bf16 v[0:15], v[64:67], v[68:71], v[0:15]
	ds_read_b64_tr_b16 v[60:61], v180 offset:18432
	ds_read_b64_tr_b16 v[62:63], v180 offset:18944
	ds_read_b64_tr_b16 v[64:65], v180 offset:22528
	ds_read_b64_tr_b16 v[66:67], v180 offset:23040
	s_waitcnt lgkmcnt(2)
	v_mfma_f32_32x32x16_bf16 v[16:31], v[60:63], v[48:51], v[16:31]
	s_waitcnt lgkmcnt(0)
	v_mfma_f32_32x32x16_bf16 v[0:15], v[64:67], v[48:51], v[0:15]
	ds_read_b64_tr_b16 v[48:49], v180 offset:19456
	ds_read_b64_tr_b16 v[50:51], v180 offset:19968
	ds_read_b64_tr_b16 v[60:61], v180 offset:23552
	ds_read_b64_tr_b16 v[62:63], v180 offset:24064
	s_waitcnt lgkmcnt(2)
	v_mfma_f32_32x32x16_bf16 v[16:31], v[48:51], v[56:59], v[16:31]
	s_waitcnt lgkmcnt(0)
	v_mfma_f32_32x32x16_bf16 v[0:15], v[60:63], v[56:59], v[0:15]
	v_add_f32_e32 v182, v52, v53
	v_add_f32_e32 v183, v54, v55
	v_add_f32_e32 v182, v182, v183
	v_add_f32_e32 v169, v169, v182
	s_waitcnt vmcnt(2)
	ds_write_b128 v177, v[134:137]
	ds_write_b128 v178, v[138:141] offset:24576
	s_waitcnt lgkmcnt(0)
	s_barrier
	v_add_co_u32_e32 v64, vcc, 0x8920000, v146
	s_nop 1
	v_addc_co_u32_e32 v65, vcc, 0, v147, vcc
	global_load_dwordx4 v[134:137], v[64:65], off offset:3072
	v_add_co_u32_e32 v64, vcc, 0x88d8000, v148
	s_nop 1
	v_addc_co_u32_e32 v65, vcc, 0, v149, vcc
	global_load_dwordx4 v[138:141], v[64:65], off offset:3328
	ds_read_b128 v[182:185], v179
	ds_read_b128 v[186:189], v179 offset:512
	ds_read_b128 v[190:193], v179 offset:2048
	ds_read_b128 v[200:203], v179 offset:2560
	ds_read_b128 v[204:207], v179 offset:4096
	ds_read_b128 v[208:211], v179 offset:4608
	ds_read_b128 v[212:215], v179 offset:6144
	ds_read_b128 v[146:149], v179 offset:6656
	v_exp_f32_e32 v64, v96
	v_exp_f32_e32 v65, v97
	v_exp_f32_e32 v66, v98
	v_exp_f32_e32 v67, v99
	v_cvt_pk_bf16_f32 v96, v64, v65
	v_cvt_pk_bf16_f32 v97, v66, v67
	v_exp_f32_e32 v68, v80
	v_exp_f32_e32 v69, v81
	v_exp_f32_e32 v70, v82
	v_exp_f32_e32 v71, v83
	v_cvt_pk_bf16_f32 v80, v68, v69
	v_cvt_pk_bf16_f32 v81, v70, v71
	v_add_f32_e32 v68, v68, v64
	v_add_f32_e32 v69, v69, v65
	v_add_f32_e32 v82, v70, v66
	v_add_f32_e32 v83, v71, v67
	v_exp_f32_e32 v98, v100
	v_exp_f32_e32 v99, v101
	v_exp_f32_e32 v100, v102
	v_exp_f32_e32 v101, v103
	v_add_f32_e32 v102, v98, v68
	v_add_f32_e32 v103, v99, v69
	s_waitcnt lgkmcnt(7)
	v_mfma_f32_32x32x16_bf16 v[64:79], v[182:185], v[118:121], v[32:47]
	v_add_f32_e32 v82, v100, v82
	v_add_f32_e32 v83, v101, v83
	v_cvt_pk_bf16_f32 v98, v98, v99
	v_cvt_pk_bf16_f32 v99, v100, v101
	s_waitcnt lgkmcnt(6)
	v_mfma_f32_32x32x16_bf16 v[48:63], v[186:189], v[118:121], v[32:47]
	v_exp_f32_e32 v84, v84
	v_exp_f32_e32 v85, v85
	v_exp_f32_e32 v86, v86
	v_exp_f32_e32 v87, v87
	v_add_f32_e32 v100, v84, v102
	v_add_f32_e32 v101, v85, v103
	v_add_f32_e32 v102, v86, v82
	v_add_f32_e32 v103, v87, v83
	v_cvt_pk_bf16_f32 v82, v84, v85
	v_cvt_pk_bf16_f32 v83, v86, v87
	s_waitcnt lgkmcnt(5)
	v_mfma_f32_32x32x16_bf16 v[64:79], v[190:193], v[122:125], v[64:79]
	v_exp_f32_e32 v84, v104
	v_exp_f32_e32 v85, v105
	v_exp_f32_e32 v86, v106
	v_exp_f32_e32 v87, v107
	v_add_f32_e32 v104, v84, v100
	v_add_f32_e32 v105, v85, v101
	v_add_f32_e32 v102, v86, v102
	v_add_f32_e32 v103, v87, v103
	v_cvt_pk_bf16_f32 v100, v84, v85
	v_cvt_pk_bf16_f32 v101, v86, v87
	s_waitcnt lgkmcnt(4)
	v_mfma_f32_32x32x16_bf16 v[48:63], v[200:203], v[122:125], v[48:63]
	v_exp_f32_e32 v84, v88
	v_exp_f32_e32 v85, v89
	v_exp_f32_e32 v86, v90
	v_exp_f32_e32 v87, v91
	v_add_f32_e32 v90, v84, v104
	v_add_f32_e32 v91, v85, v105
	v_add_f32_e32 v102, v86, v102
	v_add_f32_e32 v103, v87, v103
	v_cvt_pk_bf16_f32 v88, v84, v85
	v_cvt_pk_bf16_f32 v89, v86, v87
	s_waitcnt lgkmcnt(3)
	v_mfma_f32_32x32x16_bf16 v[64:79], v[204:207], v[126:129], v[64:79]
	v_exp_f32_e32 v84, v108
	v_exp_f32_e32 v85, v109
	v_exp_f32_e32 v86, v110
	v_exp_f32_e32 v87, v111
	v_add_f32_e32 v90, v84, v90
	v_add_f32_e32 v91, v85, v91
	v_add_f32_e32 v104, v86, v102
	v_add_f32_e32 v105, v87, v103
	v_cvt_pk_bf16_f32 v102, v84, v85
	v_cvt_pk_bf16_f32 v103, v86, v87
	s_waitcnt lgkmcnt(2)
	v_mfma_f32_32x32x16_bf16 v[48:63], v[208:211], v[126:129], v[48:63]
	v_exp_f32_e32 v92, v92
	v_exp_f32_e32 v93, v93
	v_exp_f32_e32 v94, v94
	v_exp_f32_e32 v95, v95
	v_add_f32_e32 v84, v92, v90
	v_add_f32_e32 v85, v93, v91
	v_add_f32_e32 v86, v94, v104
	v_add_f32_e32 v87, v95, v105
	v_cvt_pk_bf16_f32 v90, v92, v93
	v_cvt_pk_bf16_f32 v91, v94, v95
	s_waitcnt lgkmcnt(1)
	v_mfma_f32_32x32x16_bf16 v[64:79], v[212:215], v[130:133], v[64:79]
	ds_read_b64_tr_b16 v[92:93], v180 offset:24576
	ds_read_b64_tr_b16 v[94:95], v180 offset:25088
	ds_read_b64_tr_b16 v[104:105], v180 offset:28672
	ds_read_b64_tr_b16 v[106:107], v180 offset:29184
	s_waitcnt lgkmcnt(4)
	v_mfma_f32_32x32x16_bf16 v[48:63], v[146:149], v[130:133], v[48:63]
	s_waitcnt lgkmcnt(2)
	v_mfma_f32_32x32x16_bf16 v[16:31], v[92:95], v[96:99], v[16:31]
	s_waitcnt lgkmcnt(0)
	v_mfma_f32_32x32x16_bf16 v[0:15], v[104:107], v[96:99], v[0:15]
	ds_read_b64_tr_b16 v[92:93], v180 offset:25600
	ds_read_b64_tr_b16 v[94:95], v180 offset:26112
	ds_read_b64_tr_b16 v[96:97], v180 offset:29696
	ds_read_b64_tr_b16 v[98:99], v180 offset:30208
	s_waitcnt lgkmcnt(2)
	v_mfma_f32_32x32x16_bf16 v[16:31], v[92:95], v[100:103], v[16:31]
	s_waitcnt lgkmcnt(0)
	v_mfma_f32_32x32x16_bf16 v[0:15], v[96:99], v[100:103], v[0:15]
	ds_read_b64_tr_b16 v[92:93], v180 offset:26624
	ds_read_b64_tr_b16 v[94:95], v180 offset:27136
	ds_read_b64_tr_b16 v[96:97], v180 offset:30720
	ds_read_b64_tr_b16 v[98:99], v180 offset:31232
	s_waitcnt lgkmcnt(2)
	v_mfma_f32_32x32x16_bf16 v[16:31], v[92:95], v[80:83], v[16:31]
	s_waitcnt lgkmcnt(0)
	v_mfma_f32_32x32x16_bf16 v[0:15], v[96:99], v[80:83], v[0:15]
	ds_read_b64_tr_b16 v[80:81], v180 offset:27648
	ds_read_b64_tr_b16 v[82:83], v180 offset:28160
	ds_read_b64_tr_b16 v[92:93], v180 offset:31744
	ds_read_b64_tr_b16 v[94:95], v180 offset:32256
	s_waitcnt lgkmcnt(2)
	v_mfma_f32_32x32x16_bf16 v[16:31], v[80:83], v[88:91], v[16:31]
	s_waitcnt lgkmcnt(0)
	v_mfma_f32_32x32x16_bf16 v[0:15], v[92:95], v[88:91], v[0:15]
	v_add_f32_e32 v182, v84, v85
	v_add_f32_e32 v183, v86, v87
	v_add_f32_e32 v182, v182, v183
	v_add_f32_e32 v169, v169, v182
	s_waitcnt vmcnt(2)
	ds_write_b128 v177, v[114:117] offset:8192
	ds_write_b128 v178, v[142:145] offset:32768
	s_waitcnt lgkmcnt(0)
	s_barrier
	v_lshl_add_u64 v[172:173], v[172:173], 0, s[4:5]
	v_lshl_add_u64 v[174:175], v[174:175], 0, s[4:5]
	v_lshl_add_u64 v[146:147], v[174:175], 0, s[46:47]
	v_lshl_add_u64 v[148:149], v[172:173], 0, s[46:47]
	v_add_co_u32_e32 v80, vcc, 0x88d8000, v146
	s_nop 1
	v_addc_co_u32_e32 v81, vcc, 0, v147, vcc
	global_load_dwordx4 v[114:117], v[80:81], off offset:3072
	v_add_co_u32_e32 v80, vcc, 0x8890000, v148
	s_nop 1
	v_addc_co_u32_e32 v81, vcc, 0, v149, vcc
	global_load_dwordx4 v[142:145], v[80:81], off offset:3328
	ds_read_b128 v[80:83], v179 offset:8192
	ds_read_b128 v[182:185], v179 offset:8704
	ds_read_b128 v[186:189], v179 offset:10240
	ds_read_b128 v[190:193], v179 offset:10752
	ds_read_b128 v[200:203], v179 offset:12288
	ds_read_b128 v[204:207], v179 offset:12800
	ds_read_b128 v[208:211], v179 offset:14336
	ds_read_b128 v[212:215], v179 offset:14848
	v_exp_f32_e32 v64, v64
	v_exp_f32_e32 v65, v65
	v_exp_f32_e32 v66, v66
	v_exp_f32_e32 v67, v67
	v_exp_f32_e32 v48, v48
	v_exp_f32_e32 v49, v49
	v_exp_f32_e32 v50, v50
	v_exp_f32_e32 v51, v51
	v_add_f32_e32 v84, v50, v66
	v_add_f32_e32 v85, v51, v67
	v_add_f32_e32 v86, v48, v64
	v_add_f32_e32 v87, v49, v65
	v_cvt_pk_bf16_f32 v64, v64, v65
	v_cvt_pk_bf16_f32 v65, v66, v67
	v_cvt_pk_bf16_f32 v48, v48, v49
	v_cvt_pk_bf16_f32 v49, v50, v51
	s_waitcnt lgkmcnt(7)
	v_mfma_f32_32x32x16_bf16 v[96:111], v[80:83], v[118:121], v[32:47]
	v_exp_f32_e32 v50, v68
	v_exp_f32_e32 v51, v69
	v_exp_f32_e32 v68, v70
	v_exp_f32_e32 v69, v71
	v_add_f32_e32 v70, v50, v86
	v_add_f32_e32 v71, v51, v87
	v_add_f32_e32 v181, v68, v84
	v_add_f32_e32 v228, v69, v85
	v_cvt_pk_bf16_f32 v66, v50, v51
	v_cvt_pk_bf16_f32 v67, v68, v69
	s_waitcnt lgkmcnt(6)
	v_mfma_f32_32x32x16_bf16 v[80:95], v[182:185], v[118:121], v[32:47]
	v_exp_f32_e32 v50, v52
	v_exp_f32_e32 v51, v53
	v_exp_f32_e32 v52, v54
	v_exp_f32_e32 v53, v55
	v_add_f32_e32 v54, v50, v70
	v_add_f32_e32 v55, v51, v71
	v_add_f32_e32 v68, v52, v181
	v_add_f32_e32 v69, v53, v228
	v_cvt_pk_bf16_f32 v50, v50, v51
	v_cvt_pk_bf16_f32 v51, v52, v53
	s_waitcnt lgkmcnt(5)
	v_mfma_f32_32x32x16_bf16 v[96:111], v[186:189], v[122:125], v[96:111]
	v_exp_f32_e32 v52, v72
	v_exp_f32_e32 v53, v73
	v_exp_f32_e32 v70, v74
	v_exp_f32_e32 v71, v75
	v_add_f32_e32 v54, v52, v54
	v_add_f32_e32 v55, v53, v55
	v_add_f32_e32 v72, v70, v68
	v_add_f32_e32 v73, v71, v69
	v_cvt_pk_bf16_f32 v68, v52, v53
	v_cvt_pk_bf16_f32 v69, v70, v71
	s_waitcnt lgkmcnt(4)
	v_mfma_f32_32x32x16_bf16 v[80:95], v[190:193], v[122:125], v[80:95]
	v_exp_f32_e32 v52, v56
	v_exp_f32_e32 v53, v57
	v_exp_f32_e32 v57, v58
	v_exp_f32_e32 v58, v59
	v_add_f32_e32 v54, v52, v54
	v_add_f32_e32 v55, v53, v55
	v_add_f32_e32 v59, v57, v72
	v_add_f32_e32 v70, v58, v73
	v_cvt_pk_bf16_f32 v56, v52, v53
	v_cvt_pk_bf16_f32 v57, v57, v58
	s_waitcnt lgkmcnt(3)
	v_mfma_f32_32x32x16_bf16 v[96:111], v[200:203], v[126:129], v[96:111]
	v_exp_f32_e32 v52, v76
	v_exp_f32_e32 v53, v77
	v_exp_f32_e32 v58, v78
	v_exp_f32_e32 v71, v79
	v_add_f32_e32 v54, v52, v54
	v_add_f32_e32 v55, v53, v55
	v_add_f32_e32 v59, v58, v59
	v_add_f32_e32 v72, v71, v70
	v_cvt_pk_bf16_f32 v70, v52, v53
	v_cvt_pk_bf16_f32 v71, v58, v71
	s_waitcnt lgkmcnt(2)
	v_mfma_f32_32x32x16_bf16 v[80:95], v[204:207], v[126:129], v[80:95]
	v_exp_f32_e32 v58, v60
	v_exp_f32_e32 v60, v61
	v_exp_f32_e32 v61, v62
	v_exp_f32_e32 v62, v63
	v_add_f32_e32 v52, v58, v54
	v_add_f32_e32 v53, v60, v55
	v_add_f32_e32 v54, v61, v59
	v_add_f32_e32 v55, v62, v72
	v_cvt_pk_bf16_f32 v58, v58, v60
	v_cvt_pk_bf16_f32 v59, v61, v62
	s_waitcnt lgkmcnt(1)
	v_mfma_f32_32x32x16_bf16 v[96:111], v[208:211], v[130:133], v[96:111]
	ds_read_b64_tr_b16 v[60:61], v180 offset:32768
	ds_read_b64_tr_b16 v[62:63], v180 offset:33280
	ds_read_b64_tr_b16 v[72:73], v180 offset:36864
	ds_read_b64_tr_b16 v[74:75], v180 offset:37376
	s_waitcnt lgkmcnt(4)
	v_mfma_f32_32x32x16_bf16 v[80:95], v[212:215], v[130:133], v[80:95]
	s_waitcnt lgkmcnt(2)
	v_mfma_f32_32x32x16_bf16 v[16:31], v[60:63], v[64:67], v[16:31]
	s_waitcnt lgkmcnt(0)
	v_mfma_f32_32x32x16_bf16 v[0:15], v[72:75], v[64:67], v[0:15]
	ds_read_b64_tr_b16 v[60:61], v180 offset:33792
	ds_read_b64_tr_b16 v[62:63], v180 offset:34304
	ds_read_b64_tr_b16 v[64:65], v180 offset:37888
	ds_read_b64_tr_b16 v[66:67], v180 offset:38400
	s_waitcnt lgkmcnt(2)
	v_mfma_f32_32x32x16_bf16 v[16:31], v[60:63], v[68:71], v[16:31]
	s_waitcnt lgkmcnt(0)
	v_mfma_f32_32x32x16_bf16 v[0:15], v[64:67], v[68:71], v[0:15]
	ds_read_b64_tr_b16 v[60:61], v180 offset:34816
	ds_read_b64_tr_b16 v[62:63], v180 offset:35328
	ds_read_b64_tr_b16 v[64:65], v180 offset:38912
	ds_read_b64_tr_b16 v[66:67], v180 offset:39424
	s_waitcnt lgkmcnt(2)
	v_mfma_f32_32x32x16_bf16 v[16:31], v[60:63], v[48:51], v[16:31]
	s_waitcnt lgkmcnt(0)
	v_mfma_f32_32x32x16_bf16 v[0:15], v[64:67], v[48:51], v[0:15]
	ds_read_b64_tr_b16 v[48:49], v180 offset:35840
	ds_read_b64_tr_b16 v[50:51], v180 offset:36352
	ds_read_b64_tr_b16 v[60:61], v180 offset:39936
	ds_read_b64_tr_b16 v[62:63], v180 offset:40448
	s_waitcnt lgkmcnt(2)
	v_mfma_f32_32x32x16_bf16 v[16:31], v[48:51], v[56:59], v[16:31]
	s_waitcnt lgkmcnt(0)
	v_mfma_f32_32x32x16_bf16 v[0:15], v[60:63], v[56:59], v[0:15]
	v_add_f32_e32 v182, v52, v53
	v_add_f32_e32 v183, v54, v55
	v_add_f32_e32 v182, v182, v183
	v_add_f32_e32 v169, v169, v182
	s_waitcnt vmcnt(2)
	ds_write_b128 v177, v[134:137]
	ds_write_b128 v178, v[138:141] offset:40960
	s_waitcnt lgkmcnt(0)
	s_barrier
; __device__ __forceinline__ void attn_unit(LAS unsigned char* lds, bf16_t* P, const float* qgain, const float* rope, int s, int h, int qb, int lane, int wid, bool dry) {
;     ...
;     for (int t = 0; t < NT; t += 2) {
;         ASTEP(t, pA0, pA1, pB0, pB1, krA, vrA, krB, vrB);
;         ASTEP(t + 1, pB0, pB1, pA0, pA1, krB, vrB, krA, vrA);
;     }
	v_add_co_u32_e32 v64, vcc, 0x8920000, v146
	s_nop 1
	v_addc_co_u32_e32 v65, vcc, 0, v147, vcc
	global_load_dwordx4 v[134:137], v[64:65], off offset:3072
	v_add_co_u32_e32 v64, vcc, 0x88d8000, v148
	s_nop 1
	v_addc_co_u32_e32 v65, vcc, 0, v149, vcc
	global_load_dwordx4 v[138:141], v[64:65], off offset:3328
	ds_read_b128 v[182:185], v179
	ds_read_b128 v[186:189], v179 offset:512
	ds_read_b128 v[190:193], v179 offset:2048
	ds_read_b128 v[200:203], v179 offset:2560
	ds_read_b128 v[204:207], v179 offset:4096
	ds_read_b128 v[208:211], v179 offset:4608
	ds_read_b128 v[212:215], v179 offset:6144
	ds_read_b128 v[146:149], v179 offset:6656
	v_exp_f32_e32 v64, v96
	v_exp_f32_e32 v65, v97
	v_exp_f32_e32 v66, v98
	v_exp_f32_e32 v67, v99
	v_cvt_pk_bf16_f32 v96, v64, v65
	v_cvt_pk_bf16_f32 v97, v66, v67
	v_exp_f32_e32 v68, v80
	v_exp_f32_e32 v69, v81
	v_exp_f32_e32 v70, v82
	v_exp_f32_e32 v71, v83
	v_cvt_pk_bf16_f32 v80, v68, v69
	v_cvt_pk_bf16_f32 v81, v70, v71
	v_add_f32_e32 v68, v68, v64
	v_add_f32_e32 v69, v69, v65
	v_add_f32_e32 v82, v70, v66
	v_add_f32_e32 v83, v71, v67
	v_exp_f32_e32 v98, v100
	v_exp_f32_e32 v99, v101
	v_exp_f32_e32 v100, v102
	v_exp_f32_e32 v101, v103
	v_add_f32_e32 v102, v98, v68
	v_add_f32_e32 v103, v99, v69
	s_waitcnt lgkmcnt(7)
	v_mfma_f32_32x32x16_bf16 v[64:79], v[182:185], v[118:121], v[32:47]
	v_add_f32_e32 v82, v100, v82
	v_add_f32_e32 v83, v101, v83
	v_cvt_pk_bf16_f32 v98, v98, v99
	v_cvt_pk_bf16_f32 v99, v100, v101
	s_waitcnt lgkmcnt(6)
	v_mfma_f32_32x32x16_bf16 v[48:63], v[186:189], v[118:121], v[32:47]
	v_exp_f32_e32 v84, v84
	v_exp_f32_e32 v85, v85
	v_exp_f32_e32 v86, v86
	v_exp_f32_e32 v87, v87
	v_add_f32_e32 v100, v84, v102
	v_add_f32_e32 v101, v85, v103
	v_add_f32_e32 v102, v86, v82
	v_add_f32_e32 v103, v87, v83
	v_cvt_pk_bf16_f32 v82, v84, v85
	v_cvt_pk_bf16_f32 v83, v86, v87
	s_waitcnt lgkmcnt(5)
	v_mfma_f32_32x32x16_bf16 v[64:79], v[190:193], v[122:125], v[64:79]
	v_exp_f32_e32 v84, v104
	v_exp_f32_e32 v85, v105
	v_exp_f32_e32 v86, v106
	v_exp_f32_e32 v87, v107
	v_add_f32_e32 v104, v84, v100
	v_add_f32_e32 v105, v85, v101
	v_add_f32_e32 v102, v86, v102
	v_add_f32_e32 v103, v87, v103
	v_cvt_pk_bf16_f32 v100, v84, v85
	v_cvt_pk_bf16_f32 v101, v86, v87
	s_waitcnt lgkmcnt(4)
	v_mfma_f32_32x32x16_bf16 v[48:63], v[200:203], v[122:125], v[48:63]
	v_exp_f32_e32 v84, v88
	v_exp_f32_e32 v85, v89
	v_exp_f32_e32 v86, v90
	v_exp_f32_e32 v87, v91
	v_add_f32_e32 v90, v84, v104
	v_add_f32_e32 v91, v85, v105
	v_add_f32_e32 v102, v86, v102
	v_add_f32_e32 v103, v87, v103
	v_cvt_pk_bf16_f32 v88, v84, v85
	v_cvt_pk_bf16_f32 v89, v86, v87
	s_waitcnt lgkmcnt(3)
	v_mfma_f32_32x32x16_bf16 v[64:79], v[204:207], v[126:129], v[64:79]
	v_exp_f32_e32 v84, v108
	v_exp_f32_e32 v85, v109
	v_exp_f32_e32 v86, v110
	v_exp_f32_e32 v87, v111
	v_add_f32_e32 v90, v84, v90
	v_add_f32_e32 v91, v85, v91
	v_add_f32_e32 v104, v86, v102
	v_add_f32_e32 v105, v87, v103
	v_cvt_pk_bf16_f32 v102, v84, v85
	v_cvt_pk_bf16_f32 v103, v86, v87
	s_waitcnt lgkmcnt(2)
	v_mfma_f32_32x32x16_bf16 v[48:63], v[208:211], v[126:129], v[48:63]
	v_exp_f32_e32 v92, v92
	v_exp_f32_e32 v93, v93
	v_exp_f32_e32 v94, v94
	v_exp_f32_e32 v95, v95
	v_add_f32_e32 v84, v92, v90
	v_add_f32_e32 v85, v93, v91
	v_add_f32_e32 v86, v94, v104
	v_add_f32_e32 v87, v95, v105
	v_cvt_pk_bf16_f32 v90, v92, v93
	v_cvt_pk_bf16_f32 v91, v94, v95
	s_waitcnt lgkmcnt(1)
	v_mfma_f32_32x32x16_bf16 v[64:79], v[212:215], v[130:133], v[64:79]
	ds_read_b64_tr_b16 v[92:93], v180 offset:40960
	ds_read_b64_tr_b16 v[94:95], v180 offset:41472
	ds_read_b64_tr_b16 v[104:105], v180 offset:45056
	ds_read_b64_tr_b16 v[106:107], v180 offset:45568
	s_waitcnt lgkmcnt(4)
	v_mfma_f32_32x32x16_bf16 v[48:63], v[146:149], v[130:133], v[48:63]
	s_waitcnt lgkmcnt(2)
	v_mfma_f32_32x32x16_bf16 v[16:31], v[92:95], v[96:99], v[16:31]
	s_waitcnt lgkmcnt(0)
	v_mfma_f32_32x32x16_bf16 v[0:15], v[104:107], v[96:99], v[0:15]
	ds_read_b64_tr_b16 v[92:93], v180 offset:41984
	ds_read_b64_tr_b16 v[94:95], v180 offset:42496
	ds_read_b64_tr_b16 v[96:97], v180 offset:46080
	ds_read_b64_tr_b16 v[98:99], v180 offset:46592
	s_waitcnt lgkmcnt(2)
	v_mfma_f32_32x32x16_bf16 v[16:31], v[92:95], v[100:103], v[16:31]
	s_waitcnt lgkmcnt(0)
	v_mfma_f32_32x32x16_bf16 v[0:15], v[96:99], v[100:103], v[0:15]
	ds_read_b64_tr_b16 v[92:93], v180 offset:43008
	ds_read_b64_tr_b16 v[94:95], v180 offset:43520
	ds_read_b64_tr_b16 v[96:97], v180 offset:47104
	ds_read_b64_tr_b16 v[98:99], v180 offset:47616
	s_waitcnt lgkmcnt(2)
	v_mfma_f32_32x32x16_bf16 v[16:31], v[92:95], v[80:83], v[16:31]
	s_waitcnt lgkmcnt(0)
	v_mfma_f32_32x32x16_bf16 v[0:15], v[96:99], v[80:83], v[0:15]
	ds_read_b64_tr_b16 v[80:81], v180 offset:44032
	ds_read_b64_tr_b16 v[82:83], v180 offset:44544
	ds_read_b64_tr_b16 v[92:93], v180 offset:48128
	ds_read_b64_tr_b16 v[94:95], v180 offset:48640
	s_waitcnt lgkmcnt(2)
	v_mfma_f32_32x32x16_bf16 v[16:31], v[80:83], v[88:91], v[16:31]
	s_waitcnt lgkmcnt(0)
	v_mfma_f32_32x32x16_bf16 v[0:15], v[92:95], v[88:91], v[0:15]
	v_add_f32_e32 v182, v84, v85
	v_add_f32_e32 v183, v86, v87
	v_add_f32_e32 v182, v182, v183
	v_add_f32_e32 v169, v169, v182
	s_waitcnt vmcnt(2)
	ds_write_b128 v177, v[114:117] offset:8192
	ds_write_b128 v178, v[142:145] offset:16384
	s_waitcnt lgkmcnt(0)
	s_barrier
	v_lshl_add_u64 v[172:173], v[172:173], 0, s[4:5]
	v_lshl_add_u64 v[174:175], v[174:175], 0, s[4:5]
	s_add_i32 s80, s80, 4
	s_cmp_lt_u32 s80, 60
	s_cbranch_scc1 .Lfa_g0_loop
	v_lshl_add_u64 v[146:147], v[174:175], 0, s[46:47]
	v_lshl_add_u64 v[148:149], v[172:173], 0, s[46:47]
	v_add_co_u32_e32 v80, vcc, 0x88d8000, v146
	s_nop 1
	v_addc_co_u32_e32 v81, vcc, 0, v147, vcc
	global_load_dwordx4 v[114:117], v[80:81], off offset:3072
	v_add_co_u32_e32 v80, vcc, 0x8890000, v148
	s_nop 1
	v_addc_co_u32_e32 v81, vcc, 0, v149, vcc
	global_load_dwordx4 v[142:145], v[80:81], off offset:3328
	ds_read_b128 v[80:83], v179 offset:8192
	ds_read_b128 v[182:185], v179 offset:8704
	ds_read_b128 v[186:189], v179 offset:10240
	ds_read_b128 v[190:193], v179 offset:10752
	ds_read_b128 v[200:203], v179 offset:12288
	ds_read_b128 v[204:207], v179 offset:12800
	ds_read_b128 v[208:211], v179 offset:14336
	ds_read_b128 v[212:215], v179 offset:14848
	v_exp_f32_e32 v64, v64
	v_exp_f32_e32 v65, v65
	v_exp_f32_e32 v66, v66
	v_exp_f32_e32 v67, v67
	v_exp_f32_e32 v48, v48
	v_exp_f32_e32 v49, v49
	v_exp_f32_e32 v50, v50
	v_exp_f32_e32 v51, v51
	v_add_f32_e32 v84, v50, v66
	v_add_f32_e32 v85, v51, v67
	v_add_f32_e32 v86, v48, v64
	v_add_f32_e32 v87, v49, v65
	v_cvt_pk_bf16_f32 v64, v64, v65
	v_cvt_pk_bf16_f32 v65, v66, v67
	v_cvt_pk_bf16_f32 v48, v48, v49
	v_cvt_pk_bf16_f32 v49, v50, v51
	s_waitcnt lgkmcnt(7)
	v_mfma_f32_32x32x16_bf16 v[96:111], v[80:83], v[118:121], v[32:47]
	v_exp_f32_e32 v50, v68
	v_exp_f32_e32 v51, v69
	v_exp_f32_e32 v68, v70
	v_exp_f32_e32 v69, v71
	v_add_f32_e32 v70, v50, v86
	v_add_f32_e32 v71, v51, v87
	v_add_f32_e32 v181, v68, v84
	v_add_f32_e32 v228, v69, v85
	v_cvt_pk_bf16_f32 v66, v50, v51
	v_cvt_pk_bf16_f32 v67, v68, v69
	s_waitcnt lgkmcnt(6)
	v_mfma_f32_32x32x16_bf16 v[80:95], v[182:185], v[118:121], v[32:47]
	v_exp_f32_e32 v50, v52
	v_exp_f32_e32 v51, v53
	v_exp_f32_e32 v52, v54
	v_exp_f32_e32 v53, v55
	v_add_f32_e32 v54, v50, v70
	v_add_f32_e32 v55, v51, v71
	v_add_f32_e32 v68, v52, v181
	v_add_f32_e32 v69, v53, v228
	v_cvt_pk_bf16_f32 v50, v50, v51
	v_cvt_pk_bf16_f32 v51, v52, v53
	s_waitcnt lgkmcnt(5)
	v_mfma_f32_32x32x16_bf16 v[96:111], v[186:189], v[122:125], v[96:111]
	v_exp_f32_e32 v52, v72
	v_exp_f32_e32 v53, v73
	v_exp_f32_e32 v70, v74
	v_exp_f32_e32 v71, v75
	v_add_f32_e32 v54, v52, v54
	v_add_f32_e32 v55, v53, v55
	v_add_f32_e32 v72, v70, v68
	v_add_f32_e32 v73, v71, v69
	v_cvt_pk_bf16_f32 v68, v52, v53
	v_cvt_pk_bf16_f32 v69, v70, v71
	s_waitcnt lgkmcnt(4)
	v_mfma_f32_32x32x16_bf16 v[80:95], v[190:193], v[122:125], v[80:95]
	v_exp_f32_e32 v52, v56
	v_exp_f32_e32 v53, v57
	v_exp_f32_e32 v57, v58
	v_exp_f32_e32 v58, v59
	v_add_f32_e32 v54, v52, v54
	v_add_f32_e32 v55, v53, v55
	v_add_f32_e32 v59, v57, v72
	v_add_f32_e32 v70, v58, v73
	v_cvt_pk_bf16_f32 v56, v52, v53
	v_cvt_pk_bf16_f32 v57, v57, v58
	s_waitcnt lgkmcnt(3)
	v_mfma_f32_32x32x16_bf16 v[96:111], v[200:203], v[126:129], v[96:111]
	v_exp_f32_e32 v52, v76
	v_exp_f32_e32 v53, v77
	v_exp_f32_e32 v58, v78
	v_exp_f32_e32 v71, v79
	v_add_f32_e32 v54, v52, v54
	v_add_f32_e32 v55, v53, v55
	v_add_f32_e32 v59, v58, v59
	v_add_f32_e32 v72, v71, v70
	v_cvt_pk_bf16_f32 v70, v52, v53
	v_cvt_pk_bf16_f32 v71, v58, v71
	s_waitcnt lgkmcnt(2)
	v_mfma_f32_32x32x16_bf16 v[80:95], v[204:207], v[126:129], v[80:95]
	v_exp_f32_e32 v58, v60
	v_exp_f32_e32 v60, v61
	v_exp_f32_e32 v61, v62
	v_exp_f32_e32 v62, v63
	v_add_f32_e32 v52, v58, v54
	v_add_f32_e32 v53, v60, v55
	v_add_f32_e32 v54, v61, v59
	v_add_f32_e32 v55, v62, v72
	v_cvt_pk_bf16_f32 v58, v58, v60
	v_cvt_pk_bf16_f32 v59, v61, v62
	s_waitcnt lgkmcnt(1)
	v_mfma_f32_32x32x16_bf16 v[96:111], v[208:211], v[130:133], v[96:111]
	ds_read_b64_tr_b16 v[60:61], v180 offset:16384
	ds_read_b64_tr_b16 v[62:63], v180 offset:16896
	ds_read_b64_tr_b16 v[72:73], v180 offset:20480
	ds_read_b64_tr_b16 v[74:75], v180 offset:20992
	s_waitcnt lgkmcnt(4)
	v_mfma_f32_32x32x16_bf16 v[80:95], v[212:215], v[130:133], v[80:95]
	s_waitcnt lgkmcnt(2)
	v_mfma_f32_32x32x16_bf16 v[16:31], v[60:63], v[64:67], v[16:31]
	s_waitcnt lgkmcnt(0)
	v_mfma_f32_32x32x16_bf16 v[0:15], v[72:75], v[64:67], v[0:15]
	ds_read_b64_tr_b16 v[60:61], v180 offset:17408
	ds_read_b64_tr_b16 v[62:63], v180 offset:17920
	ds_read_b64_tr_b16 v[64:65], v180 offset:21504
	ds_read_b64_tr_b16 v[66:67], v180 offset:22016
	s_waitcnt lgkmcnt(2)
	v_mfma_f32_32x32x16_bf16 v[16:31], v[60:63], v[68:71], v[16:31]
	s_waitcnt lgkmcnt(0)
	v_mfma_f32_32x32x16_bf16 v[0:15], v[64:67], v[68:71], v[0:15]
	ds_read_b64_tr_b16 v[60:61], v180 offset:18432
	ds_read_b64_tr_b16 v[62:63], v180 offset:18944
	ds_read_b64_tr_b16 v[64:65], v180 offset:22528
	ds_read_b64_tr_b16 v[66:67], v180 offset:23040
	s_waitcnt lgkmcnt(2)
	v_mfma_f32_32x32x16_bf16 v[16:31], v[60:63], v[48:51], v[16:31]
	s_waitcnt lgkmcnt(0)
	v_mfma_f32_32x32x16_bf16 v[0:15], v[64:67], v[48:51], v[0:15]
	ds_read_b64_tr_b16 v[48:49], v180 offset:19456
	ds_read_b64_tr_b16 v[50:51], v180 offset:19968
	ds_read_b64_tr_b16 v[60:61], v180 offset:23552
	ds_read_b64_tr_b16 v[62:63], v180 offset:24064
	s_waitcnt lgkmcnt(2)
	v_mfma_f32_32x32x16_bf16 v[16:31], v[48:51], v[56:59], v[16:31]
	s_waitcnt lgkmcnt(0)
	v_mfma_f32_32x32x16_bf16 v[0:15], v[60:63], v[56:59], v[0:15]
	v_add_f32_e32 v182, v52, v53
	v_add_f32_e32 v183, v54, v55
	v_add_f32_e32 v182, v182, v183
	v_add_f32_e32 v169, v169, v182
	s_waitcnt vmcnt(2)
	ds_write_b128 v177, v[134:137]
	ds_write_b128 v178, v[138:141] offset:24576
	s_waitcnt lgkmcnt(0)
	s_barrier
	v_add_co_u32_e32 v64, vcc, 0x88d8000, v148
	s_nop 1
	v_addc_co_u32_e32 v65, vcc, 0, v149, vcc
	global_load_dwordx4 v[138:141], v[64:65], off offset:3328
	ds_read_b128 v[182:185], v179
	ds_read_b128 v[186:189], v179 offset:512
	ds_read_b128 v[190:193], v179 offset:2048
	ds_read_b128 v[200:203], v179 offset:2560
	ds_read_b128 v[204:207], v179 offset:4096
	ds_read_b128 v[208:211], v179 offset:4608
	ds_read_b128 v[212:215], v179 offset:6144
	ds_read_b128 v[146:149], v179 offset:6656
	v_exp_f32_e32 v64, v96
	v_exp_f32_e32 v65, v97
	v_exp_f32_e32 v66, v98
	v_exp_f32_e32 v67, v99
	v_cvt_pk_bf16_f32 v96, v64, v65
	v_cvt_pk_bf16_f32 v97, v66, v67
	v_exp_f32_e32 v68, v80
	v_exp_f32_e32 v69, v81
	v_exp_f32_e32 v70, v82
	v_exp_f32_e32 v71, v83
	v_cvt_pk_bf16_f32 v80, v68, v69
	v_cvt_pk_bf16_f32 v81, v70, v71
	v_add_f32_e32 v68, v68, v64
	v_add_f32_e32 v69, v69, v65
	v_add_f32_e32 v82, v70, v66
	v_add_f32_e32 v83, v71, v67
	v_exp_f32_e32 v98, v100
	v_exp_f32_e32 v99, v101
	v_exp_f32_e32 v100, v102
	v_exp_f32_e32 v101, v103
	v_add_f32_e32 v102, v98, v68
	v_add_f32_e32 v103, v99, v69
	s_waitcnt lgkmcnt(7)
	v_mfma_f32_32x32x16_bf16 v[64:79], v[182:185], v[118:121], v[32:47]
	v_add_f32_e32 v82, v100, v82
	v_add_f32_e32 v83, v101, v83
	v_cvt_pk_bf16_f32 v98, v98, v99
	v_cvt_pk_bf16_f32 v99, v100, v101
	s_waitcnt lgkmcnt(6)
	v_mfma_f32_32x32x16_bf16 v[48:63], v[186:189], v[118:121], v[32:47]
	v_exp_f32_e32 v84, v84
	v_exp_f32_e32 v85, v85
	v_exp_f32_e32 v86, v86
	v_exp_f32_e32 v87, v87
	v_add_f32_e32 v100, v84, v102
	v_add_f32_e32 v101, v85, v103
	v_add_f32_e32 v102, v86, v82
	v_add_f32_e32 v103, v87, v83
	v_cvt_pk_bf16_f32 v82, v84, v85
	v_cvt_pk_bf16_f32 v83, v86, v87
	s_waitcnt lgkmcnt(5)
	v_mfma_f32_32x32x16_bf16 v[64:79], v[190:193], v[122:125], v[64:79]
	v_exp_f32_e32 v84, v104
	v_exp_f32_e32 v85, v105
	v_exp_f32_e32 v86, v106
	v_exp_f32_e32 v87, v107
	v_add_f32_e32 v104, v84, v100
	v_add_f32_e32 v105, v85, v101
	v_add_f32_e32 v102, v86, v102
	v_add_f32_e32 v103, v87, v103
	v_cvt_pk_bf16_f32 v100, v84, v85
	v_cvt_pk_bf16_f32 v101, v86, v87
	s_waitcnt lgkmcnt(4)
	v_mfma_f32_32x32x16_bf16 v[48:63], v[200:203], v[122:125], v[48:63]
	v_exp_f32_e32 v84, v88
	v_exp_f32_e32 v85, v89
	v_exp_f32_e32 v86, v90
	v_exp_f32_e32 v87, v91
	v_add_f32_e32 v90, v84, v104
	v_add_f32_e32 v91, v85, v105
	v_add_f32_e32 v102, v86, v102
	v_add_f32_e32 v103, v87, v103
	v_cvt_pk_bf16_f32 v88, v84, v85
	v_cvt_pk_bf16_f32 v89, v86, v87
	s_waitcnt lgkmcnt(3)
	v_mfma_f32_32x32x16_bf16 v[64:79], v[204:207], v[126:129], v[64:79]
	v_exp_f32_e32 v84, v108
	v_exp_f32_e32 v85, v109
	v_exp_f32_e32 v86, v110
	v_exp_f32_e32 v87, v111
	v_add_f32_e32 v90, v84, v90
	v_add_f32_e32 v91, v85, v91
	v_add_f32_e32 v104, v86, v102
	v_add_f32_e32 v105, v87, v103
	v_cvt_pk_bf16_f32 v102, v84, v85
	v_cvt_pk_bf16_f32 v103, v86, v87
	s_waitcnt lgkmcnt(2)
	v_mfma_f32_32x32x16_bf16 v[48:63], v[208:211], v[126:129], v[48:63]
	v_exp_f32_e32 v92, v92
	v_exp_f32_e32 v93, v93
	v_exp_f32_e32 v94, v94
	v_exp_f32_e32 v95, v95
	v_add_f32_e32 v84, v92, v90
	v_add_f32_e32 v85, v93, v91
	v_add_f32_e32 v86, v94, v104
	v_add_f32_e32 v87, v95, v105
	v_cvt_pk_bf16_f32 v90, v92, v93
	v_cvt_pk_bf16_f32 v91, v94, v95
	s_waitcnt lgkmcnt(1)
	v_mfma_f32_32x32x16_bf16 v[64:79], v[212:215], v[130:133], v[64:79]
	ds_read_b64_tr_b16 v[92:93], v180 offset:24576
	ds_read_b64_tr_b16 v[94:95], v180 offset:25088
	ds_read_b64_tr_b16 v[104:105], v180 offset:28672
	ds_read_b64_tr_b16 v[106:107], v180 offset:29184
	s_waitcnt lgkmcnt(4)
	v_mfma_f32_32x32x16_bf16 v[48:63], v[146:149], v[130:133], v[48:63]
	s_waitcnt lgkmcnt(2)
	v_mfma_f32_32x32x16_bf16 v[16:31], v[92:95], v[96:99], v[16:31]
	s_waitcnt lgkmcnt(0)
	v_mfma_f32_32x32x16_bf16 v[0:15], v[104:107], v[96:99], v[0:15]
	ds_read_b64_tr_b16 v[92:93], v180 offset:25600
	ds_read_b64_tr_b16 v[94:95], v180 offset:26112
	ds_read_b64_tr_b16 v[96:97], v180 offset:29696
	ds_read_b64_tr_b16 v[98:99], v180 offset:30208
	s_waitcnt lgkmcnt(2)
	v_mfma_f32_32x32x16_bf16 v[16:31], v[92:95], v[100:103], v[16:31]
	s_waitcnt lgkmcnt(0)
	v_mfma_f32_32x32x16_bf16 v[0:15], v[96:99], v[100:103], v[0:15]
	ds_read_b64_tr_b16 v[92:93], v180 offset:26624
	ds_read_b64_tr_b16 v[94:95], v180 offset:27136
	ds_read_b64_tr_b16 v[96:97], v180 offset:30720
	ds_read_b64_tr_b16 v[98:99], v180 offset:31232
	s_waitcnt lgkmcnt(2)
	v_mfma_f32_32x32x16_bf16 v[16:31], v[92:95], v[80:83], v[16:31]
	s_waitcnt lgkmcnt(0)
	v_mfma_f32_32x32x16_bf16 v[0:15], v[96:99], v[80:83], v[0:15]
	ds_read_b64_tr_b16 v[80:81], v180 offset:27648
	ds_read_b64_tr_b16 v[82:83], v180 offset:28160
	ds_read_b64_tr_b16 v[92:93], v180 offset:31744
	ds_read_b64_tr_b16 v[94:95], v180 offset:32256
	s_waitcnt lgkmcnt(2)
	v_mfma_f32_32x32x16_bf16 v[16:31], v[80:83], v[88:91], v[16:31]
	s_waitcnt lgkmcnt(0)
	v_mfma_f32_32x32x16_bf16 v[0:15], v[92:95], v[88:91], v[0:15]
	v_add_f32_e32 v182, v84, v85
	v_add_f32_e32 v183, v86, v87
	v_add_f32_e32 v182, v182, v183
	v_add_f32_e32 v169, v169, v182
	s_waitcnt vmcnt(1)
	ds_write_b128 v177, v[114:117] offset:8192
	ds_write_b128 v178, v[142:145] offset:32768
	s_waitcnt lgkmcnt(0)
	s_barrier
	v_lshl_add_u64 v[172:173], v[172:173], 0, s[4:5]
	v_lshl_add_u64 v[174:175], v[174:175], 0, s[4:5]
	v_lshl_add_u64 v[146:147], v[174:175], 0, s[46:47]
	v_lshl_add_u64 v[148:149], v[172:173], 0, s[46:47]
	ds_read_b128 v[80:83], v179 offset:8192
	ds_read_b128 v[182:185], v179 offset:8704
	ds_read_b128 v[186:189], v179 offset:10240
	ds_read_b128 v[190:193], v179 offset:10752
	ds_read_b128 v[200:203], v179 offset:12288
	ds_read_b128 v[204:207], v179 offset:12800
	ds_read_b128 v[208:211], v179 offset:14336
	ds_read_b128 v[212:215], v179 offset:14848
	v_exp_f32_e32 v64, v64
	v_exp_f32_e32 v65, v65
	v_exp_f32_e32 v66, v66
	v_exp_f32_e32 v67, v67
	v_exp_f32_e32 v48, v48
	v_exp_f32_e32 v49, v49
	v_exp_f32_e32 v50, v50
	v_exp_f32_e32 v51, v51
	v_add_f32_e32 v84, v50, v66
	v_add_f32_e32 v85, v51, v67
	v_add_f32_e32 v86, v48, v64
	v_add_f32_e32 v87, v49, v65
	v_cvt_pk_bf16_f32 v64, v64, v65
	v_cvt_pk_bf16_f32 v65, v66, v67
	v_cvt_pk_bf16_f32 v48, v48, v49
	v_cvt_pk_bf16_f32 v49, v50, v51
	s_waitcnt lgkmcnt(7)
	v_mfma_f32_32x32x16_bf16 v[96:111], v[80:83], v[118:121], v[32:47]
	v_exp_f32_e32 v50, v68
	v_exp_f32_e32 v51, v69
	v_exp_f32_e32 v68, v70
	v_exp_f32_e32 v69, v71
	v_add_f32_e32 v70, v50, v86
	v_add_f32_e32 v71, v51, v87
	v_add_f32_e32 v181, v68, v84
	v_add_f32_e32 v228, v69, v85
	v_cvt_pk_bf16_f32 v66, v50, v51
	v_cvt_pk_bf16_f32 v67, v68, v69
	s_waitcnt lgkmcnt(6)
	v_mfma_f32_32x32x16_bf16 v[80:95], v[182:185], v[118:121], v[32:47]
	v_exp_f32_e32 v50, v52
	v_exp_f32_e32 v51, v53
	v_exp_f32_e32 v52, v54
	v_exp_f32_e32 v53, v55
	v_add_f32_e32 v54, v50, v70
	v_add_f32_e32 v55, v51, v71
	v_add_f32_e32 v68, v52, v181
	v_add_f32_e32 v69, v53, v228
	v_cvt_pk_bf16_f32 v50, v50, v51
	v_cvt_pk_bf16_f32 v51, v52, v53
	s_waitcnt lgkmcnt(5)
	v_mfma_f32_32x32x16_bf16 v[96:111], v[186:189], v[122:125], v[96:111]
	v_exp_f32_e32 v52, v72
	v_exp_f32_e32 v53, v73
	v_exp_f32_e32 v70, v74
	v_exp_f32_e32 v71, v75
	v_add_f32_e32 v54, v52, v54
	v_add_f32_e32 v55, v53, v55
	v_add_f32_e32 v72, v70, v68
	v_add_f32_e32 v73, v71, v69
	v_cvt_pk_bf16_f32 v68, v52, v53
	v_cvt_pk_bf16_f32 v69, v70, v71
	s_waitcnt lgkmcnt(4)
	v_mfma_f32_32x32x16_bf16 v[80:95], v[190:193], v[122:125], v[80:95]
	v_exp_f32_e32 v52, v56
	v_exp_f32_e32 v53, v57
	v_exp_f32_e32 v57, v58
	v_exp_f32_e32 v58, v59
	v_add_f32_e32 v54, v52, v54
	v_add_f32_e32 v55, v53, v55
	v_add_f32_e32 v59, v57, v72
	v_add_f32_e32 v70, v58, v73
	v_cvt_pk_bf16_f32 v56, v52, v53
	v_cvt_pk_bf16_f32 v57, v57, v58
	s_waitcnt lgkmcnt(3)
	v_mfma_f32_32x32x16_bf16 v[96:111], v[200:203], v[126:129], v[96:111]
	v_exp_f32_e32 v52, v76
	v_exp_f32_e32 v53, v77
	v_exp_f32_e32 v58, v78
	v_exp_f32_e32 v71, v79
	v_add_f32_e32 v54, v52, v54
	v_add_f32_e32 v55, v53, v55
	v_add_f32_e32 v59, v58, v59
	v_add_f32_e32 v72, v71, v70
	v_cvt_pk_bf16_f32 v70, v52, v53
	v_cvt_pk_bf16_f32 v71, v58, v71
	s_waitcnt lgkmcnt(2)
	v_mfma_f32_32x32x16_bf16 v[80:95], v[204:207], v[126:129], v[80:95]
	v_exp_f32_e32 v58, v60
	v_exp_f32_e32 v60, v61
	v_exp_f32_e32 v61, v62
	v_exp_f32_e32 v62, v63
	v_add_f32_e32 v52, v58, v54
	v_add_f32_e32 v53, v60, v55
	v_add_f32_e32 v54, v61, v59
	v_add_f32_e32 v55, v62, v72
	v_cvt_pk_bf16_f32 v58, v58, v60
	v_cvt_pk_bf16_f32 v59, v61, v62
	s_waitcnt lgkmcnt(1)
	v_mfma_f32_32x32x16_bf16 v[96:111], v[208:211], v[130:133], v[96:111]
	ds_read_b64_tr_b16 v[60:61], v180 offset:32768
	ds_read_b64_tr_b16 v[62:63], v180 offset:33280
	ds_read_b64_tr_b16 v[72:73], v180 offset:36864
	ds_read_b64_tr_b16 v[74:75], v180 offset:37376
	s_waitcnt lgkmcnt(4)
	v_mfma_f32_32x32x16_bf16 v[80:95], v[212:215], v[130:133], v[80:95]
	s_waitcnt lgkmcnt(2)
	v_mfma_f32_32x32x16_bf16 v[16:31], v[60:63], v[64:67], v[16:31]
	s_waitcnt lgkmcnt(0)
	v_mfma_f32_32x32x16_bf16 v[0:15], v[72:75], v[64:67], v[0:15]
	ds_read_b64_tr_b16 v[60:61], v180 offset:33792
	ds_read_b64_tr_b16 v[62:63], v180 offset:34304
	ds_read_b64_tr_b16 v[64:65], v180 offset:37888
	ds_read_b64_tr_b16 v[66:67], v180 offset:38400
	s_waitcnt lgkmcnt(2)
	v_mfma_f32_32x32x16_bf16 v[16:31], v[60:63], v[68:71], v[16:31]
	s_waitcnt lgkmcnt(0)
	v_mfma_f32_32x32x16_bf16 v[0:15], v[64:67], v[68:71], v[0:15]
	ds_read_b64_tr_b16 v[60:61], v180 offset:34816
	ds_read_b64_tr_b16 v[62:63], v180 offset:35328
	ds_read_b64_tr_b16 v[64:65], v180 offset:38912
	ds_read_b64_tr_b16 v[66:67], v180 offset:39424
	s_waitcnt lgkmcnt(2)
	v_mfma_f32_32x32x16_bf16 v[16:31], v[60:63], v[48:51], v[16:31]
	s_waitcnt lgkmcnt(0)
	v_mfma_f32_32x32x16_bf16 v[0:15], v[64:67], v[48:51], v[0:15]
	ds_read_b64_tr_b16 v[48:49], v180 offset:35840
	ds_read_b64_tr_b16 v[50:51], v180 offset:36352
	ds_read_b64_tr_b16 v[60:61], v180 offset:39936
	ds_read_b64_tr_b16 v[62:63], v180 offset:40448
	s_waitcnt lgkmcnt(2)
	v_mfma_f32_32x32x16_bf16 v[16:31], v[48:51], v[56:59], v[16:31]
	s_waitcnt lgkmcnt(0)
	v_mfma_f32_32x32x16_bf16 v[0:15], v[60:63], v[56:59], v[0:15]
	v_add_f32_e32 v182, v52, v53
	v_add_f32_e32 v183, v54, v55
	v_add_f32_e32 v182, v182, v183
	v_add_f32_e32 v169, v169, v182
	s_waitcnt vmcnt(0)
	ds_write_b128 v178, v[138:141] offset:40960
	s_waitcnt lgkmcnt(0)
	s_barrier
	v_exp_f32_e32 v64, v96
	v_exp_f32_e32 v65, v97
	v_exp_f32_e32 v66, v98
	v_exp_f32_e32 v67, v99
	v_cvt_pk_bf16_f32 v96, v64, v65
	v_cvt_pk_bf16_f32 v97, v66, v67
	v_exp_f32_e32 v68, v80
	v_exp_f32_e32 v69, v81
	v_exp_f32_e32 v70, v82
	v_exp_f32_e32 v71, v83
	v_cvt_pk_bf16_f32 v80, v68, v69
	v_cvt_pk_bf16_f32 v81, v70, v71
	v_add_f32_e32 v68, v68, v64
	v_add_f32_e32 v69, v69, v65
	v_add_f32_e32 v82, v70, v66
	v_add_f32_e32 v83, v71, v67
	v_exp_f32_e32 v98, v100
	v_exp_f32_e32 v99, v101
	v_exp_f32_e32 v100, v102
	v_exp_f32_e32 v101, v103
	v_add_f32_e32 v102, v98, v68
	v_add_f32_e32 v103, v99, v69
	v_add_f32_e32 v82, v100, v82
	v_add_f32_e32 v83, v101, v83
	v_cvt_pk_bf16_f32 v98, v98, v99
	v_cvt_pk_bf16_f32 v99, v100, v101
	v_exp_f32_e32 v84, v84
	v_exp_f32_e32 v85, v85
	v_exp_f32_e32 v86, v86
	v_exp_f32_e32 v87, v87
	v_add_f32_e32 v100, v84, v102
	v_add_f32_e32 v101, v85, v103
	v_add_f32_e32 v102, v86, v82
	v_add_f32_e32 v103, v87, v83
	v_cvt_pk_bf16_f32 v82, v84, v85
	v_cvt_pk_bf16_f32 v83, v86, v87
	v_exp_f32_e32 v84, v104
	v_exp_f32_e32 v85, v105
	v_exp_f32_e32 v86, v106
	v_exp_f32_e32 v87, v107
	v_add_f32_e32 v104, v84, v100
	v_add_f32_e32 v105, v85, v101
	v_add_f32_e32 v102, v86, v102
	v_add_f32_e32 v103, v87, v103
	v_cvt_pk_bf16_f32 v100, v84, v85
	v_cvt_pk_bf16_f32 v101, v86, v87
	v_exp_f32_e32 v84, v88
	v_exp_f32_e32 v85, v89
	v_exp_f32_e32 v86, v90
	v_exp_f32_e32 v87, v91
	v_add_f32_e32 v90, v84, v104
	v_add_f32_e32 v91, v85, v105
	v_add_f32_e32 v102, v86, v102
	v_add_f32_e32 v103, v87, v103
	v_cvt_pk_bf16_f32 v88, v84, v85
	v_cvt_pk_bf16_f32 v89, v86, v87
	v_exp_f32_e32 v84, v108
	v_exp_f32_e32 v85, v109
	v_exp_f32_e32 v86, v110
	v_exp_f32_e32 v87, v111
	v_add_f32_e32 v90, v84, v90
	v_add_f32_e32 v91, v85, v91
	v_add_f32_e32 v104, v86, v102
	v_add_f32_e32 v105, v87, v103
	v_cvt_pk_bf16_f32 v102, v84, v85
	v_cvt_pk_bf16_f32 v103, v86, v87
	v_exp_f32_e32 v92, v92
	v_exp_f32_e32 v93, v93
	v_exp_f32_e32 v94, v94
	v_exp_f32_e32 v95, v95
	v_add_f32_e32 v84, v92, v90
	v_add_f32_e32 v85, v93, v91
	v_add_f32_e32 v86, v94, v104
	v_add_f32_e32 v87, v95, v105
	v_cvt_pk_bf16_f32 v90, v92, v93
	v_cvt_pk_bf16_f32 v91, v94, v95
	ds_read_b64_tr_b16 v[92:93], v180 offset:40960
	ds_read_b64_tr_b16 v[94:95], v180 offset:41472
	ds_read_b64_tr_b16 v[104:105], v180 offset:45056
	ds_read_b64_tr_b16 v[106:107], v180 offset:45568
	s_waitcnt lgkmcnt(2)
	v_mfma_f32_32x32x16_bf16 v[16:31], v[92:95], v[96:99], v[16:31]
	s_waitcnt lgkmcnt(0)
	v_mfma_f32_32x32x16_bf16 v[0:15], v[104:107], v[96:99], v[0:15]
	ds_read_b64_tr_b16 v[92:93], v180 offset:41984
	ds_read_b64_tr_b16 v[94:95], v180 offset:42496
	ds_read_b64_tr_b16 v[96:97], v180 offset:46080
	ds_read_b64_tr_b16 v[98:99], v180 offset:46592
	s_waitcnt lgkmcnt(2)
	v_mfma_f32_32x32x16_bf16 v[16:31], v[92:95], v[100:103], v[16:31]
	s_waitcnt lgkmcnt(0)
	v_mfma_f32_32x32x16_bf16 v[0:15], v[96:99], v[100:103], v[0:15]
	ds_read_b64_tr_b16 v[92:93], v180 offset:43008
	ds_read_b64_tr_b16 v[94:95], v180 offset:43520
	ds_read_b64_tr_b16 v[96:97], v180 offset:47104
	ds_read_b64_tr_b16 v[98:99], v180 offset:47616
	s_waitcnt lgkmcnt(2)
	v_mfma_f32_32x32x16_bf16 v[16:31], v[92:95], v[80:83], v[16:31]
	s_waitcnt lgkmcnt(0)
	v_mfma_f32_32x32x16_bf16 v[0:15], v[96:99], v[80:83], v[0:15]
	ds_read_b64_tr_b16 v[80:81], v180 offset:44032
	ds_read_b64_tr_b16 v[82:83], v180 offset:44544
	ds_read_b64_tr_b16 v[92:93], v180 offset:48128
	ds_read_b64_tr_b16 v[94:95], v180 offset:48640
	s_waitcnt lgkmcnt(2)
	v_mfma_f32_32x32x16_bf16 v[16:31], v[80:83], v[88:91], v[16:31]
	s_waitcnt lgkmcnt(0)
	v_mfma_f32_32x32x16_bf16 v[0:15], v[92:95], v[88:91], v[0:15]
	v_add_f32_e32 v182, v84, v85
	v_add_f32_e32 v183, v86, v87
	v_add_f32_e32 v182, v182, v183
	v_add_f32_e32 v169, v169, v182
	s_waitcnt lgkmcnt(0)
	s_barrier
	v_lshl_add_u64 v[172:173], v[172:173], 0, s[4:5]
	v_lshl_add_u64 v[174:175], v[174:175], 0, s[4:5]
	s_branch .LBB0_62
.Lfa_g1_entry:
	v_lshl_add_u64 v[146:147], v[174:175], 0, s[46:47]
	v_lshl_add_u64 v[148:149], v[172:173], 0, s[46:47]
	v_add_co_u32_e32 v80, vcc, 0x88d8000, v146
	s_nop 1
	v_addc_co_u32_e32 v81, vcc, 0, v147, vcc
	global_load_dwordx4 v[114:117], v[80:81], off offset:3072
	v_add_co_u32_e32 v80, vcc, 0x8890000, v148
	s_nop 1
	v_addc_co_u32_e32 v81, vcc, 0, v149, vcc
	global_load_dwordx4 v[142:145], v[80:81], off offset:3328
	ds_read_b128 v[80:83], v179 offset:8192
	ds_read_b128 v[182:185], v179 offset:8704
	ds_read_b128 v[186:189], v179 offset:10240
	ds_read_b128 v[190:193], v179 offset:10752
	ds_read_b128 v[200:203], v179 offset:12288
	ds_read_b128 v[204:207], v179 offset:12800
	ds_read_b128 v[208:211], v179 offset:14336
	ds_read_b128 v[212:215], v179 offset:14848
	v_exp_f32_e32 v64, v64
	v_exp_f32_e32 v65, v65
	v_exp_f32_e32 v66, v66
	v_exp_f32_e32 v67, v67
	v_exp_f32_e32 v48, v48
	v_exp_f32_e32 v49, v49
	v_exp_f32_e32 v50, v50
	v_exp_f32_e32 v51, v51
	v_add_f32_e32 v84, v50, v66
	v_add_f32_e32 v85, v51, v67
	v_add_f32_e32 v86, v48, v64
	v_add_f32_e32 v87, v49, v65
	v_cvt_pk_bf16_f32 v64, v64, v65
	v_cvt_pk_bf16_f32 v65, v66, v67
	v_cvt_pk_bf16_f32 v48, v48, v49
	v_cvt_pk_bf16_f32 v49, v50, v51
	s_waitcnt lgkmcnt(7)
	v_mfma_f32_32x32x16_bf16 v[96:111], v[80:83], v[118:121], v[32:47]
	v_exp_f32_e32 v50, v68
	v_exp_f32_e32 v51, v69
	v_exp_f32_e32 v68, v70
	v_exp_f32_e32 v69, v71
	v_add_f32_e32 v70, v50, v86
	v_add_f32_e32 v71, v51, v87
	v_add_f32_e32 v181, v68, v84
	v_add_f32_e32 v228, v69, v85
	v_cvt_pk_bf16_f32 v66, v50, v51
	v_cvt_pk_bf16_f32 v67, v68, v69
	s_waitcnt lgkmcnt(6)
	v_mfma_f32_32x32x16_bf16 v[80:95], v[182:185], v[118:121], v[32:47]
	v_exp_f32_e32 v50, v52
	v_exp_f32_e32 v51, v53
	v_exp_f32_e32 v52, v54
	v_exp_f32_e32 v53, v55
	v_add_f32_e32 v54, v50, v70
	v_add_f32_e32 v55, v51, v71
	v_add_f32_e32 v68, v52, v181
	v_add_f32_e32 v69, v53, v228
	v_cvt_pk_bf16_f32 v50, v50, v51
	v_cvt_pk_bf16_f32 v51, v52, v53
	s_waitcnt lgkmcnt(5)
	v_mfma_f32_32x32x16_bf16 v[96:111], v[186:189], v[122:125], v[96:111]
	v_exp_f32_e32 v52, v72
	v_exp_f32_e32 v53, v73
	v_exp_f32_e32 v70, v74
	v_exp_f32_e32 v71, v75
	v_add_f32_e32 v54, v52, v54
	v_add_f32_e32 v55, v53, v55
	v_add_f32_e32 v72, v70, v68
	v_add_f32_e32 v73, v71, v69
	v_cvt_pk_bf16_f32 v68, v52, v53
	v_cvt_pk_bf16_f32 v69, v70, v71
	s_waitcnt lgkmcnt(4)
	v_mfma_f32_32x32x16_bf16 v[80:95], v[190:193], v[122:125], v[80:95]
	v_exp_f32_e32 v52, v56
	v_exp_f32_e32 v53, v57
	v_exp_f32_e32 v57, v58
	v_exp_f32_e32 v58, v59
	v_add_f32_e32 v54, v52, v54
	v_add_f32_e32 v55, v53, v55
	v_add_f32_e32 v59, v57, v72
	v_add_f32_e32 v70, v58, v73
	v_cvt_pk_bf16_f32 v56, v52, v53
	v_cvt_pk_bf16_f32 v57, v57, v58
	s_waitcnt lgkmcnt(3)
	v_mfma_f32_32x32x16_bf16 v[96:111], v[200:203], v[126:129], v[96:111]
	v_exp_f32_e32 v52, v76
	v_exp_f32_e32 v53, v77
	v_exp_f32_e32 v58, v78
	v_exp_f32_e32 v71, v79
	v_add_f32_e32 v54, v52, v54
	v_add_f32_e32 v55, v53, v55
	v_add_f32_e32 v59, v58, v59
	v_add_f32_e32 v72, v71, v70
	v_cvt_pk_bf16_f32 v70, v52, v53
	v_cvt_pk_bf16_f32 v71, v58, v71
	s_waitcnt lgkmcnt(2)
	v_mfma_f32_32x32x16_bf16 v[80:95], v[204:207], v[126:129], v[80:95]
	v_exp_f32_e32 v58, v60
	v_exp_f32_e32 v60, v61
	v_exp_f32_e32 v61, v62
	v_exp_f32_e32 v62, v63
	v_add_f32_e32 v52, v58, v54
	v_add_f32_e32 v53, v60, v55
	v_add_f32_e32 v54, v61, v59
	v_add_f32_e32 v55, v62, v72
	v_cvt_pk_bf16_f32 v58, v58, v60
	v_cvt_pk_bf16_f32 v59, v61, v62
	s_waitcnt lgkmcnt(1)
	v_mfma_f32_32x32x16_bf16 v[96:111], v[208:211], v[130:133], v[96:111]
	s_waitcnt lgkmcnt(0)
	v_mfma_f32_32x32x16_bf16 v[80:95], v[212:215], v[130:133], v[80:95]
	v_add_f32_e32 v182, v52, v53
	v_add_f32_e32 v183, v54, v55
	v_add_f32_e32 v182, v182, v183
	v_add_f32_e32 v169, v169, v182
	s_waitcnt vmcnt(2)
	ds_write_b128 v177, v[134:137]
	ds_write_b128 v178, v[138:141] offset:24576
	s_waitcnt lgkmcnt(0)
	s_barrier
	ds_read_b64_tr_b16 v[60:61], v180 offset:16384
	ds_read_b64_tr_b16 v[62:63], v180 offset:16896
	ds_read_b64_tr_b16 v[72:73], v180 offset:20480
	ds_read_b64_tr_b16 v[74:75], v180 offset:20992
	s_waitcnt lgkmcnt(2)
	v_mfma_f32_32x32x16_bf16 v[16:31], v[60:63], v[64:67], v[16:31]
	s_waitcnt lgkmcnt(0)
	v_mfma_f32_32x32x16_bf16 v[0:15], v[72:75], v[64:67], v[0:15]
	ds_read_b64_tr_b16 v[60:61], v180 offset:17408
	ds_read_b64_tr_b16 v[62:63], v180 offset:17920
	ds_read_b64_tr_b16 v[64:65], v180 offset:21504
	ds_read_b64_tr_b16 v[66:67], v180 offset:22016
	s_waitcnt lgkmcnt(2)
	v_mfma_f32_32x32x16_bf16 v[16:31], v[60:63], v[68:71], v[16:31]
	s_waitcnt lgkmcnt(0)
	v_mfma_f32_32x32x16_bf16 v[0:15], v[64:67], v[68:71], v[0:15]
	ds_read_b64_tr_b16 v[60:61], v180 offset:18432
	ds_read_b64_tr_b16 v[62:63], v180 offset:18944
	ds_read_b64_tr_b16 v[64:65], v180 offset:22528
	ds_read_b64_tr_b16 v[66:67], v180 offset:23040
	s_waitcnt lgkmcnt(2)
	v_mfma_f32_32x32x16_bf16 v[16:31], v[60:63], v[48:51], v[16:31]
	s_waitcnt lgkmcnt(0)
	v_mfma_f32_32x32x16_bf16 v[0:15], v[64:67], v[48:51], v[0:15]
	ds_read_b64_tr_b16 v[48:49], v180 offset:19456
	ds_read_b64_tr_b16 v[50:51], v180 offset:19968
	ds_read_b64_tr_b16 v[60:61], v180 offset:23552
	ds_read_b64_tr_b16 v[62:63], v180 offset:24064
	s_waitcnt lgkmcnt(2)
	v_mfma_f32_32x32x16_bf16 v[16:31], v[48:51], v[56:59], v[16:31]
	s_waitcnt lgkmcnt(0)
	v_mfma_f32_32x32x16_bf16 v[0:15], v[60:63], v[56:59], v[0:15]
	v_add_co_u32_e32 v64, vcc, 0x8920000, v146
	s_nop 1
	v_addc_co_u32_e32 v65, vcc, 0, v147, vcc
	global_load_dwordx4 v[134:137], v[64:65], off offset:3072
	v_add_co_u32_e32 v64, vcc, 0x88d8000, v148
	s_nop 1
	v_addc_co_u32_e32 v65, vcc, 0, v149, vcc
	global_load_dwordx4 v[138:141], v[64:65], off offset:3328
	ds_read_b128 v[182:185], v179
	ds_read_b128 v[186:189], v179 offset:512
	ds_read_b128 v[190:193], v179 offset:2048
	ds_read_b128 v[200:203], v179 offset:2560
	ds_read_b128 v[204:207], v179 offset:4096
	ds_read_b128 v[208:211], v179 offset:4608
	ds_read_b128 v[212:215], v179 offset:6144
	ds_read_b128 v[146:149], v179 offset:6656
	v_exp_f32_e32 v64, v96
	v_exp_f32_e32 v65, v97
	v_exp_f32_e32 v66, v98
	v_exp_f32_e32 v67, v99
	v_cvt_pk_bf16_f32 v96, v64, v65
	v_cvt_pk_bf16_f32 v97, v66, v67
	v_exp_f32_e32 v68, v80
	v_exp_f32_e32 v69, v81
	v_exp_f32_e32 v70, v82
	v_exp_f32_e32 v71, v83
	v_cvt_pk_bf16_f32 v80, v68, v69
	v_cvt_pk_bf16_f32 v81, v70, v71
	v_add_f32_e32 v68, v68, v64
	v_add_f32_e32 v69, v69, v65
	v_add_f32_e32 v82, v70, v66
	v_add_f32_e32 v83, v71, v67
	v_exp_f32_e32 v98, v100
	v_exp_f32_e32 v99, v101
	v_exp_f32_e32 v100, v102
	v_exp_f32_e32 v101, v103
	v_add_f32_e32 v102, v98, v68
	v_add_f32_e32 v103, v99, v69
	s_waitcnt lgkmcnt(7)
	v_mfma_f32_32x32x16_bf16 v[64:79], v[182:185], v[118:121], v[32:47]
	v_add_f32_e32 v82, v100, v82
	v_add_f32_e32 v83, v101, v83
	v_cvt_pk_bf16_f32 v98, v98, v99
	v_cvt_pk_bf16_f32 v99, v100, v101
	s_waitcnt lgkmcnt(6)
	v_mfma_f32_32x32x16_bf16 v[48:63], v[186:189], v[118:121], v[32:47]
	v_exp_f32_e32 v84, v84
	v_exp_f32_e32 v85, v85
	v_exp_f32_e32 v86, v86
	v_exp_f32_e32 v87, v87
	v_add_f32_e32 v100, v84, v102
	v_add_f32_e32 v101, v85, v103
	v_add_f32_e32 v102, v86, v82
	v_add_f32_e32 v103, v87, v83
	v_cvt_pk_bf16_f32 v82, v84, v85
	v_cvt_pk_bf16_f32 v83, v86, v87
	s_waitcnt lgkmcnt(5)
	v_mfma_f32_32x32x16_bf16 v[64:79], v[190:193], v[122:125], v[64:79]
	v_exp_f32_e32 v84, v104
	v_exp_f32_e32 v85, v105
	v_exp_f32_e32 v86, v106
	v_exp_f32_e32 v87, v107
	v_add_f32_e32 v104, v84, v100
	v_add_f32_e32 v105, v85, v101
	v_add_f32_e32 v102, v86, v102
	v_add_f32_e32 v103, v87, v103
	v_cvt_pk_bf16_f32 v100, v84, v85
	v_cvt_pk_bf16_f32 v101, v86, v87
	s_waitcnt lgkmcnt(4)
	v_mfma_f32_32x32x16_bf16 v[48:63], v[200:203], v[122:125], v[48:63]
	v_exp_f32_e32 v84, v88
	v_exp_f32_e32 v85, v89
	v_exp_f32_e32 v86, v90
	v_exp_f32_e32 v87, v91
	v_add_f32_e32 v90, v84, v104
	v_add_f32_e32 v91, v85, v105
	v_add_f32_e32 v102, v86, v102
	v_add_f32_e32 v103, v87, v103
	v_cvt_pk_bf16_f32 v88, v84, v85
	v_cvt_pk_bf16_f32 v89, v86, v87
	s_waitcnt lgkmcnt(3)
	v_mfma_f32_32x32x16_bf16 v[64:79], v[204:207], v[126:129], v[64:79]
	v_exp_f32_e32 v84, v108
	v_exp_f32_e32 v85, v109
	v_exp_f32_e32 v86, v110
	v_exp_f32_e32 v87, v111
	v_add_f32_e32 v90, v84, v90
	v_add_f32_e32 v91, v85, v91
	v_add_f32_e32 v104, v86, v102
	v_add_f32_e32 v105, v87, v103
	v_cvt_pk_bf16_f32 v102, v84, v85
	v_cvt_pk_bf16_f32 v103, v86, v87
	s_waitcnt lgkmcnt(2)
	v_mfma_f32_32x32x16_bf16 v[48:63], v[208:211], v[126:129], v[48:63]
	v_exp_f32_e32 v92, v92
	v_exp_f32_e32 v93, v93
	v_exp_f32_e32 v94, v94
	v_exp_f32_e32 v95, v95
	v_add_f32_e32 v84, v92, v90
	v_add_f32_e32 v85, v93, v91
	v_add_f32_e32 v86, v94, v104
	v_add_f32_e32 v87, v95, v105
	v_cvt_pk_bf16_f32 v90, v92, v93
	v_cvt_pk_bf16_f32 v91, v94, v95
	s_waitcnt lgkmcnt(1)
	v_mfma_f32_32x32x16_bf16 v[64:79], v[212:215], v[130:133], v[64:79]
	s_waitcnt lgkmcnt(0)
	v_mfma_f32_32x32x16_bf16 v[48:63], v[146:149], v[130:133], v[48:63]
	v_add_f32_e32 v182, v84, v85
	v_add_f32_e32 v183, v86, v87
	v_add_f32_e32 v182, v182, v183
	v_add_f32_e32 v169, v169, v182
	s_waitcnt vmcnt(2)
	ds_write_b128 v177, v[114:117] offset:8192
	ds_write_b128 v178, v[142:145] offset:32768
	s_waitcnt lgkmcnt(0)
	s_barrier
	v_lshl_add_u64 v[172:173], v[172:173], 0, s[4:5]
	v_lshl_add_u64 v[174:175], v[174:175], 0, s[4:5]
	ds_read_b64_tr_b16 v[92:93], v180 offset:24576
	ds_read_b64_tr_b16 v[94:95], v180 offset:25088
	ds_read_b64_tr_b16 v[104:105], v180 offset:28672
	ds_read_b64_tr_b16 v[106:107], v180 offset:29184
	s_waitcnt lgkmcnt(2)
	v_mfma_f32_32x32x16_bf16 v[16:31], v[92:95], v[96:99], v[16:31]
	s_waitcnt lgkmcnt(0)
	v_mfma_f32_32x32x16_bf16 v[0:15], v[104:107], v[96:99], v[0:15]
	ds_read_b64_tr_b16 v[92:93], v180 offset:25600
	ds_read_b64_tr_b16 v[94:95], v180 offset:26112
	ds_read_b64_tr_b16 v[96:97], v180 offset:29696
	ds_read_b64_tr_b16 v[98:99], v180 offset:30208
	s_waitcnt lgkmcnt(2)
	v_mfma_f32_32x32x16_bf16 v[16:31], v[92:95], v[100:103], v[16:31]
	s_waitcnt lgkmcnt(0)
	v_mfma_f32_32x32x16_bf16 v[0:15], v[96:99], v[100:103], v[0:15]
	ds_read_b64_tr_b16 v[92:93], v180 offset:26624
	ds_read_b64_tr_b16 v[94:95], v180 offset:27136
	ds_read_b64_tr_b16 v[96:97], v180 offset:30720
	ds_read_b64_tr_b16 v[98:99], v180 offset:31232
	s_waitcnt lgkmcnt(2)
	v_mfma_f32_32x32x16_bf16 v[16:31], v[92:95], v[80:83], v[16:31]
	s_waitcnt lgkmcnt(0)
	v_mfma_f32_32x32x16_bf16 v[0:15], v[96:99], v[80:83], v[0:15]
	ds_read_b64_tr_b16 v[80:81], v180 offset:27648
	ds_read_b64_tr_b16 v[82:83], v180 offset:28160
	ds_read_b64_tr_b16 v[92:93], v180 offset:31744
	ds_read_b64_tr_b16 v[94:95], v180 offset:32256
	s_waitcnt lgkmcnt(2)
	v_mfma_f32_32x32x16_bf16 v[16:31], v[80:83], v[88:91], v[16:31]
	s_waitcnt lgkmcnt(0)
	v_mfma_f32_32x32x16_bf16 v[0:15], v[92:95], v[88:91], v[0:15]
	v_lshl_add_u64 v[146:147], v[174:175], 0, s[46:47]
	v_lshl_add_u64 v[148:149], v[172:173], 0, s[46:47]
	v_add_co_u32_e32 v80, vcc, 0x88d8000, v146
	s_nop 1
	v_addc_co_u32_e32 v81, vcc, 0, v147, vcc
	global_load_dwordx4 v[114:117], v[80:81], off offset:3072
	v_add_co_u32_e32 v80, vcc, 0x8890000, v148
	s_nop 1
	v_addc_co_u32_e32 v81, vcc, 0, v149, vcc
	global_load_dwordx4 v[142:145], v[80:81], off offset:3328
	ds_read_b128 v[80:83], v179 offset:8192
	ds_read_b128 v[182:185], v179 offset:8704
	ds_read_b128 v[186:189], v179 offset:10240
	ds_read_b128 v[190:193], v179 offset:10752
	ds_read_b128 v[200:203], v179 offset:12288
	ds_read_b128 v[204:207], v179 offset:12800
	ds_read_b128 v[208:211], v179 offset:14336
	ds_read_b128 v[212:215], v179 offset:14848
	v_exp_f32_e32 v64, v64
	v_exp_f32_e32 v65, v65
	v_exp_f32_e32 v66, v66
	v_exp_f32_e32 v67, v67
	v_exp_f32_e32 v48, v48
	v_exp_f32_e32 v49, v49
	v_exp_f32_e32 v50, v50
	v_exp_f32_e32 v51, v51
	v_add_f32_e32 v84, v50, v66
	v_add_f32_e32 v85, v51, v67
	v_add_f32_e32 v86, v48, v64
	v_add_f32_e32 v87, v49, v65
	v_cvt_pk_bf16_f32 v64, v64, v65
	v_cvt_pk_bf16_f32 v65, v66, v67
	v_cvt_pk_bf16_f32 v48, v48, v49
	v_cvt_pk_bf16_f32 v49, v50, v51
	s_waitcnt lgkmcnt(7)
	v_mfma_f32_32x32x16_bf16 v[96:111], v[80:83], v[118:121], v[32:47]
	v_exp_f32_e32 v50, v68
	v_exp_f32_e32 v51, v69
	v_exp_f32_e32 v68, v70
	v_exp_f32_e32 v69, v71
	v_add_f32_e32 v70, v50, v86
	v_add_f32_e32 v71, v51, v87
	v_add_f32_e32 v181, v68, v84
	v_add_f32_e32 v228, v69, v85
	v_cvt_pk_bf16_f32 v66, v50, v51
	v_cvt_pk_bf16_f32 v67, v68, v69
	s_waitcnt lgkmcnt(6)
	v_mfma_f32_32x32x16_bf16 v[80:95], v[182:185], v[118:121], v[32:47]
	v_exp_f32_e32 v50, v52
	v_exp_f32_e32 v51, v53
	v_exp_f32_e32 v52, v54
	v_exp_f32_e32 v53, v55
	v_add_f32_e32 v54, v50, v70
	v_add_f32_e32 v55, v51, v71
	v_add_f32_e32 v68, v52, v181
	v_add_f32_e32 v69, v53, v228
	v_cvt_pk_bf16_f32 v50, v50, v51
	v_cvt_pk_bf16_f32 v51, v52, v53
	s_waitcnt lgkmcnt(5)
	v_mfma_f32_32x32x16_bf16 v[96:111], v[186:189], v[122:125], v[96:111]
	v_exp_f32_e32 v52, v72
	v_exp_f32_e32 v53, v73
	v_exp_f32_e32 v70, v74
	v_exp_f32_e32 v71, v75
	v_add_f32_e32 v54, v52, v54
	v_add_f32_e32 v55, v53, v55
	v_add_f32_e32 v72, v70, v68
	v_add_f32_e32 v73, v71, v69
	v_cvt_pk_bf16_f32 v68, v52, v53
	v_cvt_pk_bf16_f32 v69, v70, v71
	s_waitcnt lgkmcnt(4)
	v_mfma_f32_32x32x16_bf16 v[80:95], v[190:193], v[122:125], v[80:95]
	v_exp_f32_e32 v52, v56
	v_exp_f32_e32 v53, v57
	v_exp_f32_e32 v57, v58
	v_exp_f32_e32 v58, v59
	v_add_f32_e32 v54, v52, v54
	v_add_f32_e32 v55, v53, v55
	v_add_f32_e32 v59, v57, v72
	v_add_f32_e32 v70, v58, v73
	v_cvt_pk_bf16_f32 v56, v52, v53
	v_cvt_pk_bf16_f32 v57, v57, v58
	s_waitcnt lgkmcnt(3)
	v_mfma_f32_32x32x16_bf16 v[96:111], v[200:203], v[126:129], v[96:111]
	v_exp_f32_e32 v52, v76
	v_exp_f32_e32 v53, v77
	v_exp_f32_e32 v58, v78
	v_exp_f32_e32 v71, v79
	v_add_f32_e32 v54, v52, v54
	v_add_f32_e32 v55, v53, v55
	v_add_f32_e32 v59, v58, v59
	v_add_f32_e32 v72, v71, v70
	v_cvt_pk_bf16_f32 v70, v52, v53
	v_cvt_pk_bf16_f32 v71, v58, v71
	s_waitcnt lgkmcnt(2)
	v_mfma_f32_32x32x16_bf16 v[80:95], v[204:207], v[126:129], v[80:95]
	v_exp_f32_e32 v58, v60
	v_exp_f32_e32 v60, v61
	v_exp_f32_e32 v61, v62
	v_exp_f32_e32 v62, v63
	v_add_f32_e32 v52, v58, v54
	v_add_f32_e32 v53, v60, v55
	v_add_f32_e32 v54, v61, v59
	v_add_f32_e32 v55, v62, v72
	v_cvt_pk_bf16_f32 v58, v58, v60
	v_cvt_pk_bf16_f32 v59, v61, v62
	s_waitcnt lgkmcnt(1)
	v_mfma_f32_32x32x16_bf16 v[96:111], v[208:211], v[130:133], v[96:111]
	s_waitcnt lgkmcnt(0)
	v_mfma_f32_32x32x16_bf16 v[80:95], v[212:215], v[130:133], v[80:95]
	v_add_f32_e32 v182, v52, v53
	v_add_f32_e32 v183, v54, v55
	v_add_f32_e32 v182, v182, v183
	v_add_f32_e32 v169, v169, v182
	s_waitcnt vmcnt(2)
	ds_write_b128 v177, v[134:137]
	ds_write_b128 v178, v[138:141] offset:40960
	s_waitcnt lgkmcnt(0)
	s_barrier
	ds_read_b64_tr_b16 v[60:61], v180 offset:32768
	ds_read_b64_tr_b16 v[62:63], v180 offset:33280
	ds_read_b64_tr_b16 v[72:73], v180 offset:36864
	ds_read_b64_tr_b16 v[74:75], v180 offset:37376
	s_waitcnt lgkmcnt(2)
	v_mfma_f32_32x32x16_bf16 v[16:31], v[60:63], v[64:67], v[16:31]
	s_waitcnt lgkmcnt(0)
	v_mfma_f32_32x32x16_bf16 v[0:15], v[72:75], v[64:67], v[0:15]
	ds_read_b64_tr_b16 v[60:61], v180 offset:33792
	ds_read_b64_tr_b16 v[62:63], v180 offset:34304
	ds_read_b64_tr_b16 v[64:65], v180 offset:37888
	ds_read_b64_tr_b16 v[66:67], v180 offset:38400
	s_waitcnt lgkmcnt(2)
	v_mfma_f32_32x32x16_bf16 v[16:31], v[60:63], v[68:71], v[16:31]
	s_waitcnt lgkmcnt(0)
	v_mfma_f32_32x32x16_bf16 v[0:15], v[64:67], v[68:71], v[0:15]
	ds_read_b64_tr_b16 v[60:61], v180 offset:34816
	ds_read_b64_tr_b16 v[62:63], v180 offset:35328
	ds_read_b64_tr_b16 v[64:65], v180 offset:38912
	ds_read_b64_tr_b16 v[66:67], v180 offset:39424
	s_waitcnt lgkmcnt(2)
	v_mfma_f32_32x32x16_bf16 v[16:31], v[60:63], v[48:51], v[16:31]
	s_waitcnt lgkmcnt(0)
	v_mfma_f32_32x32x16_bf16 v[0:15], v[64:67], v[48:51], v[0:15]
	ds_read_b64_tr_b16 v[48:49], v180 offset:35840
	ds_read_b64_tr_b16 v[50:51], v180 offset:36352
	ds_read_b64_tr_b16 v[60:61], v180 offset:39936
	ds_read_b64_tr_b16 v[62:63], v180 offset:40448
	s_waitcnt lgkmcnt(2)
	v_mfma_f32_32x32x16_bf16 v[16:31], v[48:51], v[56:59], v[16:31]
	s_waitcnt lgkmcnt(0)
	v_mfma_f32_32x32x16_bf16 v[0:15], v[60:63], v[56:59], v[0:15]
	v_add_co_u32_e32 v64, vcc, 0x8920000, v146
	s_nop 1
	v_addc_co_u32_e32 v65, vcc, 0, v147, vcc
	global_load_dwordx4 v[134:137], v[64:65], off offset:3072
	v_add_co_u32_e32 v64, vcc, 0x88d8000, v148
	s_nop 1
	v_addc_co_u32_e32 v65, vcc, 0, v149, vcc
	global_load_dwordx4 v[138:141], v[64:65], off offset:3328
	ds_read_b128 v[182:185], v179
	ds_read_b128 v[186:189], v179 offset:512
	ds_read_b128 v[190:193], v179 offset:2048
	ds_read_b128 v[200:203], v179 offset:2560
	ds_read_b128 v[204:207], v179 offset:4096
	ds_read_b128 v[208:211], v179 offset:4608
	ds_read_b128 v[212:215], v179 offset:6144
	ds_read_b128 v[146:149], v179 offset:6656
	v_exp_f32_e32 v64, v96
	v_exp_f32_e32 v65, v97
	v_exp_f32_e32 v66, v98
	v_exp_f32_e32 v67, v99
	v_cvt_pk_bf16_f32 v96, v64, v65
	v_cvt_pk_bf16_f32 v97, v66, v67
	v_exp_f32_e32 v68, v80
	v_exp_f32_e32 v69, v81
	v_exp_f32_e32 v70, v82
	v_exp_f32_e32 v71, v83
	v_cvt_pk_bf16_f32 v80, v68, v69
	v_cvt_pk_bf16_f32 v81, v70, v71
	v_add_f32_e32 v68, v68, v64
	v_add_f32_e32 v69, v69, v65
	v_add_f32_e32 v82, v70, v66
	v_add_f32_e32 v83, v71, v67
	v_exp_f32_e32 v98, v100
	v_exp_f32_e32 v99, v101
	v_exp_f32_e32 v100, v102
	v_exp_f32_e32 v101, v103
	v_add_f32_e32 v102, v98, v68
	v_add_f32_e32 v103, v99, v69
	s_waitcnt lgkmcnt(7)
	v_mfma_f32_32x32x16_bf16 v[64:79], v[182:185], v[118:121], v[32:47]
	v_add_f32_e32 v82, v100, v82
	v_add_f32_e32 v83, v101, v83
	v_cvt_pk_bf16_f32 v98, v98, v99
	v_cvt_pk_bf16_f32 v99, v100, v101
	s_waitcnt lgkmcnt(6)
	v_mfma_f32_32x32x16_bf16 v[48:63], v[186:189], v[118:121], v[32:47]
	v_exp_f32_e32 v84, v84
	v_exp_f32_e32 v85, v85
	v_exp_f32_e32 v86, v86
	v_exp_f32_e32 v87, v87
	v_add_f32_e32 v100, v84, v102
	v_add_f32_e32 v101, v85, v103
	v_add_f32_e32 v102, v86, v82
	v_add_f32_e32 v103, v87, v83
	v_cvt_pk_bf16_f32 v82, v84, v85
	v_cvt_pk_bf16_f32 v83, v86, v87
	s_waitcnt lgkmcnt(5)
	v_mfma_f32_32x32x16_bf16 v[64:79], v[190:193], v[122:125], v[64:79]
	v_exp_f32_e32 v84, v104
	v_exp_f32_e32 v85, v105
	v_exp_f32_e32 v86, v106
	v_exp_f32_e32 v87, v107
	v_add_f32_e32 v104, v84, v100
	v_add_f32_e32 v105, v85, v101
	v_add_f32_e32 v102, v86, v102
	v_add_f32_e32 v103, v87, v103
	v_cvt_pk_bf16_f32 v100, v84, v85
	v_cvt_pk_bf16_f32 v101, v86, v87
	s_waitcnt lgkmcnt(4)
	v_mfma_f32_32x32x16_bf16 v[48:63], v[200:203], v[122:125], v[48:63]
	v_exp_f32_e32 v84, v88
	v_exp_f32_e32 v85, v89
	v_exp_f32_e32 v86, v90
	v_exp_f32_e32 v87, v91
	v_add_f32_e32 v90, v84, v104
	v_add_f32_e32 v91, v85, v105
	v_add_f32_e32 v102, v86, v102
	v_add_f32_e32 v103, v87, v103
	v_cvt_pk_bf16_f32 v88, v84, v85
	v_cvt_pk_bf16_f32 v89, v86, v87
	s_waitcnt lgkmcnt(3)
	v_mfma_f32_32x32x16_bf16 v[64:79], v[204:207], v[126:129], v[64:79]
	v_exp_f32_e32 v84, v108
	v_exp_f32_e32 v85, v109
	v_exp_f32_e32 v86, v110
	v_exp_f32_e32 v87, v111
	v_add_f32_e32 v90, v84, v90
	v_add_f32_e32 v91, v85, v91
	v_add_f32_e32 v104, v86, v102
	v_add_f32_e32 v105, v87, v103
	v_cvt_pk_bf16_f32 v102, v84, v85
	v_cvt_pk_bf16_f32 v103, v86, v87
	s_waitcnt lgkmcnt(2)
	v_mfma_f32_32x32x16_bf16 v[48:63], v[208:211], v[126:129], v[48:63]
	v_exp_f32_e32 v92, v92
	v_exp_f32_e32 v93, v93
	v_exp_f32_e32 v94, v94
	v_exp_f32_e32 v95, v95
	v_add_f32_e32 v84, v92, v90
	v_add_f32_e32 v85, v93, v91
	v_add_f32_e32 v86, v94, v104
	v_add_f32_e32 v87, v95, v105
	v_cvt_pk_bf16_f32 v90, v92, v93
	v_cvt_pk_bf16_f32 v91, v94, v95
	s_waitcnt lgkmcnt(1)
	v_mfma_f32_32x32x16_bf16 v[64:79], v[212:215], v[130:133], v[64:79]
	s_waitcnt lgkmcnt(0)
	v_mfma_f32_32x32x16_bf16 v[48:63], v[146:149], v[130:133], v[48:63]
	v_add_f32_e32 v182, v84, v85
	v_add_f32_e32 v183, v86, v87
	v_add_f32_e32 v182, v182, v183
	v_add_f32_e32 v169, v169, v182
	s_waitcnt vmcnt(2)
	ds_write_b128 v177, v[114:117] offset:8192
	ds_write_b128 v178, v[142:145] offset:16384
	s_waitcnt lgkmcnt(0)
	s_barrier
	v_lshl_add_u64 v[172:173], v[172:173], 0, s[4:5]
	v_lshl_add_u64 v[174:175], v[174:175], 0, s[4:5]
	s_mov_b32 s80, 4
.Lfa_g1_loop:
	ds_read_b64_tr_b16 v[92:93], v180 offset:40960
	ds_read_b64_tr_b16 v[94:95], v180 offset:41472
	ds_read_b64_tr_b16 v[104:105], v180 offset:45056
	ds_read_b64_tr_b16 v[106:107], v180 offset:45568
	s_waitcnt lgkmcnt(2)
	v_mfma_f32_32x32x16_bf16 v[16:31], v[92:95], v[96:99], v[16:31]
	s_waitcnt lgkmcnt(0)
	v_mfma_f32_32x32x16_bf16 v[0:15], v[104:107], v[96:99], v[0:15]
	ds_read_b64_tr_b16 v[92:93], v180 offset:41984
	ds_read_b64_tr_b16 v[94:95], v180 offset:42496
	ds_read_b64_tr_b16 v[96:97], v180 offset:46080
	ds_read_b64_tr_b16 v[98:99], v180 offset:46592
	s_waitcnt lgkmcnt(2)
	v_mfma_f32_32x32x16_bf16 v[16:31], v[92:95], v[100:103], v[16:31]
	s_waitcnt lgkmcnt(0)
	v_mfma_f32_32x32x16_bf16 v[0:15], v[96:99], v[100:103], v[0:15]
	ds_read_b64_tr_b16 v[92:93], v180 offset:43008
	ds_read_b64_tr_b16 v[94:95], v180 offset:43520
	ds_read_b64_tr_b16 v[96:97], v180 offset:47104
	ds_read_b64_tr_b16 v[98:99], v180 offset:47616
	s_waitcnt lgkmcnt(2)
	v_mfma_f32_32x32x16_bf16 v[16:31], v[92:95], v[80:83], v[16:31]
	s_waitcnt lgkmcnt(0)
	v_mfma_f32_32x32x16_bf16 v[0:15], v[96:99], v[80:83], v[0:15]
	ds_read_b64_tr_b16 v[80:81], v180 offset:44032
	ds_read_b64_tr_b16 v[82:83], v180 offset:44544
	ds_read_b64_tr_b16 v[92:93], v180 offset:48128
	ds_read_b64_tr_b16 v[94:95], v180 offset:48640
	s_waitcnt lgkmcnt(2)
	v_mfma_f32_32x32x16_bf16 v[16:31], v[80:83], v[88:91], v[16:31]
	s_waitcnt lgkmcnt(0)
	v_mfma_f32_32x32x16_bf16 v[0:15], v[92:95], v[88:91], v[0:15]
	v_lshl_add_u64 v[146:147], v[174:175], 0, s[46:47]
	v_lshl_add_u64 v[148:149], v[172:173], 0, s[46:47]
	v_add_co_u32_e32 v80, vcc, 0x88d8000, v146
	s_nop 1
	v_addc_co_u32_e32 v81, vcc, 0, v147, vcc
	global_load_dwordx4 v[114:117], v[80:81], off offset:3072
	v_add_co_u32_e32 v80, vcc, 0x8890000, v148
	s_nop 1
	v_addc_co_u32_e32 v81, vcc, 0, v149, vcc
	global_load_dwordx4 v[142:145], v[80:81], off offset:3328
	ds_read_b128 v[80:83], v179 offset:8192
	ds_read_b128 v[182:185], v179 offset:8704
	ds_read_b128 v[186:189], v179 offset:10240
	ds_read_b128 v[190:193], v179 offset:10752
	ds_read_b128 v[200:203], v179 offset:12288
	ds_read_b128 v[204:207], v179 offset:12800
	ds_read_b128 v[208:211], v179 offset:14336
	ds_read_b128 v[212:215], v179 offset:14848
	v_exp_f32_e32 v64, v64
	v_exp_f32_e32 v65, v65
	v_exp_f32_e32 v66, v66
	v_exp_f32_e32 v67, v67
	v_exp_f32_e32 v48, v48
	v_exp_f32_e32 v49, v49
	v_exp_f32_e32 v50, v50
	v_exp_f32_e32 v51, v51
	v_add_f32_e32 v84, v50, v66
	v_add_f32_e32 v85, v51, v67
	v_add_f32_e32 v86, v48, v64
	v_add_f32_e32 v87, v49, v65
	v_cvt_pk_bf16_f32 v64, v64, v65
	v_cvt_pk_bf16_f32 v65, v66, v67
	v_cvt_pk_bf16_f32 v48, v48, v49
	v_cvt_pk_bf16_f32 v49, v50, v51
	s_waitcnt lgkmcnt(7)
	v_mfma_f32_32x32x16_bf16 v[96:111], v[80:83], v[118:121], v[32:47]
	v_exp_f32_e32 v50, v68
	v_exp_f32_e32 v51, v69
	v_exp_f32_e32 v68, v70
	v_exp_f32_e32 v69, v71
	v_add_f32_e32 v70, v50, v86
	v_add_f32_e32 v71, v51, v87
	v_add_f32_e32 v181, v68, v84
	v_add_f32_e32 v228, v69, v85
	v_cvt_pk_bf16_f32 v66, v50, v51
	v_cvt_pk_bf16_f32 v67, v68, v69
	s_waitcnt lgkmcnt(6)
	v_mfma_f32_32x32x16_bf16 v[80:95], v[182:185], v[118:121], v[32:47]
	v_exp_f32_e32 v50, v52
	v_exp_f32_e32 v51, v53
	v_exp_f32_e32 v52, v54
	v_exp_f32_e32 v53, v55
	v_add_f32_e32 v54, v50, v70
	v_add_f32_e32 v55, v51, v71
	v_add_f32_e32 v68, v52, v181
	v_add_f32_e32 v69, v53, v228
	v_cvt_pk_bf16_f32 v50, v50, v51
	v_cvt_pk_bf16_f32 v51, v52, v53
	s_waitcnt lgkmcnt(5)
	v_mfma_f32_32x32x16_bf16 v[96:111], v[186:189], v[122:125], v[96:111]
	v_exp_f32_e32 v52, v72
	v_exp_f32_e32 v53, v73
	v_exp_f32_e32 v70, v74
	v_exp_f32_e32 v71, v75
	v_add_f32_e32 v54, v52, v54
	v_add_f32_e32 v55, v53, v55
	v_add_f32_e32 v72, v70, v68
	v_add_f32_e32 v73, v71, v69
	v_cvt_pk_bf16_f32 v68, v52, v53
	v_cvt_pk_bf16_f32 v69, v70, v71
	s_waitcnt lgkmcnt(4)
	v_mfma_f32_32x32x16_bf16 v[80:95], v[190:193], v[122:125], v[80:95]
	v_exp_f32_e32 v52, v56
	v_exp_f32_e32 v53, v57
	v_exp_f32_e32 v57, v58
	v_exp_f32_e32 v58, v59
	v_add_f32_e32 v54, v52, v54
	v_add_f32_e32 v55, v53, v55
	v_add_f32_e32 v59, v57, v72
	v_add_f32_e32 v70, v58, v73
	v_cvt_pk_bf16_f32 v56, v52, v53
	v_cvt_pk_bf16_f32 v57, v57, v58
	s_waitcnt lgkmcnt(3)
	v_mfma_f32_32x32x16_bf16 v[96:111], v[200:203], v[126:129], v[96:111]
	v_exp_f32_e32 v52, v76
	v_exp_f32_e32 v53, v77
	v_exp_f32_e32 v58, v78
	v_exp_f32_e32 v71, v79
	v_add_f32_e32 v54, v52, v54
	v_add_f32_e32 v55, v53, v55
	v_add_f32_e32 v59, v58, v59
	v_add_f32_e32 v72, v71, v70
	v_cvt_pk_bf16_f32 v70, v52, v53
	v_cvt_pk_bf16_f32 v71, v58, v71
	s_waitcnt lgkmcnt(2)
	v_mfma_f32_32x32x16_bf16 v[80:95], v[204:207], v[126:129], v[80:95]
	v_exp_f32_e32 v58, v60
	v_exp_f32_e32 v60, v61
	v_exp_f32_e32 v61, v62
	v_exp_f32_e32 v62, v63
	v_add_f32_e32 v52, v58, v54
	v_add_f32_e32 v53, v60, v55
	v_add_f32_e32 v54, v61, v59
	v_add_f32_e32 v55, v62, v72
	v_cvt_pk_bf16_f32 v58, v58, v60
	v_cvt_pk_bf16_f32 v59, v61, v62
	s_waitcnt lgkmcnt(1)
	v_mfma_f32_32x32x16_bf16 v[96:111], v[208:211], v[130:133], v[96:111]
	s_waitcnt lgkmcnt(0)
	v_mfma_f32_32x32x16_bf16 v[80:95], v[212:215], v[130:133], v[80:95]
	v_add_f32_e32 v182, v52, v53
	v_add_f32_e32 v183, v54, v55
	v_add_f32_e32 v182, v182, v183
	v_add_f32_e32 v169, v169, v182
	s_waitcnt vmcnt(2)
	ds_write_b128 v177, v[134:137]
	ds_write_b128 v178, v[138:141] offset:24576
	s_waitcnt lgkmcnt(0)
	s_barrier
	ds_read_b64_tr_b16 v[60:61], v180 offset:16384
	ds_read_b64_tr_b16 v[62:63], v180 offset:16896
	ds_read_b64_tr_b16 v[72:73], v180 offset:20480
	ds_read_b64_tr_b16 v[74:75], v180 offset:20992
	s_waitcnt lgkmcnt(2)
	v_mfma_f32_32x32x16_bf16 v[16:31], v[60:63], v[64:67], v[16:31]
	s_waitcnt lgkmcnt(0)
	v_mfma_f32_32x32x16_bf16 v[0:15], v[72:75], v[64:67], v[0:15]
	ds_read_b64_tr_b16 v[60:61], v180 offset:17408
	ds_read_b64_tr_b16 v[62:63], v180 offset:17920
	ds_read_b64_tr_b16 v[64:65], v180 offset:21504
	ds_read_b64_tr_b16 v[66:67], v180 offset:22016
	s_waitcnt lgkmcnt(2)
	v_mfma_f32_32x32x16_bf16 v[16:31], v[60:63], v[68:71], v[16:31]
	s_waitcnt lgkmcnt(0)
	v_mfma_f32_32x32x16_bf16 v[0:15], v[64:67], v[68:71], v[0:15]
	ds_read_b64_tr_b16 v[60:61], v180 offset:18432
	ds_read_b64_tr_b16 v[62:63], v180 offset:18944
	ds_read_b64_tr_b16 v[64:65], v180 offset:22528
	ds_read_b64_tr_b16 v[66:67], v180 offset:23040
	s_waitcnt lgkmcnt(2)
	v_mfma_f32_32x32x16_bf16 v[16:31], v[60:63], v[48:51], v[16:31]
	s_waitcnt lgkmcnt(0)
	v_mfma_f32_32x32x16_bf16 v[0:15], v[64:67], v[48:51], v[0:15]
	ds_read_b64_tr_b16 v[48:49], v180 offset:19456
	ds_read_b64_tr_b16 v[50:51], v180 offset:19968
	ds_read_b64_tr_b16 v[60:61], v180 offset:23552
	ds_read_b64_tr_b16 v[62:63], v180 offset:24064
	s_waitcnt lgkmcnt(2)
	v_mfma_f32_32x32x16_bf16 v[16:31], v[48:51], v[56:59], v[16:31]
	s_waitcnt lgkmcnt(0)
	v_mfma_f32_32x32x16_bf16 v[0:15], v[60:63], v[56:59], v[0:15]
	v_add_co_u32_e32 v64, vcc, 0x8920000, v146
	s_nop 1
	v_addc_co_u32_e32 v65, vcc, 0, v147, vcc
	global_load_dwordx4 v[134:137], v[64:65], off offset:3072
	v_add_co_u32_e32 v64, vcc, 0x88d8000, v148
	s_nop 1
	v_addc_co_u32_e32 v65, vcc, 0, v149, vcc
	global_load_dwordx4 v[138:141], v[64:65], off offset:3328
	ds_read_b128 v[182:185], v179
	ds_read_b128 v[186:189], v179 offset:512
	ds_read_b128 v[190:193], v179 offset:2048
	ds_read_b128 v[200:203], v179 offset:2560
	ds_read_b128 v[204:207], v179 offset:4096
	ds_read_b128 v[208:211], v179 offset:4608
	ds_read_b128 v[212:215], v179 offset:6144
	ds_read_b128 v[146:149], v179 offset:6656
	v_exp_f32_e32 v64, v96
	v_exp_f32_e32 v65, v97
	v_exp_f32_e32 v66, v98
	v_exp_f32_e32 v67, v99
	v_cvt_pk_bf16_f32 v96, v64, v65
	v_cvt_pk_bf16_f32 v97, v66, v67
	v_exp_f32_e32 v68, v80
	v_exp_f32_e32 v69, v81
	v_exp_f32_e32 v70, v82
	v_exp_f32_e32 v71, v83
	v_cvt_pk_bf16_f32 v80, v68, v69
	v_cvt_pk_bf16_f32 v81, v70, v71
	v_add_f32_e32 v68, v68, v64
	v_add_f32_e32 v69, v69, v65
	v_add_f32_e32 v82, v70, v66
	v_add_f32_e32 v83, v71, v67
	v_exp_f32_e32 v98, v100
	v_exp_f32_e32 v99, v101
	v_exp_f32_e32 v100, v102
	v_exp_f32_e32 v101, v103
	v_add_f32_e32 v102, v98, v68
	v_add_f32_e32 v103, v99, v69
	s_waitcnt lgkmcnt(7)
	v_mfma_f32_32x32x16_bf16 v[64:79], v[182:185], v[118:121], v[32:47]
	v_add_f32_e32 v82, v100, v82
	v_add_f32_e32 v83, v101, v83
	v_cvt_pk_bf16_f32 v98, v98, v99
	v_cvt_pk_bf16_f32 v99, v100, v101
	s_waitcnt lgkmcnt(6)
	v_mfma_f32_32x32x16_bf16 v[48:63], v[186:189], v[118:121], v[32:47]
	v_exp_f32_e32 v84, v84
	v_exp_f32_e32 v85, v85
	v_exp_f32_e32 v86, v86
	v_exp_f32_e32 v87, v87
	v_add_f32_e32 v100, v84, v102
	v_add_f32_e32 v101, v85, v103
	v_add_f32_e32 v102, v86, v82
	v_add_f32_e32 v103, v87, v83
	v_cvt_pk_bf16_f32 v82, v84, v85
	v_cvt_pk_bf16_f32 v83, v86, v87
	s_waitcnt lgkmcnt(5)
	v_mfma_f32_32x32x16_bf16 v[64:79], v[190:193], v[122:125], v[64:79]
	v_exp_f32_e32 v84, v104
	v_exp_f32_e32 v85, v105
	v_exp_f32_e32 v86, v106
	v_exp_f32_e32 v87, v107
	v_add_f32_e32 v104, v84, v100
	v_add_f32_e32 v105, v85, v101
	v_add_f32_e32 v102, v86, v102
	v_add_f32_e32 v103, v87, v103
	v_cvt_pk_bf16_f32 v100, v84, v85
	v_cvt_pk_bf16_f32 v101, v86, v87
	s_waitcnt lgkmcnt(4)
	v_mfma_f32_32x32x16_bf16 v[48:63], v[200:203], v[122:125], v[48:63]
	v_exp_f32_e32 v84, v88
	v_exp_f32_e32 v85, v89
	v_exp_f32_e32 v86, v90
	v_exp_f32_e32 v87, v91
	v_add_f32_e32 v90, v84, v104
	v_add_f32_e32 v91, v85, v105
	v_add_f32_e32 v102, v86, v102
	v_add_f32_e32 v103, v87, v103
	v_cvt_pk_bf16_f32 v88, v84, v85
	v_cvt_pk_bf16_f32 v89, v86, v87
	s_waitcnt lgkmcnt(3)
	v_mfma_f32_32x32x16_bf16 v[64:79], v[204:207], v[126:129], v[64:79]
	v_exp_f32_e32 v84, v108
	v_exp_f32_e32 v85, v109
	v_exp_f32_e32 v86, v110
	v_exp_f32_e32 v87, v111
	v_add_f32_e32 v90, v84, v90
	v_add_f32_e32 v91, v85, v91
	v_add_f32_e32 v104, v86, v102
	v_add_f32_e32 v105, v87, v103
	v_cvt_pk_bf16_f32 v102, v84, v85
	v_cvt_pk_bf16_f32 v103, v86, v87
	s_waitcnt lgkmcnt(2)
	v_mfma_f32_32x32x16_bf16 v[48:63], v[208:211], v[126:129], v[48:63]
	v_exp_f32_e32 v92, v92
	v_exp_f32_e32 v93, v93
	v_exp_f32_e32 v94, v94
	v_exp_f32_e32 v95, v95
	v_add_f32_e32 v84, v92, v90
	v_add_f32_e32 v85, v93, v91
	v_add_f32_e32 v86, v94, v104
	v_add_f32_e32 v87, v95, v105
	v_cvt_pk_bf16_f32 v90, v92, v93
	v_cvt_pk_bf16_f32 v91, v94, v95
	s_waitcnt lgkmcnt(1)
	v_mfma_f32_32x32x16_bf16 v[64:79], v[212:215], v[130:133], v[64:79]
	s_waitcnt lgkmcnt(0)
	v_mfma_f32_32x32x16_bf16 v[48:63], v[146:149], v[130:133], v[48:63]
	v_add_f32_e32 v182, v84, v85
	v_add_f32_e32 v183, v86, v87
	v_add_f32_e32 v182, v182, v183
	v_add_f32_e32 v169, v169, v182
	s_waitcnt vmcnt(2)
	ds_write_b128 v177, v[114:117] offset:8192
	ds_write_b128 v178, v[142:145] offset:32768
	s_waitcnt lgkmcnt(0)
	s_barrier
	v_lshl_add_u64 v[172:173], v[172:173], 0, s[4:5]
	v_lshl_add_u64 v[174:175], v[174:175], 0, s[4:5]
	ds_read_b64_tr_b16 v[92:93], v180 offset:24576
	ds_read_b64_tr_b16 v[94:95], v180 offset:25088
	ds_read_b64_tr_b16 v[104:105], v180 offset:28672
	ds_read_b64_tr_b16 v[106:107], v180 offset:29184
	s_waitcnt lgkmcnt(2)
	v_mfma_f32_32x32x16_bf16 v[16:31], v[92:95], v[96:99], v[16:31]
	s_waitcnt lgkmcnt(0)
	v_mfma_f32_32x32x16_bf16 v[0:15], v[104:107], v[96:99], v[0:15]
	ds_read_b64_tr_b16 v[92:93], v180 offset:25600
	ds_read_b64_tr_b16 v[94:95], v180 offset:26112
	ds_read_b64_tr_b16 v[96:97], v180 offset:29696
	ds_read_b64_tr_b16 v[98:99], v180 offset:30208
	s_waitcnt lgkmcnt(2)
	v_mfma_f32_32x32x16_bf16 v[16:31], v[92:95], v[100:103], v[16:31]
	s_waitcnt lgkmcnt(0)
	v_mfma_f32_32x32x16_bf16 v[0:15], v[96:99], v[100:103], v[0:15]
	ds_read_b64_tr_b16 v[92:93], v180 offset:26624
	ds_read_b64_tr_b16 v[94:95], v180 offset:27136
	ds_read_b64_tr_b16 v[96:97], v180 offset:30720
	ds_read_b64_tr_b16 v[98:99], v180 offset:31232
	s_waitcnt lgkmcnt(2)
	v_mfma_f32_32x32x16_bf16 v[16:31], v[92:95], v[80:83], v[16:31]
	s_waitcnt lgkmcnt(0)
	v_mfma_f32_32x32x16_bf16 v[0:15], v[96:99], v[80:83], v[0:15]
	ds_read_b64_tr_b16 v[80:81], v180 offset:27648
	ds_read_b64_tr_b16 v[82:83], v180 offset:28160
	ds_read_b64_tr_b16 v[92:93], v180 offset:31744
	ds_read_b64_tr_b16 v[94:95], v180 offset:32256
	s_waitcnt lgkmcnt(2)
	v_mfma_f32_32x32x16_bf16 v[16:31], v[80:83], v[88:91], v[16:31]
	s_waitcnt lgkmcnt(0)
	v_mfma_f32_32x32x16_bf16 v[0:15], v[92:95], v[88:91], v[0:15]
	v_lshl_add_u64 v[146:147], v[174:175], 0, s[46:47]
	v_lshl_add_u64 v[148:149], v[172:173], 0, s[46:47]
	v_add_co_u32_e32 v80, vcc, 0x88d8000, v146
	s_nop 1
	v_addc_co_u32_e32 v81, vcc, 0, v147, vcc
	global_load_dwordx4 v[114:117], v[80:81], off offset:3072
	v_add_co_u32_e32 v80, vcc, 0x8890000, v148
	s_nop 1
	v_addc_co_u32_e32 v81, vcc, 0, v149, vcc
	global_load_dwordx4 v[142:145], v[80:81], off offset:3328
	ds_read_b128 v[80:83], v179 offset:8192
	ds_read_b128 v[182:185], v179 offset:8704
	ds_read_b128 v[186:189], v179 offset:10240
	ds_read_b128 v[190:193], v179 offset:10752
	ds_read_b128 v[200:203], v179 offset:12288
	ds_read_b128 v[204:207], v179 offset:12800
	ds_read_b128 v[208:211], v179 offset:14336
	ds_read_b128 v[212:215], v179 offset:14848
	v_exp_f32_e32 v64, v64
	v_exp_f32_e32 v65, v65
	v_exp_f32_e32 v66, v66
	v_exp_f32_e32 v67, v67
	v_exp_f32_e32 v48, v48
	v_exp_f32_e32 v49, v49
	v_exp_f32_e32 v50, v50
	v_exp_f32_e32 v51, v51
	v_add_f32_e32 v84, v50, v66
	v_add_f32_e32 v85, v51, v67
	v_add_f32_e32 v86, v48, v64
	v_add_f32_e32 v87, v49, v65
	v_cvt_pk_bf16_f32 v64, v64, v65
	v_cvt_pk_bf16_f32 v65, v66, v67
	v_cvt_pk_bf16_f32 v48, v48, v49
	v_cvt_pk_bf16_f32 v49, v50, v51
	s_waitcnt lgkmcnt(7)
	v_mfma_f32_32x32x16_bf16 v[96:111], v[80:83], v[118:121], v[32:47]
	v_exp_f32_e32 v50, v68
	v_exp_f32_e32 v51, v69
	v_exp_f32_e32 v68, v70
	v_exp_f32_e32 v69, v71
	v_add_f32_e32 v70, v50, v86
	v_add_f32_e32 v71, v51, v87
	v_add_f32_e32 v181, v68, v84
	v_add_f32_e32 v228, v69, v85
	v_cvt_pk_bf16_f32 v66, v50, v51
	v_cvt_pk_bf16_f32 v67, v68, v69
	s_waitcnt lgkmcnt(6)
	v_mfma_f32_32x32x16_bf16 v[80:95], v[182:185], v[118:121], v[32:47]
	v_exp_f32_e32 v50, v52
	v_exp_f32_e32 v51, v53
	v_exp_f32_e32 v52, v54
	v_exp_f32_e32 v53, v55
	v_add_f32_e32 v54, v50, v70
	v_add_f32_e32 v55, v51, v71
	v_add_f32_e32 v68, v52, v181
	v_add_f32_e32 v69, v53, v228
	v_cvt_pk_bf16_f32 v50, v50, v51
	v_cvt_pk_bf16_f32 v51, v52, v53
	s_waitcnt lgkmcnt(5)
	v_mfma_f32_32x32x16_bf16 v[96:111], v[186:189], v[122:125], v[96:111]
	v_exp_f32_e32 v52, v72
	v_exp_f32_e32 v53, v73
	v_exp_f32_e32 v70, v74
	v_exp_f32_e32 v71, v75
	v_add_f32_e32 v54, v52, v54
	v_add_f32_e32 v55, v53, v55
	v_add_f32_e32 v72, v70, v68
	v_add_f32_e32 v73, v71, v69
	v_cvt_pk_bf16_f32 v68, v52, v53
	v_cvt_pk_bf16_f32 v69, v70, v71
	s_waitcnt lgkmcnt(4)
	v_mfma_f32_32x32x16_bf16 v[80:95], v[190:193], v[122:125], v[80:95]
	v_exp_f32_e32 v52, v56
	v_exp_f32_e32 v53, v57
	v_exp_f32_e32 v57, v58
	v_exp_f32_e32 v58, v59
	v_add_f32_e32 v54, v52, v54
	v_add_f32_e32 v55, v53, v55
	v_add_f32_e32 v59, v57, v72
	v_add_f32_e32 v70, v58, v73
	v_cvt_pk_bf16_f32 v56, v52, v53
	v_cvt_pk_bf16_f32 v57, v57, v58
	s_waitcnt lgkmcnt(3)
	v_mfma_f32_32x32x16_bf16 v[96:111], v[200:203], v[126:129], v[96:111]
	v_exp_f32_e32 v52, v76
	v_exp_f32_e32 v53, v77
	v_exp_f32_e32 v58, v78
	v_exp_f32_e32 v71, v79
	v_add_f32_e32 v54, v52, v54
	v_add_f32_e32 v55, v53, v55
	v_add_f32_e32 v59, v58, v59
	v_add_f32_e32 v72, v71, v70
	v_cvt_pk_bf16_f32 v70, v52, v53
	v_cvt_pk_bf16_f32 v71, v58, v71
	s_waitcnt lgkmcnt(2)
	v_mfma_f32_32x32x16_bf16 v[80:95], v[204:207], v[126:129], v[80:95]
	v_exp_f32_e32 v58, v60
	v_exp_f32_e32 v60, v61
	v_exp_f32_e32 v61, v62
	v_exp_f32_e32 v62, v63
	v_add_f32_e32 v52, v58, v54
	v_add_f32_e32 v53, v60, v55
	v_add_f32_e32 v54, v61, v59
	v_add_f32_e32 v55, v62, v72
	v_cvt_pk_bf16_f32 v58, v58, v60
	v_cvt_pk_bf16_f32 v59, v61, v62
	s_waitcnt lgkmcnt(1)
	v_mfma_f32_32x32x16_bf16 v[96:111], v[208:211], v[130:133], v[96:111]
	s_waitcnt lgkmcnt(0)
	v_mfma_f32_32x32x16_bf16 v[80:95], v[212:215], v[130:133], v[80:95]
	v_add_f32_e32 v182, v52, v53
	v_add_f32_e32 v183, v54, v55
	v_add_f32_e32 v182, v182, v183
	v_add_f32_e32 v169, v169, v182
	s_waitcnt vmcnt(2)
	ds_write_b128 v177, v[134:137]
	ds_write_b128 v178, v[138:141] offset:40960
	s_waitcnt lgkmcnt(0)
	s_barrier
; __device__ __forceinline__ void attn_unit(LAS unsigned char* lds, bf16_t* P, const float* qgain, const float* rope, int s, int h, int qb, int lane, int wid, bool dry) {
;     ...
;     for (int t = 0; t < NT; t += 2) {
;         ASTEP(t, pA0, pA1, pB0, pB1, krA, vrA, krB, vrB);
;         ASTEP(t + 1, pB0, pB1, pA0, pA1, krB, vrB, krA, vrA);
;     }
	ds_read_b64_tr_b16 v[60:61], v180 offset:32768
	ds_read_b64_tr_b16 v[62:63], v180 offset:33280
	ds_read_b64_tr_b16 v[72:73], v180 offset:36864
	ds_read_b64_tr_b16 v[74:75], v180 offset:37376
	s_waitcnt lgkmcnt(2)
	v_mfma_f32_32x32x16_bf16 v[16:31], v[60:63], v[64:67], v[16:31]
	s_waitcnt lgkmcnt(0)
	v_mfma_f32_32x32x16_bf16 v[0:15], v[72:75], v[64:67], v[0:15]
	ds_read_b64_tr_b16 v[60:61], v180 offset:33792
	ds_read_b64_tr_b16 v[62:63], v180 offset:34304
	ds_read_b64_tr_b16 v[64:65], v180 offset:37888
	ds_read_b64_tr_b16 v[66:67], v180 offset:38400
	s_waitcnt lgkmcnt(2)
	v_mfma_f32_32x32x16_bf16 v[16:31], v[60:63], v[68:71], v[16:31]
	s_waitcnt lgkmcnt(0)
	v_mfma_f32_32x32x16_bf16 v[0:15], v[64:67], v[68:71], v[0:15]
	ds_read_b64_tr_b16 v[60:61], v180 offset:34816
	ds_read_b64_tr_b16 v[62:63], v180 offset:35328
	ds_read_b64_tr_b16 v[64:65], v180 offset:38912
	ds_read_b64_tr_b16 v[66:67], v180 offset:39424
	s_waitcnt lgkmcnt(2)
	v_mfma_f32_32x32x16_bf16 v[16:31], v[60:63], v[48:51], v[16:31]
	s_waitcnt lgkmcnt(0)
	v_mfma_f32_32x32x16_bf16 v[0:15], v[64:67], v[48:51], v[0:15]
	ds_read_b64_tr_b16 v[48:49], v180 offset:35840
	ds_read_b64_tr_b16 v[50:51], v180 offset:36352
	ds_read_b64_tr_b16 v[60:61], v180 offset:39936
	ds_read_b64_tr_b16 v[62:63], v180 offset:40448
	s_waitcnt lgkmcnt(2)
	v_mfma_f32_32x32x16_bf16 v[16:31], v[48:51], v[56:59], v[16:31]
	s_waitcnt lgkmcnt(0)
	v_mfma_f32_32x32x16_bf16 v[0:15], v[60:63], v[56:59], v[0:15]
	v_add_co_u32_e32 v64, vcc, 0x8920000, v146
	s_nop 1
	v_addc_co_u32_e32 v65, vcc, 0, v147, vcc
	global_load_dwordx4 v[134:137], v[64:65], off offset:3072
	v_add_co_u32_e32 v64, vcc, 0x88d8000, v148
	s_nop 1
	v_addc_co_u32_e32 v65, vcc, 0, v149, vcc
	global_load_dwordx4 v[138:141], v[64:65], off offset:3328
	ds_read_b128 v[182:185], v179
	ds_read_b128 v[186:189], v179 offset:512
	ds_read_b128 v[190:193], v179 offset:2048
	ds_read_b128 v[200:203], v179 offset:2560
	ds_read_b128 v[204:207], v179 offset:4096
	ds_read_b128 v[208:211], v179 offset:4608
	ds_read_b128 v[212:215], v179 offset:6144
	ds_read_b128 v[146:149], v179 offset:6656
	v_exp_f32_e32 v64, v96
	v_exp_f32_e32 v65, v97
	v_exp_f32_e32 v66, v98
	v_exp_f32_e32 v67, v99
	v_cvt_pk_bf16_f32 v96, v64, v65
	v_cvt_pk_bf16_f32 v97, v66, v67
	v_exp_f32_e32 v68, v80
	v_exp_f32_e32 v69, v81
	v_exp_f32_e32 v70, v82
	v_exp_f32_e32 v71, v83
	v_cvt_pk_bf16_f32 v80, v68, v69
	v_cvt_pk_bf16_f32 v81, v70, v71
	v_add_f32_e32 v68, v68, v64
	v_add_f32_e32 v69, v69, v65
	v_add_f32_e32 v82, v70, v66
	v_add_f32_e32 v83, v71, v67
	v_exp_f32_e32 v98, v100
	v_exp_f32_e32 v99, v101
	v_exp_f32_e32 v100, v102
	v_exp_f32_e32 v101, v103
	v_add_f32_e32 v102, v98, v68
	v_add_f32_e32 v103, v99, v69
	s_waitcnt lgkmcnt(7)
	v_mfma_f32_32x32x16_bf16 v[64:79], v[182:185], v[118:121], v[32:47]
	v_add_f32_e32 v82, v100, v82
	v_add_f32_e32 v83, v101, v83
	v_cvt_pk_bf16_f32 v98, v98, v99
	v_cvt_pk_bf16_f32 v99, v100, v101
	s_waitcnt lgkmcnt(6)
	v_mfma_f32_32x32x16_bf16 v[48:63], v[186:189], v[118:121], v[32:47]
	v_exp_f32_e32 v84, v84
	v_exp_f32_e32 v85, v85
	v_exp_f32_e32 v86, v86
	v_exp_f32_e32 v87, v87
	v_add_f32_e32 v100, v84, v102
	v_add_f32_e32 v101, v85, v103
	v_add_f32_e32 v102, v86, v82
	v_add_f32_e32 v103, v87, v83
	v_cvt_pk_bf16_f32 v82, v84, v85
	v_cvt_pk_bf16_f32 v83, v86, v87
	s_waitcnt lgkmcnt(5)
	v_mfma_f32_32x32x16_bf16 v[64:79], v[190:193], v[122:125], v[64:79]
	v_exp_f32_e32 v84, v104
	v_exp_f32_e32 v85, v105
	v_exp_f32_e32 v86, v106
	v_exp_f32_e32 v87, v107
	v_add_f32_e32 v104, v84, v100
	v_add_f32_e32 v105, v85, v101
	v_add_f32_e32 v102, v86, v102
	v_add_f32_e32 v103, v87, v103
	v_cvt_pk_bf16_f32 v100, v84, v85
	v_cvt_pk_bf16_f32 v101, v86, v87
	s_waitcnt lgkmcnt(4)
	v_mfma_f32_32x32x16_bf16 v[48:63], v[200:203], v[122:125], v[48:63]
	v_exp_f32_e32 v84, v88
	v_exp_f32_e32 v85, v89
	v_exp_f32_e32 v86, v90
	v_exp_f32_e32 v87, v91
	v_add_f32_e32 v90, v84, v104
	v_add_f32_e32 v91, v85, v105
	v_add_f32_e32 v102, v86, v102
	v_add_f32_e32 v103, v87, v103
	v_cvt_pk_bf16_f32 v88, v84, v85
	v_cvt_pk_bf16_f32 v89, v86, v87
	s_waitcnt lgkmcnt(3)
	v_mfma_f32_32x32x16_bf16 v[64:79], v[204:207], v[126:129], v[64:79]
	v_exp_f32_e32 v84, v108
	v_exp_f32_e32 v85, v109
	v_exp_f32_e32 v86, v110
	v_exp_f32_e32 v87, v111
	v_add_f32_e32 v90, v84, v90
	v_add_f32_e32 v91, v85, v91
	v_add_f32_e32 v104, v86, v102
	v_add_f32_e32 v105, v87, v103
	v_cvt_pk_bf16_f32 v102, v84, v85
	v_cvt_pk_bf16_f32 v103, v86, v87
	s_waitcnt lgkmcnt(2)
	v_mfma_f32_32x32x16_bf16 v[48:63], v[208:211], v[126:129], v[48:63]
	v_exp_f32_e32 v92, v92
	v_exp_f32_e32 v93, v93
	v_exp_f32_e32 v94, v94
	v_exp_f32_e32 v95, v95
	v_add_f32_e32 v84, v92, v90
	v_add_f32_e32 v85, v93, v91
	v_add_f32_e32 v86, v94, v104
	v_add_f32_e32 v87, v95, v105
	v_cvt_pk_bf16_f32 v90, v92, v93
	v_cvt_pk_bf16_f32 v91, v94, v95
	s_waitcnt lgkmcnt(1)
	v_mfma_f32_32x32x16_bf16 v[64:79], v[212:215], v[130:133], v[64:79]
	s_waitcnt lgkmcnt(0)
	v_mfma_f32_32x32x16_bf16 v[48:63], v[146:149], v[130:133], v[48:63]
	v_add_f32_e32 v182, v84, v85
	v_add_f32_e32 v183, v86, v87
	v_add_f32_e32 v182, v182, v183
	v_add_f32_e32 v169, v169, v182
	s_waitcnt vmcnt(2)
	ds_write_b128 v177, v[114:117] offset:8192
	ds_write_b128 v178, v[142:145] offset:16384
	s_waitcnt lgkmcnt(0)
	s_barrier
	v_lshl_add_u64 v[172:173], v[172:173], 0, s[4:5]
	v_lshl_add_u64 v[174:175], v[174:175], 0, s[4:5]
	s_add_i32 s80, s80, 4
	s_cmp_lt_u32 s80, 60
	s_cbranch_scc1 .Lfa_g1_loop
	ds_read_b64_tr_b16 v[92:93], v180 offset:40960
	ds_read_b64_tr_b16 v[94:95], v180 offset:41472
	ds_read_b64_tr_b16 v[104:105], v180 offset:45056
	ds_read_b64_tr_b16 v[106:107], v180 offset:45568
	s_waitcnt lgkmcnt(2)
	v_mfma_f32_32x32x16_bf16 v[16:31], v[92:95], v[96:99], v[16:31]
	s_waitcnt lgkmcnt(0)
	v_mfma_f32_32x32x16_bf16 v[0:15], v[104:107], v[96:99], v[0:15]
	ds_read_b64_tr_b16 v[92:93], v180 offset:41984
	ds_read_b64_tr_b16 v[94:95], v180 offset:42496
	ds_read_b64_tr_b16 v[96:97], v180 offset:46080
	ds_read_b64_tr_b16 v[98:99], v180 offset:46592
	s_waitcnt lgkmcnt(2)
	v_mfma_f32_32x32x16_bf16 v[16:31], v[92:95], v[100:103], v[16:31]
	s_waitcnt lgkmcnt(0)
	v_mfma_f32_32x32x16_bf16 v[0:15], v[96:99], v[100:103], v[0:15]
	ds_read_b64_tr_b16 v[92:93], v180 offset:43008
	ds_read_b64_tr_b16 v[94:95], v180 offset:43520
	ds_read_b64_tr_b16 v[96:97], v180 offset:47104
	ds_read_b64_tr_b16 v[98:99], v180 offset:47616
	s_waitcnt lgkmcnt(2)
	v_mfma_f32_32x32x16_bf16 v[16:31], v[92:95], v[80:83], v[16:31]
	s_waitcnt lgkmcnt(0)
	v_mfma_f32_32x32x16_bf16 v[0:15], v[96:99], v[80:83], v[0:15]
	ds_read_b64_tr_b16 v[80:81], v180 offset:44032
	ds_read_b64_tr_b16 v[82:83], v180 offset:44544
	ds_read_b64_tr_b16 v[92:93], v180 offset:48128
	ds_read_b64_tr_b16 v[94:95], v180 offset:48640
	s_waitcnt lgkmcnt(2)
	v_mfma_f32_32x32x16_bf16 v[16:31], v[80:83], v[88:91], v[16:31]
	s_waitcnt lgkmcnt(0)
	v_mfma_f32_32x32x16_bf16 v[0:15], v[92:95], v[88:91], v[0:15]
	v_lshl_add_u64 v[146:147], v[174:175], 0, s[46:47]
	v_lshl_add_u64 v[148:149], v[172:173], 0, s[46:47]
	v_add_co_u32_e32 v80, vcc, 0x88d8000, v146
	s_nop 1
	v_addc_co_u32_e32 v81, vcc, 0, v147, vcc
	global_load_dwordx4 v[114:117], v[80:81], off offset:3072
	v_add_co_u32_e32 v80, vcc, 0x8890000, v148
	s_nop 1
	v_addc_co_u32_e32 v81, vcc, 0, v149, vcc
	global_load_dwordx4 v[142:145], v[80:81], off offset:3328
	ds_read_b128 v[80:83], v179 offset:8192
	ds_read_b128 v[182:185], v179 offset:8704
	ds_read_b128 v[186:189], v179 offset:10240
	ds_read_b128 v[190:193], v179 offset:10752
	ds_read_b128 v[200:203], v179 offset:12288
	ds_read_b128 v[204:207], v179 offset:12800
	ds_read_b128 v[208:211], v179 offset:14336
	ds_read_b128 v[212:215], v179 offset:14848
	v_exp_f32_e32 v64, v64
	v_exp_f32_e32 v65, v65
	v_exp_f32_e32 v66, v66
	v_exp_f32_e32 v67, v67
	v_exp_f32_e32 v48, v48
	v_exp_f32_e32 v49, v49
	v_exp_f32_e32 v50, v50
	v_exp_f32_e32 v51, v51
	v_add_f32_e32 v84, v50, v66
	v_add_f32_e32 v85, v51, v67
	v_add_f32_e32 v86, v48, v64
	v_add_f32_e32 v87, v49, v65
	v_cvt_pk_bf16_f32 v64, v64, v65
	v_cvt_pk_bf16_f32 v65, v66, v67
	v_cvt_pk_bf16_f32 v48, v48, v49
	v_cvt_pk_bf16_f32 v49, v50, v51
	s_waitcnt lgkmcnt(7)
	v_mfma_f32_32x32x16_bf16 v[96:111], v[80:83], v[118:121], v[32:47]
	v_exp_f32_e32 v50, v68
	v_exp_f32_e32 v51, v69
	v_exp_f32_e32 v68, v70
	v_exp_f32_e32 v69, v71
	v_add_f32_e32 v70, v50, v86
	v_add_f32_e32 v71, v51, v87
	v_add_f32_e32 v181, v68, v84
	v_add_f32_e32 v228, v69, v85
	v_cvt_pk_bf16_f32 v66, v50, v51
	v_cvt_pk_bf16_f32 v67, v68, v69
	s_waitcnt lgkmcnt(6)
	v_mfma_f32_32x32x16_bf16 v[80:95], v[182:185], v[118:121], v[32:47]
	v_exp_f32_e32 v50, v52
	v_exp_f32_e32 v51, v53
	v_exp_f32_e32 v52, v54
	v_exp_f32_e32 v53, v55
	v_add_f32_e32 v54, v50, v70
	v_add_f32_e32 v55, v51, v71
	v_add_f32_e32 v68, v52, v181
	v_add_f32_e32 v69, v53, v228
	v_cvt_pk_bf16_f32 v50, v50, v51
	v_cvt_pk_bf16_f32 v51, v52, v53
	s_waitcnt lgkmcnt(5)
	v_mfma_f32_32x32x16_bf16 v[96:111], v[186:189], v[122:125], v[96:111]
	v_exp_f32_e32 v52, v72
	v_exp_f32_e32 v53, v73
	v_exp_f32_e32 v70, v74
	v_exp_f32_e32 v71, v75
	v_add_f32_e32 v54, v52, v54
	v_add_f32_e32 v55, v53, v55
	v_add_f32_e32 v72, v70, v68
	v_add_f32_e32 v73, v71, v69
	v_cvt_pk_bf16_f32 v68, v52, v53
	v_cvt_pk_bf16_f32 v69, v70, v71
	s_waitcnt lgkmcnt(4)
	v_mfma_f32_32x32x16_bf16 v[80:95], v[190:193], v[122:125], v[80:95]
	v_exp_f32_e32 v52, v56
	v_exp_f32_e32 v53, v57
	v_exp_f32_e32 v57, v58
	v_exp_f32_e32 v58, v59
	v_add_f32_e32 v54, v52, v54
	v_add_f32_e32 v55, v53, v55
	v_add_f32_e32 v59, v57, v72
	v_add_f32_e32 v70, v58, v73
	v_cvt_pk_bf16_f32 v56, v52, v53
	v_cvt_pk_bf16_f32 v57, v57, v58
	s_waitcnt lgkmcnt(3)
	v_mfma_f32_32x32x16_bf16 v[96:111], v[200:203], v[126:129], v[96:111]
	v_exp_f32_e32 v52, v76
	v_exp_f32_e32 v53, v77
	v_exp_f32_e32 v58, v78
	v_exp_f32_e32 v71, v79
	v_add_f32_e32 v54, v52, v54
	v_add_f32_e32 v55, v53, v55
	v_add_f32_e32 v59, v58, v59
	v_add_f32_e32 v72, v71, v70
	v_cvt_pk_bf16_f32 v70, v52, v53
	v_cvt_pk_bf16_f32 v71, v58, v71
	s_waitcnt lgkmcnt(2)
	v_mfma_f32_32x32x16_bf16 v[80:95], v[204:207], v[126:129], v[80:95]
	v_exp_f32_e32 v58, v60
	v_exp_f32_e32 v60, v61
	v_exp_f32_e32 v61, v62
	v_exp_f32_e32 v62, v63
	v_add_f32_e32 v52, v58, v54
	v_add_f32_e32 v53, v60, v55
	v_add_f32_e32 v54, v61, v59
	v_add_f32_e32 v55, v62, v72
	v_cvt_pk_bf16_f32 v58, v58, v60
	v_cvt_pk_bf16_f32 v59, v61, v62
	s_waitcnt lgkmcnt(1)
	v_mfma_f32_32x32x16_bf16 v[96:111], v[208:211], v[130:133], v[96:111]
	s_waitcnt lgkmcnt(0)
	v_mfma_f32_32x32x16_bf16 v[80:95], v[212:215], v[130:133], v[80:95]
	v_add_f32_e32 v182, v52, v53
	v_add_f32_e32 v183, v54, v55
	v_add_f32_e32 v182, v182, v183
	v_add_f32_e32 v169, v169, v182
	s_waitcnt vmcnt(2)
	ds_write_b128 v177, v[134:137]
	ds_write_b128 v178, v[138:141] offset:24576
	s_waitcnt lgkmcnt(0)
	s_barrier
	ds_read_b64_tr_b16 v[60:61], v180 offset:16384
	ds_read_b64_tr_b16 v[62:63], v180 offset:16896
	ds_read_b64_tr_b16 v[72:73], v180 offset:20480
	ds_read_b64_tr_b16 v[74:75], v180 offset:20992
	s_waitcnt lgkmcnt(2)
	v_mfma_f32_32x32x16_bf16 v[16:31], v[60:63], v[64:67], v[16:31]
	s_waitcnt lgkmcnt(0)
	v_mfma_f32_32x32x16_bf16 v[0:15], v[72:75], v[64:67], v[0:15]
	ds_read_b64_tr_b16 v[60:61], v180 offset:17408
	ds_read_b64_tr_b16 v[62:63], v180 offset:17920
	ds_read_b64_tr_b16 v[64:65], v180 offset:21504
	ds_read_b64_tr_b16 v[66:67], v180 offset:22016
	s_waitcnt lgkmcnt(2)
	v_mfma_f32_32x32x16_bf16 v[16:31], v[60:63], v[68:71], v[16:31]
	s_waitcnt lgkmcnt(0)
	v_mfma_f32_32x32x16_bf16 v[0:15], v[64:67], v[68:71], v[0:15]
	ds_read_b64_tr_b16 v[60:61], v180 offset:18432
	ds_read_b64_tr_b16 v[62:63], v180 offset:18944
	ds_read_b64_tr_b16 v[64:65], v180 offset:22528
	ds_read_b64_tr_b16 v[66:67], v180 offset:23040
	s_waitcnt lgkmcnt(2)
	v_mfma_f32_32x32x16_bf16 v[16:31], v[60:63], v[48:51], v[16:31]
	s_waitcnt lgkmcnt(0)
	v_mfma_f32_32x32x16_bf16 v[0:15], v[64:67], v[48:51], v[0:15]
	ds_read_b64_tr_b16 v[48:49], v180 offset:19456
	ds_read_b64_tr_b16 v[50:51], v180 offset:19968
	ds_read_b64_tr_b16 v[60:61], v180 offset:23552
	ds_read_b64_tr_b16 v[62:63], v180 offset:24064
	s_waitcnt lgkmcnt(2)
	v_mfma_f32_32x32x16_bf16 v[16:31], v[48:51], v[56:59], v[16:31]
	s_waitcnt lgkmcnt(0)
	v_mfma_f32_32x32x16_bf16 v[0:15], v[60:63], v[56:59], v[0:15]
	v_add_co_u32_e32 v64, vcc, 0x88d8000, v148
	s_nop 1
	v_addc_co_u32_e32 v65, vcc, 0, v149, vcc
	global_load_dwordx4 v[138:141], v[64:65], off offset:3328
	ds_read_b128 v[182:185], v179
	ds_read_b128 v[186:189], v179 offset:512
	ds_read_b128 v[190:193], v179 offset:2048
	ds_read_b128 v[200:203], v179 offset:2560
	ds_read_b128 v[204:207], v179 offset:4096
	ds_read_b128 v[208:211], v179 offset:4608
	ds_read_b128 v[212:215], v179 offset:6144
	ds_read_b128 v[146:149], v179 offset:6656
	v_exp_f32_e32 v64, v96
	v_exp_f32_e32 v65, v97
	v_exp_f32_e32 v66, v98
	v_exp_f32_e32 v67, v99
	v_cvt_pk_bf16_f32 v96, v64, v65
	v_cvt_pk_bf16_f32 v97, v66, v67
	v_exp_f32_e32 v68, v80
	v_exp_f32_e32 v69, v81
	v_exp_f32_e32 v70, v82
	v_exp_f32_e32 v71, v83
	v_cvt_pk_bf16_f32 v80, v68, v69
	v_cvt_pk_bf16_f32 v81, v70, v71
	v_add_f32_e32 v68, v68, v64
	v_add_f32_e32 v69, v69, v65
	v_add_f32_e32 v82, v70, v66
	v_add_f32_e32 v83, v71, v67
	v_exp_f32_e32 v98, v100
	v_exp_f32_e32 v99, v101
	v_exp_f32_e32 v100, v102
	v_exp_f32_e32 v101, v103
	v_add_f32_e32 v102, v98, v68
	v_add_f32_e32 v103, v99, v69
	s_waitcnt lgkmcnt(7)
	v_mfma_f32_32x32x16_bf16 v[64:79], v[182:185], v[118:121], v[32:47]
	v_add_f32_e32 v82, v100, v82
	v_add_f32_e32 v83, v101, v83
	v_cvt_pk_bf16_f32 v98, v98, v99
	v_cvt_pk_bf16_f32 v99, v100, v101
	s_waitcnt lgkmcnt(6)
	v_mfma_f32_32x32x16_bf16 v[48:63], v[186:189], v[118:121], v[32:47]
	v_exp_f32_e32 v84, v84
	v_exp_f32_e32 v85, v85
	v_exp_f32_e32 v86, v86
	v_exp_f32_e32 v87, v87
	v_add_f32_e32 v100, v84, v102
	v_add_f32_e32 v101, v85, v103
	v_add_f32_e32 v102, v86, v82
	v_add_f32_e32 v103, v87, v83
	v_cvt_pk_bf16_f32 v82, v84, v85
	v_cvt_pk_bf16_f32 v83, v86, v87
	s_waitcnt lgkmcnt(5)
	v_mfma_f32_32x32x16_bf16 v[64:79], v[190:193], v[122:125], v[64:79]
	v_exp_f32_e32 v84, v104
	v_exp_f32_e32 v85, v105
	v_exp_f32_e32 v86, v106
	v_exp_f32_e32 v87, v107
	v_add_f32_e32 v104, v84, v100
	v_add_f32_e32 v105, v85, v101
	v_add_f32_e32 v102, v86, v102
	v_add_f32_e32 v103, v87, v103
	v_cvt_pk_bf16_f32 v100, v84, v85
	v_cvt_pk_bf16_f32 v101, v86, v87
	s_waitcnt lgkmcnt(4)
	v_mfma_f32_32x32x16_bf16 v[48:63], v[200:203], v[122:125], v[48:63]
	v_exp_f32_e32 v84, v88
	v_exp_f32_e32 v85, v89
	v_exp_f32_e32 v86, v90
	v_exp_f32_e32 v87, v91
	v_add_f32_e32 v90, v84, v104
	v_add_f32_e32 v91, v85, v105
	v_add_f32_e32 v102, v86, v102
	v_add_f32_e32 v103, v87, v103
	v_cvt_pk_bf16_f32 v88, v84, v85
	v_cvt_pk_bf16_f32 v89, v86, v87
	s_waitcnt lgkmcnt(3)
	v_mfma_f32_32x32x16_bf16 v[64:79], v[204:207], v[126:129], v[64:79]
	v_exp_f32_e32 v84, v108
	v_exp_f32_e32 v85, v109
	v_exp_f32_e32 v86, v110
	v_exp_f32_e32 v87, v111
	v_add_f32_e32 v90, v84, v90
	v_add_f32_e32 v91, v85, v91
	v_add_f32_e32 v104, v86, v102
	v_add_f32_e32 v105, v87, v103
	v_cvt_pk_bf16_f32 v102, v84, v85
	v_cvt_pk_bf16_f32 v103, v86, v87
	s_waitcnt lgkmcnt(2)
	v_mfma_f32_32x32x16_bf16 v[48:63], v[208:211], v[126:129], v[48:63]
	v_exp_f32_e32 v92, v92
	v_exp_f32_e32 v93, v93
	v_exp_f32_e32 v94, v94
	v_exp_f32_e32 v95, v95
	v_add_f32_e32 v84, v92, v90
	v_add_f32_e32 v85, v93, v91
	v_add_f32_e32 v86, v94, v104
	v_add_f32_e32 v87, v95, v105
	v_cvt_pk_bf16_f32 v90, v92, v93
	v_cvt_pk_bf16_f32 v91, v94, v95
	s_waitcnt lgkmcnt(1)
	v_mfma_f32_32x32x16_bf16 v[64:79], v[212:215], v[130:133], v[64:79]
	s_waitcnt lgkmcnt(0)
	v_mfma_f32_32x32x16_bf16 v[48:63], v[146:149], v[130:133], v[48:63]
	v_add_f32_e32 v182, v84, v85
	v_add_f32_e32 v183, v86, v87
	v_add_f32_e32 v182, v182, v183
	v_add_f32_e32 v169, v169, v182
	s_waitcnt vmcnt(1)
	ds_write_b128 v177, v[114:117] offset:8192
	ds_write_b128 v178, v[142:145] offset:32768
	s_waitcnt lgkmcnt(0)
	s_barrier
	v_lshl_add_u64 v[172:173], v[172:173], 0, s[4:5]
	v_lshl_add_u64 v[174:175], v[174:175], 0, s[4:5]
	ds_read_b64_tr_b16 v[92:93], v180 offset:24576
	ds_read_b64_tr_b16 v[94:95], v180 offset:25088
	ds_read_b64_tr_b16 v[104:105], v180 offset:28672
	ds_read_b64_tr_b16 v[106:107], v180 offset:29184
	s_waitcnt lgkmcnt(2)
	v_mfma_f32_32x32x16_bf16 v[16:31], v[92:95], v[96:99], v[16:31]
	s_waitcnt lgkmcnt(0)
	v_mfma_f32_32x32x16_bf16 v[0:15], v[104:107], v[96:99], v[0:15]
	ds_read_b64_tr_b16 v[92:93], v180 offset:25600
	ds_read_b64_tr_b16 v[94:95], v180 offset:26112
	ds_read_b64_tr_b16 v[96:97], v180 offset:29696
	ds_read_b64_tr_b16 v[98:99], v180 offset:30208
	s_waitcnt lgkmcnt(2)
	v_mfma_f32_32x32x16_bf16 v[16:31], v[92:95], v[100:103], v[16:31]
	s_waitcnt lgkmcnt(0)
	v_mfma_f32_32x32x16_bf16 v[0:15], v[96:99], v[100:103], v[0:15]
	ds_read_b64_tr_b16 v[92:93], v180 offset:26624
	ds_read_b64_tr_b16 v[94:95], v180 offset:27136
	ds_read_b64_tr_b16 v[96:97], v180 offset:30720
	ds_read_b64_tr_b16 v[98:99], v180 offset:31232
	s_waitcnt lgkmcnt(2)
	v_mfma_f32_32x32x16_bf16 v[16:31], v[92:95], v[80:83], v[16:31]
	s_waitcnt lgkmcnt(0)
	v_mfma_f32_32x32x16_bf16 v[0:15], v[96:99], v[80:83], v[0:15]
	ds_read_b64_tr_b16 v[80:81], v180 offset:27648
	ds_read_b64_tr_b16 v[82:83], v180 offset:28160
	ds_read_b64_tr_b16 v[92:93], v180 offset:31744
	ds_read_b64_tr_b16 v[94:95], v180 offset:32256
	s_waitcnt lgkmcnt(2)
	v_mfma_f32_32x32x16_bf16 v[16:31], v[80:83], v[88:91], v[16:31]
	s_waitcnt lgkmcnt(0)
	v_mfma_f32_32x32x16_bf16 v[0:15], v[92:95], v[88:91], v[0:15]
	v_lshl_add_u64 v[146:147], v[174:175], 0, s[46:47]
	v_lshl_add_u64 v[148:149], v[172:173], 0, s[46:47]
	ds_read_b128 v[80:83], v179 offset:8192
	ds_read_b128 v[182:185], v179 offset:8704
	ds_read_b128 v[186:189], v179 offset:10240
	ds_read_b128 v[190:193], v179 offset:10752
	ds_read_b128 v[200:203], v179 offset:12288
	ds_read_b128 v[204:207], v179 offset:12800
	ds_read_b128 v[208:211], v179 offset:14336
	ds_read_b128 v[212:215], v179 offset:14848
	v_exp_f32_e32 v64, v64
	v_exp_f32_e32 v65, v65
	v_exp_f32_e32 v66, v66
	v_exp_f32_e32 v67, v67
	v_exp_f32_e32 v48, v48
	v_exp_f32_e32 v49, v49
	v_exp_f32_e32 v50, v50
	v_exp_f32_e32 v51, v51
	v_add_f32_e32 v84, v50, v66
	v_add_f32_e32 v85, v51, v67
	v_add_f32_e32 v86, v48, v64
	v_add_f32_e32 v87, v49, v65
	v_cvt_pk_bf16_f32 v64, v64, v65
	v_cvt_pk_bf16_f32 v65, v66, v67
	v_cvt_pk_bf16_f32 v48, v48, v49
	v_cvt_pk_bf16_f32 v49, v50, v51
	s_waitcnt lgkmcnt(7)
	v_mfma_f32_32x32x16_bf16 v[96:111], v[80:83], v[118:121], v[32:47]
	v_exp_f32_e32 v50, v68
	v_exp_f32_e32 v51, v69
	v_exp_f32_e32 v68, v70
	v_exp_f32_e32 v69, v71
	v_add_f32_e32 v70, v50, v86
	v_add_f32_e32 v71, v51, v87
	v_add_f32_e32 v181, v68, v84
	v_add_f32_e32 v228, v69, v85
	v_cvt_pk_bf16_f32 v66, v50, v51
	v_cvt_pk_bf16_f32 v67, v68, v69
	s_waitcnt lgkmcnt(6)
	v_mfma_f32_32x32x16_bf16 v[80:95], v[182:185], v[118:121], v[32:47]
	v_exp_f32_e32 v50, v52
	v_exp_f32_e32 v51, v53
	v_exp_f32_e32 v52, v54
	v_exp_f32_e32 v53, v55
	v_add_f32_e32 v54, v50, v70
	v_add_f32_e32 v55, v51, v71
	v_add_f32_e32 v68, v52, v181
	v_add_f32_e32 v69, v53, v228
	v_cvt_pk_bf16_f32 v50, v50, v51
	v_cvt_pk_bf16_f32 v51, v52, v53
	s_waitcnt lgkmcnt(5)
	v_mfma_f32_32x32x16_bf16 v[96:111], v[186:189], v[122:125], v[96:111]
	v_exp_f32_e32 v52, v72
	v_exp_f32_e32 v53, v73
	v_exp_f32_e32 v70, v74
	v_exp_f32_e32 v71, v75
	v_add_f32_e32 v54, v52, v54
	v_add_f32_e32 v55, v53, v55
	v_add_f32_e32 v72, v70, v68
	v_add_f32_e32 v73, v71, v69
	v_cvt_pk_bf16_f32 v68, v52, v53
	v_cvt_pk_bf16_f32 v69, v70, v71
	s_waitcnt lgkmcnt(4)
	v_mfma_f32_32x32x16_bf16 v[80:95], v[190:193], v[122:125], v[80:95]
	v_exp_f32_e32 v52, v56
	v_exp_f32_e32 v53, v57
	v_exp_f32_e32 v57, v58
	v_exp_f32_e32 v58, v59
	v_add_f32_e32 v54, v52, v54
	v_add_f32_e32 v55, v53, v55
	v_add_f32_e32 v59, v57, v72
	v_add_f32_e32 v70, v58, v73
	v_cvt_pk_bf16_f32 v56, v52, v53
	v_cvt_pk_bf16_f32 v57, v57, v58
	s_waitcnt lgkmcnt(3)
	v_mfma_f32_32x32x16_bf16 v[96:111], v[200:203], v[126:129], v[96:111]
	v_exp_f32_e32 v52, v76
	v_exp_f32_e32 v53, v77
	v_exp_f32_e32 v58, v78
	v_exp_f32_e32 v71, v79
	v_add_f32_e32 v54, v52, v54
	v_add_f32_e32 v55, v53, v55
	v_add_f32_e32 v59, v58, v59
	v_add_f32_e32 v72, v71, v70
	v_cvt_pk_bf16_f32 v70, v52, v53
	v_cvt_pk_bf16_f32 v71, v58, v71
	s_waitcnt lgkmcnt(2)
	v_mfma_f32_32x32x16_bf16 v[80:95], v[204:207], v[126:129], v[80:95]
	v_exp_f32_e32 v58, v60
	v_exp_f32_e32 v60, v61
	v_exp_f32_e32 v61, v62
	v_exp_f32_e32 v62, v63
	v_add_f32_e32 v52, v58, v54
	v_add_f32_e32 v53, v60, v55
	v_add_f32_e32 v54, v61, v59
	v_add_f32_e32 v55, v62, v72
	v_cvt_pk_bf16_f32 v58, v58, v60
	v_cvt_pk_bf16_f32 v59, v61, v62
	s_waitcnt lgkmcnt(1)
	v_mfma_f32_32x32x16_bf16 v[96:111], v[208:211], v[130:133], v[96:111]
	s_waitcnt lgkmcnt(0)
	v_mfma_f32_32x32x16_bf16 v[80:95], v[212:215], v[130:133], v[80:95]
	v_add_f32_e32 v182, v52, v53
	v_add_f32_e32 v183, v54, v55
	v_add_f32_e32 v182, v182, v183
	v_add_f32_e32 v169, v169, v182
	s_waitcnt vmcnt(0)
	ds_write_b128 v178, v[138:141] offset:40960
	s_waitcnt lgkmcnt(0)
	s_barrier
	ds_read_b64_tr_b16 v[60:61], v180 offset:32768
	ds_read_b64_tr_b16 v[62:63], v180 offset:33280
	ds_read_b64_tr_b16 v[72:73], v180 offset:36864
	ds_read_b64_tr_b16 v[74:75], v180 offset:37376
	s_waitcnt lgkmcnt(2)
	v_mfma_f32_32x32x16_bf16 v[16:31], v[60:63], v[64:67], v[16:31]
	s_waitcnt lgkmcnt(0)
	v_mfma_f32_32x32x16_bf16 v[0:15], v[72:75], v[64:67], v[0:15]
	ds_read_b64_tr_b16 v[60:61], v180 offset:33792
	ds_read_b64_tr_b16 v[62:63], v180 offset:34304
	ds_read_b64_tr_b16 v[64:65], v180 offset:37888
	ds_read_b64_tr_b16 v[66:67], v180 offset:38400
	s_waitcnt lgkmcnt(2)
	v_mfma_f32_32x32x16_bf16 v[16:31], v[60:63], v[68:71], v[16:31]
	s_waitcnt lgkmcnt(0)
	v_mfma_f32_32x32x16_bf16 v[0:15], v[64:67], v[68:71], v[0:15]
	ds_read_b64_tr_b16 v[60:61], v180 offset:34816
	ds_read_b64_tr_b16 v[62:63], v180 offset:35328
	ds_read_b64_tr_b16 v[64:65], v180 offset:38912
	ds_read_b64_tr_b16 v[66:67], v180 offset:39424
	s_waitcnt lgkmcnt(2)
	v_mfma_f32_32x32x16_bf16 v[16:31], v[60:63], v[48:51], v[16:31]
	s_waitcnt lgkmcnt(0)
	v_mfma_f32_32x32x16_bf16 v[0:15], v[64:67], v[48:51], v[0:15]
	ds_read_b64_tr_b16 v[48:49], v180 offset:35840
	ds_read_b64_tr_b16 v[50:51], v180 offset:36352
	ds_read_b64_tr_b16 v[60:61], v180 offset:39936
	ds_read_b64_tr_b16 v[62:63], v180 offset:40448
	s_waitcnt lgkmcnt(2)
	v_mfma_f32_32x32x16_bf16 v[16:31], v[48:51], v[56:59], v[16:31]
	s_waitcnt lgkmcnt(0)
	v_mfma_f32_32x32x16_bf16 v[0:15], v[60:63], v[56:59], v[0:15]
	v_exp_f32_e32 v64, v96
	v_exp_f32_e32 v65, v97
	v_exp_f32_e32 v66, v98
	v_exp_f32_e32 v67, v99
	v_cvt_pk_bf16_f32 v96, v64, v65
	v_cvt_pk_bf16_f32 v97, v66, v67
	v_exp_f32_e32 v68, v80
	v_exp_f32_e32 v69, v81
	v_exp_f32_e32 v70, v82
	v_exp_f32_e32 v71, v83
	v_cvt_pk_bf16_f32 v80, v68, v69
	v_cvt_pk_bf16_f32 v81, v70, v71
	v_add_f32_e32 v68, v68, v64
	v_add_f32_e32 v69, v69, v65
	v_add_f32_e32 v82, v70, v66
	v_add_f32_e32 v83, v71, v67
	v_exp_f32_e32 v98, v100
	v_exp_f32_e32 v99, v101
	v_exp_f32_e32 v100, v102
	v_exp_f32_e32 v101, v103
	v_add_f32_e32 v102, v98, v68
	v_add_f32_e32 v103, v99, v69
	v_add_f32_e32 v82, v100, v82
	v_add_f32_e32 v83, v101, v83
	v_cvt_pk_bf16_f32 v98, v98, v99
	v_cvt_pk_bf16_f32 v99, v100, v101
	v_exp_f32_e32 v84, v84
	v_exp_f32_e32 v85, v85
	v_exp_f32_e32 v86, v86
	v_exp_f32_e32 v87, v87
	v_add_f32_e32 v100, v84, v102
	v_add_f32_e32 v101, v85, v103
	v_add_f32_e32 v102, v86, v82
	v_add_f32_e32 v103, v87, v83
	v_cvt_pk_bf16_f32 v82, v84, v85
	v_cvt_pk_bf16_f32 v83, v86, v87
	v_exp_f32_e32 v84, v104
	v_exp_f32_e32 v85, v105
	v_exp_f32_e32 v86, v106
	v_exp_f32_e32 v87, v107
	v_add_f32_e32 v104, v84, v100
	v_add_f32_e32 v105, v85, v101
	v_add_f32_e32 v102, v86, v102
	v_add_f32_e32 v103, v87, v103
	v_cvt_pk_bf16_f32 v100, v84, v85
	v_cvt_pk_bf16_f32 v101, v86, v87
	v_exp_f32_e32 v84, v88
	v_exp_f32_e32 v85, v89
	v_exp_f32_e32 v86, v90
	v_exp_f32_e32 v87, v91
	v_add_f32_e32 v90, v84, v104
	v_add_f32_e32 v91, v85, v105
	v_add_f32_e32 v102, v86, v102
	v_add_f32_e32 v103, v87, v103
	v_cvt_pk_bf16_f32 v88, v84, v85
	v_cvt_pk_bf16_f32 v89, v86, v87
	v_exp_f32_e32 v84, v108
	v_exp_f32_e32 v85, v109
	v_exp_f32_e32 v86, v110
	v_exp_f32_e32 v87, v111
	v_add_f32_e32 v90, v84, v90
	v_add_f32_e32 v91, v85, v91
	v_add_f32_e32 v104, v86, v102
	v_add_f32_e32 v105, v87, v103
	v_cvt_pk_bf16_f32 v102, v84, v85
	v_cvt_pk_bf16_f32 v103, v86, v87
	v_exp_f32_e32 v92, v92
	v_exp_f32_e32 v93, v93
	v_exp_f32_e32 v94, v94
	v_exp_f32_e32 v95, v95
	v_add_f32_e32 v84, v92, v90
	v_add_f32_e32 v85, v93, v91
	v_add_f32_e32 v86, v94, v104
	v_add_f32_e32 v87, v95, v105
	v_cvt_pk_bf16_f32 v90, v92, v93
	v_cvt_pk_bf16_f32 v91, v94, v95
	v_add_f32_e32 v182, v84, v85
	v_add_f32_e32 v183, v86, v87
	v_add_f32_e32 v182, v182, v183
	v_add_f32_e32 v169, v169, v182
	s_waitcnt lgkmcnt(0)
	s_barrier
	v_lshl_add_u64 v[172:173], v[172:173], 0, s[4:5]
	v_lshl_add_u64 v[174:175], v[174:175], 0, s[4:5]
	ds_read_b64_tr_b16 v[92:93], v180 offset:40960
	ds_read_b64_tr_b16 v[94:95], v180 offset:41472
	ds_read_b64_tr_b16 v[104:105], v180 offset:45056
	ds_read_b64_tr_b16 v[106:107], v180 offset:45568
	s_waitcnt lgkmcnt(2)
	v_mfma_f32_32x32x16_bf16 v[16:31], v[92:95], v[96:99], v[16:31]
	s_waitcnt lgkmcnt(0)
	v_mfma_f32_32x32x16_bf16 v[0:15], v[104:107], v[96:99], v[0:15]
	ds_read_b64_tr_b16 v[92:93], v180 offset:41984
	ds_read_b64_tr_b16 v[94:95], v180 offset:42496
	ds_read_b64_tr_b16 v[96:97], v180 offset:46080
	ds_read_b64_tr_b16 v[98:99], v180 offset:46592
	s_waitcnt lgkmcnt(2)
	v_mfma_f32_32x32x16_bf16 v[16:31], v[92:95], v[100:103], v[16:31]
	s_waitcnt lgkmcnt(0)
	v_mfma_f32_32x32x16_bf16 v[0:15], v[96:99], v[100:103], v[0:15]
	ds_read_b64_tr_b16 v[92:93], v180 offset:43008
	ds_read_b64_tr_b16 v[94:95], v180 offset:43520
	ds_read_b64_tr_b16 v[96:97], v180 offset:47104
	ds_read_b64_tr_b16 v[98:99], v180 offset:47616
	s_waitcnt lgkmcnt(2)
	v_mfma_f32_32x32x16_bf16 v[16:31], v[92:95], v[80:83], v[16:31]
	s_waitcnt lgkmcnt(0)
	v_mfma_f32_32x32x16_bf16 v[0:15], v[96:99], v[80:83], v[0:15]
	ds_read_b64_tr_b16 v[80:81], v180 offset:44032
	ds_read_b64_tr_b16 v[82:83], v180 offset:44544
	ds_read_b64_tr_b16 v[92:93], v180 offset:48128
	ds_read_b64_tr_b16 v[94:95], v180 offset:48640
	s_waitcnt lgkmcnt(2)
	v_mfma_f32_32x32x16_bf16 v[16:31], v[80:83], v[88:91], v[16:31]
	s_waitcnt lgkmcnt(0)
	v_mfma_f32_32x32x16_bf16 v[0:15], v[92:95], v[88:91], v[0:15]
	s_branch .LBB0_62

; #define LAS __attribute__((address_space(3)))
; __global__ void __launch_bounds__(512, 2) fwd_kernel(Args a) {
;     extern __shared__ __attribute__((aligned(16))) unsigned char lds_raw[];
;     LAS unsigned char* lds = (LAS unsigned char*)lds_raw;
	.amdhsa_kernel _Z10fwd_kernel4Args
		.amdhsa_group_segment_fixed_size 0
		.amdhsa_private_segment_fixed_size 0
		.amdhsa_kernarg_size 400
		.amdhsa_user_sgpr_count 2
		.amdhsa_user_sgpr_dispatch_ptr 0
		.amdhsa_user_sgpr_queue_ptr 0
		.amdhsa_user_sgpr_kernarg_segment_ptr 1
		.amdhsa_user_sgpr_dispatch_id 0
		.amdhsa_user_sgpr_kernarg_preload_length 0
		.amdhsa_user_sgpr_kernarg_preload_offset 0
		.amdhsa_user_sgpr_private_segment_size 0
		.amdhsa_uses_dynamic_stack 0
		.amdhsa_enable_private_segment 0
		.amdhsa_system_sgpr_workgroup_id_x 1
		.amdhsa_system_sgpr_workgroup_id_y 0
		.amdhsa_system_sgpr_workgroup_id_z 0
		.amdhsa_system_sgpr_workgroup_info 0
		.amdhsa_system_vgpr_workitem_id 2
		.amdhsa_next_free_vgpr 256
		.amdhsa_next_free_sgpr 102
		.amdhsa_accum_offset 256
		.amdhsa_reserve_vcc 1
		.amdhsa_float_round_mode_32 0
		.amdhsa_float_round_mode_16_64 0
		.amdhsa_float_denorm_mode_32 3
		.amdhsa_float_denorm_mode_16_64 3
		.amdhsa_dx10_clamp 1
		.amdhsa_ieee_mode 1
		.amdhsa_fp16_overflow 0
		.amdhsa_tg_split 0
		.amdhsa_exception_fp_ieee_invalid_op 0
		.amdhsa_exception_fp_denorm_src 0
		.amdhsa_exception_fp_ieee_div_zero 0
		.amdhsa_exception_fp_ieee_overflow 0
		.amdhsa_exception_fp_ieee_underflow 0
		.amdhsa_exception_fp_ieee_inexact 0
		.amdhsa_exception_int_div_zero 0
	.end_amdhsa_kernel

; #define LAS __attribute__((address_space(3)))
; __global__ void __launch_bounds__(512, 2) fwd_kernel(Args a) {
;     extern __shared__ __attribute__((aligned(16))) unsigned char lds_raw[];
;     LAS unsigned char* lds = (LAS unsigned char*)lds_raw;
amdhsa.kernels:
  - .agpr_count:     0
    .args:
      - .offset:         0
        .size:           144
        .value_kind:     by_value
      - .offset:         144
        .size:           4
        .value_kind:     hidden_block_count_x
      - .offset:         148
        .size:           4
        .value_kind:     hidden_block_count_y
      - .offset:         152
        .size:           4
        .value_kind:     hidden_block_count_z
      - .offset:         156
        .size:           2
        .value_kind:     hidden_group_size_x
      - .offset:         158
        .size:           2
        .value_kind:     hidden_group_size_y
      - .offset:         160
        .size:           2
        .value_kind:     hidden_group_size_z
      - .offset:         162
        .size:           2
        .value_kind:     hidden_remainder_x
      - .offset:         164
        .size:           2
        .value_kind:     hidden_remainder_y
      - .offset:         166
        .size:           2
        .value_kind:     hidden_remainder_z
      - .offset:         184
        .size:           8
        .value_kind:     hidden_global_offset_x
      - .offset:         192
        .size:           8
        .value_kind:     hidden_global_offset_y
      - .offset:         200
        .size:           8
        .value_kind:     hidden_global_offset_z
      - .offset:         208
        .size:           2
        .value_kind:     hidden_grid_dims
      - .offset:         232
        .size:           8
        .value_kind:     hidden_multigrid_sync_arg
      - .offset:         264
        .size:           4
        .value_kind:     hidden_dynamic_lds_size
    .group_segment_fixed_size: 0
    .kernarg_segment_align: 8
    .kernarg_segment_size: 400
    .language:       OpenCL C
    .language_version:
      - 2
      - 0
    .max_flat_workgroup_size: 512
    .name:           _Z10fwd_kernel4Args
    .private_segment_fixed_size: 0
    .sgpr_count:     108
    .sgpr_spill_count: 214
    .symbol:         _Z10fwd_kernel4Args.kd
    .uniform_work_group_size: 1
    .uses_dynamic_stack: false
    .vgpr_count:     256
    .vgpr_spill_count: 0
    .wavefront_size: 64
